# v10 + m0 save/restore and s_nop padding trimmed around the LDS-DMA issues of the 9 bf16 K-loops
# baseline (speedup 1.0000x reference)
.LBB0_155:
	s_ashr_i32 s41, s40, 31
	s_lshl_b64 s[14:15], s[40:41], 19
	s_add_u32 s42, s16, s14
	s_addc_u32 s43, s17, s15
	s_and_b64 s[14:15], s[2:3], exec
	s_cselect_b32 s14, s43, s53
	s_cselect_b32 s15, s42, s52
	s_ashr_i32 s11, s10, 31
	s_lshl_b64 s[34:35], s[10:11], 19
	s_add_u32 s44, s33, s34
	s_addc_u32 s45, s58, s35
	s_and_b64 s[34:35], s[2:3], exec
	s_cselect_b32 s11, s45, s1
	s_cselect_b32 s41, s44, s0
	s_add_u32 s87, s0, 0x100
	s_addc_u32 s88, s1, 0
	s_mov_b32 s89, -2
	v_add_u32_e32 v139, 0x10000, v137
	ds_read_b128 v[140:143], v139
	ds_read_b128 v[144:147], v139 offset:1024
	ds_read_b128 v[148:151], v139 offset:2048
	ds_read_b128 v[152:155], v139 offset:3072
	v_add_u32_e32 v139, 0x14000, v137
	ds_read_b128 v[156:159], v139
	ds_read_b128 v[160:163], v139 offset:1024
	ds_read_b128 v[164:167], v139 offset:2048
	ds_read_b128 v[168:171], v139 offset:3072
	s_add_u32 s0, s52, 0x100
	s_addc_u32 s1, s53, 0
	s_cmp_eq_u32 s89, 12
	s_cselect_b32 s34, s15, s0
	s_cselect_b32 s35, s14, s1
	s_cselect_b32 s56, s41, s87
	s_cselect_b32 s57, s11, s88
	s_add_u32 s54, s34, 0x80
	s_addc_u32 s55, s35, 0
	ds_read_b128 v[172:175], v138
	ds_read_b128 v[176:179], v138 offset:1024
	ds_read_b128 v[180:183], v138 offset:2048
	ds_read_b128 v[184:187], v138 offset:3072
	ds_read_b128 v[188:191], v138 offset:4096
	ds_read_b128 v[192:195], v138 offset:5120
	ds_read_b128 v[196:199], v138 offset:6144
	ds_read_b128 v[200:203], v138 offset:7168
	s_add_u32 s90, s52, 0x40080
	s_addc_u32 s91, s53, 0
	s_mov_b32 m0, s83
	s_nop 0
	global_load_lds_dwordx4 v1, s[90:91]
	s_add_u32 s52, s52, 0x60080
	s_addc_u32 s53, s53, 0
	s_add_i32 s12, s51, 0xe000
	s_mov_b32 m0, s12
	s_nop 0
	global_load_lds_dwordx4 v1, s[52:53]
	s_waitcnt vmcnt(8)
	s_waitcnt lgkmcnt(0)
	s_barrier
	s_waitcnt lgkmcnt(7)
	v_mfma_f32_16x16x32_bf16 v[122:125], v[140:143], v[172:175], 0
	v_mfma_f32_16x16x32_bf16 v[114:117], v[148:151], v[172:175], 0
	s_waitcnt lgkmcnt(5)
	v_mfma_f32_16x16x32_bf16 v[106:109], v[140:143], v[180:183], 0
	v_mfma_f32_16x16x32_bf16 v[98:101], v[148:151], v[180:183], 0
	s_waitcnt lgkmcnt(3)
	v_mfma_f32_16x16x32_bf16 v[90:93], v[140:143], v[188:191], 0
	v_mfma_f32_16x16x32_bf16 v[82:85], v[148:151], v[188:191], 0
	s_waitcnt lgkmcnt(1)
	v_mfma_f32_16x16x32_bf16 v[74:77], v[140:143], v[196:199], 0
	v_mfma_f32_16x16x32_bf16 v[66:69], v[148:151], v[196:199], 0
	v_mfma_f32_16x16x32_bf16 v[122:125], v[144:147], v[176:179], v[122:125]
	v_mfma_f32_16x16x32_bf16 v[114:117], v[152:155], v[176:179], v[114:117]
	v_mfma_f32_16x16x32_bf16 v[106:109], v[144:147], v[184:187], v[106:109]
	v_mfma_f32_16x16x32_bf16 v[98:101], v[152:155], v[184:187], v[98:101]
	v_mfma_f32_16x16x32_bf16 v[90:93], v[144:147], v[192:195], v[90:93]
	v_mfma_f32_16x16x32_bf16 v[82:85], v[152:155], v[192:195], v[82:85]
	s_waitcnt lgkmcnt(0)
	v_mfma_f32_16x16x32_bf16 v[74:77], v[144:147], v[200:203], v[74:77]
	v_mfma_f32_16x16x32_bf16 v[66:69], v[152:155], v[200:203], v[66:69]
	v_mfma_f32_16x16x32_bf16 v[126:129], v[156:159], v[172:175], 0
	v_mfma_f32_16x16x32_bf16 v[118:121], v[164:167], v[172:175], 0
	v_mfma_f32_16x16x32_bf16 v[110:113], v[156:159], v[180:183], 0
	v_mfma_f32_16x16x32_bf16 v[102:105], v[164:167], v[180:183], 0
	v_mfma_f32_16x16x32_bf16 v[94:97], v[156:159], v[188:191], 0
	v_mfma_f32_16x16x32_bf16 v[86:89], v[164:167], v[188:191], 0
	v_mfma_f32_16x16x32_bf16 v[78:81], v[156:159], v[196:199], 0
	v_mfma_f32_16x16x32_bf16 v[70:73], v[164:167], v[196:199], 0
	v_mfma_f32_16x16x32_bf16 v[126:129], v[160:163], v[176:179], v[126:129]
	v_mfma_f32_16x16x32_bf16 v[118:121], v[168:171], v[176:179], v[118:121]
	v_mfma_f32_16x16x32_bf16 v[110:113], v[160:163], v[184:187], v[110:113]
	v_mfma_f32_16x16x32_bf16 v[102:105], v[168:171], v[184:187], v[102:105]
	v_mfma_f32_16x16x32_bf16 v[94:97], v[160:163], v[192:195], v[94:97]
	v_mfma_f32_16x16x32_bf16 v[86:89], v[168:171], v[192:195], v[86:89]
	v_mfma_f32_16x16x32_bf16 v[78:81], v[160:163], v[200:203], v[78:81]
	v_mfma_f32_16x16x32_bf16 v[70:73], v[168:171], v[200:203], v[70:73]
	s_barrier
	s_add_u32 s52, s56, 0x20000
	ds_read_b128 v[172:175], v138 offset:16384
	ds_read_b128 v[176:179], v138 offset:17408
	ds_read_b128 v[180:183], v138 offset:18432
	ds_read_b128 v[184:187], v138 offset:19456
	ds_read_b128 v[188:191], v138 offset:20480
	ds_read_b128 v[192:195], v138 offset:21504
	ds_read_b128 v[196:199], v138 offset:22528
	ds_read_b128 v[200:203], v138 offset:23552
	s_mov_b32 m0, s62
	s_nop 0
	global_load_lds_dwordx4 v134, s[56:57]
	s_addc_u32 s53, s57, 0
	s_mov_b32 m0, s63
	s_nop 0
	global_load_lds_dwordx4 v134, s[52:53]
	s_add_u32 s52, s56, 0x40000
	s_addc_u32 s53, s57, 0
	s_mov_b32 m0, s64
	s_nop 0
	global_load_lds_dwordx4 v134, s[52:53]
	s_add_u32 s52, s56, 0x60000
	s_addc_u32 s53, s57, 0
	s_mov_b32 m0, s65
	s_nop 0
	global_load_lds_dwordx4 v134, s[52:53]
	s_add_u32 s52, s34, 0x20000
	s_mov_b32 m0, s51
	s_nop 0
	global_load_lds_dwordx4 v1, s[34:35]
	s_addc_u32 s53, s35, 0
	s_mov_b32 m0, s73
	s_nop 0
	global_load_lds_dwordx4 v1, s[52:53]
	s_waitcnt vmcnt(8)
	s_waitcnt lgkmcnt(0)
	s_barrier
	s_waitcnt lgkmcnt(7)
	v_mfma_f32_16x16x32_bf16 v[58:61], v[140:143], v[172:175], 0
	v_mfma_f32_16x16x32_bf16 v[50:53], v[148:151], v[172:175], 0
	s_waitcnt lgkmcnt(5)
	v_mfma_f32_16x16x32_bf16 v[42:45], v[140:143], v[180:183], 0
	v_mfma_f32_16x16x32_bf16 v[34:37], v[148:151], v[180:183], 0
	s_waitcnt lgkmcnt(3)
	v_mfma_f32_16x16x32_bf16 v[26:29], v[140:143], v[188:191], 0
	v_mfma_f32_16x16x32_bf16 v[18:21], v[148:151], v[188:191], 0
	s_waitcnt lgkmcnt(1)
	v_mfma_f32_16x16x32_bf16 v[10:13], v[140:143], v[196:199], 0
	v_mfma_f32_16x16x32_bf16 v[2:5], v[148:151], v[196:199], 0
	v_mfma_f32_16x16x32_bf16 v[58:61], v[144:147], v[176:179], v[58:61]
	v_mfma_f32_16x16x32_bf16 v[50:53], v[152:155], v[176:179], v[50:53]
	v_mfma_f32_16x16x32_bf16 v[42:45], v[144:147], v[184:187], v[42:45]
	v_mfma_f32_16x16x32_bf16 v[34:37], v[152:155], v[184:187], v[34:37]
	v_mfma_f32_16x16x32_bf16 v[26:29], v[144:147], v[192:195], v[26:29]
	v_mfma_f32_16x16x32_bf16 v[18:21], v[152:155], v[192:195], v[18:21]
	s_waitcnt lgkmcnt(0)
	v_mfma_f32_16x16x32_bf16 v[10:13], v[144:147], v[200:203], v[10:13]
	v_mfma_f32_16x16x32_bf16 v[2:5], v[152:155], v[200:203], v[2:5]
	v_mfma_f32_16x16x32_bf16 v[62:65], v[156:159], v[172:175], 0
	v_mfma_f32_16x16x32_bf16 v[54:57], v[164:167], v[172:175], 0
	v_mfma_f32_16x16x32_bf16 v[46:49], v[156:159], v[180:183], 0
	v_mfma_f32_16x16x32_bf16 v[38:41], v[164:167], v[180:183], 0
	v_mfma_f32_16x16x32_bf16 v[30:33], v[156:159], v[188:191], 0
	v_mfma_f32_16x16x32_bf16 v[22:25], v[164:167], v[188:191], 0
	v_mfma_f32_16x16x32_bf16 v[14:17], v[156:159], v[196:199], 0
	v_mfma_f32_16x16x32_bf16 v[6:9], v[164:167], v[196:199], 0
	v_mfma_f32_16x16x32_bf16 v[62:65], v[160:163], v[176:179], v[62:65]
	v_mfma_f32_16x16x32_bf16 v[54:57], v[168:171], v[176:179], v[54:57]
	v_mfma_f32_16x16x32_bf16 v[46:49], v[160:163], v[184:187], v[46:49]
	v_mfma_f32_16x16x32_bf16 v[38:41], v[168:171], v[184:187], v[38:41]
	v_mfma_f32_16x16x32_bf16 v[30:33], v[160:163], v[192:195], v[30:33]
	v_mfma_f32_16x16x32_bf16 v[22:25], v[168:171], v[192:195], v[22:25]
	v_mfma_f32_16x16x32_bf16 v[14:17], v[160:163], v[200:203], v[14:17]
	v_mfma_f32_16x16x32_bf16 v[6:9], v[168:171], v[200:203], v[6:9]
	s_barrier
	v_add_u32_e32 v139, 0x18000, v137
	ds_read_b128 v[140:143], v139
	ds_read_b128 v[144:147], v139 offset:1024
	ds_read_b128 v[148:151], v139 offset:2048
	ds_read_b128 v[152:155], v139 offset:3072
	v_add_u32_e32 v139, 0x1c000, v137
	ds_read_b128 v[156:159], v139
	ds_read_b128 v[160:163], v139 offset:1024
	ds_read_b128 v[164:167], v139 offset:2048
	ds_read_b128 v[168:171], v139 offset:3072
	ds_read_b128 v[172:175], v138 offset:32768
	ds_read_b128 v[176:179], v138 offset:33792
	ds_read_b128 v[180:183], v138 offset:34816
	ds_read_b128 v[184:187], v138 offset:35840
	ds_read_b128 v[188:191], v138 offset:36864
	ds_read_b128 v[192:195], v138 offset:37888
	ds_read_b128 v[196:199], v138 offset:38912
	ds_read_b128 v[200:203], v138 offset:39936
	s_add_u32 s52, s34, 0x40000
	s_addc_u32 s53, s35, 0
	s_mov_b32 m0, s74
	s_nop 0
	global_load_lds_dwordx4 v1, s[52:53]
	s_add_u32 s52, s34, 0x60000
	s_addc_u32 s53, s35, 0
	s_mov_b32 m0, s75
	s_nop 0
	global_load_lds_dwordx4 v1, s[52:53]
	s_waitcnt vmcnt(8)
	s_waitcnt lgkmcnt(0)
	s_barrier
	s_waitcnt lgkmcnt(7)
	v_mfma_f32_16x16x32_bf16 v[122:125], v[140:143], v[172:175], v[122:125]
	v_mfma_f32_16x16x32_bf16 v[114:117], v[148:151], v[172:175], v[114:117]
	s_waitcnt lgkmcnt(5)
	v_mfma_f32_16x16x32_bf16 v[106:109], v[140:143], v[180:183], v[106:109]
	v_mfma_f32_16x16x32_bf16 v[98:101], v[148:151], v[180:183], v[98:101]
	s_waitcnt lgkmcnt(3)
	v_mfma_f32_16x16x32_bf16 v[90:93], v[140:143], v[188:191], v[90:93]
	v_mfma_f32_16x16x32_bf16 v[82:85], v[148:151], v[188:191], v[82:85]
	s_waitcnt lgkmcnt(1)
	v_mfma_f32_16x16x32_bf16 v[74:77], v[140:143], v[196:199], v[74:77]
	v_mfma_f32_16x16x32_bf16 v[66:69], v[148:151], v[196:199], v[66:69]
	v_mfma_f32_16x16x32_bf16 v[122:125], v[144:147], v[176:179], v[122:125]
	v_mfma_f32_16x16x32_bf16 v[114:117], v[152:155], v[176:179], v[114:117]
	v_mfma_f32_16x16x32_bf16 v[106:109], v[144:147], v[184:187], v[106:109]
	v_mfma_f32_16x16x32_bf16 v[98:101], v[152:155], v[184:187], v[98:101]
	v_mfma_f32_16x16x32_bf16 v[90:93], v[144:147], v[192:195], v[90:93]
	v_mfma_f32_16x16x32_bf16 v[82:85], v[152:155], v[192:195], v[82:85]
	s_waitcnt lgkmcnt(0)
	v_mfma_f32_16x16x32_bf16 v[74:77], v[144:147], v[200:203], v[74:77]
	v_mfma_f32_16x16x32_bf16 v[66:69], v[152:155], v[200:203], v[66:69]
	v_mfma_f32_16x16x32_bf16 v[126:129], v[156:159], v[172:175], v[126:129]
	v_mfma_f32_16x16x32_bf16 v[118:121], v[164:167], v[172:175], v[118:121]
	v_mfma_f32_16x16x32_bf16 v[110:113], v[156:159], v[180:183], v[110:113]
	v_mfma_f32_16x16x32_bf16 v[102:105], v[164:167], v[180:183], v[102:105]
	v_mfma_f32_16x16x32_bf16 v[94:97], v[156:159], v[188:191], v[94:97]
	v_mfma_f32_16x16x32_bf16 v[86:89], v[164:167], v[188:191], v[86:89]
	v_mfma_f32_16x16x32_bf16 v[78:81], v[156:159], v[196:199], v[78:81]
	v_mfma_f32_16x16x32_bf16 v[70:73], v[164:167], v[196:199], v[70:73]
	v_mfma_f32_16x16x32_bf16 v[126:129], v[160:163], v[176:179], v[126:129]
	v_mfma_f32_16x16x32_bf16 v[118:121], v[168:171], v[176:179], v[118:121]
	v_mfma_f32_16x16x32_bf16 v[110:113], v[160:163], v[184:187], v[110:113]
	v_mfma_f32_16x16x32_bf16 v[102:105], v[168:171], v[184:187], v[102:105]
	v_mfma_f32_16x16x32_bf16 v[94:97], v[160:163], v[192:195], v[94:97]
	v_mfma_f32_16x16x32_bf16 v[86:89], v[168:171], v[192:195], v[86:89]
	v_mfma_f32_16x16x32_bf16 v[78:81], v[160:163], v[200:203], v[78:81]
	v_mfma_f32_16x16x32_bf16 v[70:73], v[168:171], v[200:203], v[70:73]
	s_barrier
	s_add_u32 s52, s56, 0x80
	s_addc_u32 s53, s57, 0
	ds_read_b128 v[172:175], v138 offset:49152
	ds_read_b128 v[176:179], v138 offset:50176
	ds_read_b128 v[180:183], v138 offset:51200
	ds_read_b128 v[184:187], v138 offset:52224
	ds_read_b128 v[188:191], v138 offset:53248
	ds_read_b128 v[192:195], v138 offset:54272
	ds_read_b128 v[196:199], v138 offset:55296
	ds_read_b128 v[200:203], v138 offset:56320
	s_mov_b32 m0, s76
	s_nop 0
	global_load_lds_dwordx4 v134, s[52:53]
	s_add_u32 s52, s56, 0x20080
	s_addc_u32 s53, s57, 0
	s_mov_b32 m0, s77
	s_nop 0
	global_load_lds_dwordx4 v134, s[52:53]
	s_add_u32 s52, s56, 0x40080
	s_addc_u32 s53, s57, 0
	s_mov_b32 m0, s80
	s_nop 0
	global_load_lds_dwordx4 v134, s[52:53]
	s_add_u32 s52, s56, 0x60080
	s_addc_u32 s53, s57, 0
	s_mov_b32 m0, s81
	s_nop 0
	global_load_lds_dwordx4 v134, s[52:53]
	s_add_u32 s34, s34, 0x20080
	s_mov_b32 m0, s78
	s_nop 0
	global_load_lds_dwordx4 v1, s[54:55]
	s_addc_u32 s35, s35, 0
	s_mov_b32 m0, s79
	s_nop 0
	global_load_lds_dwordx4 v1, s[34:35]
	s_waitcnt vmcnt(8)
	s_waitcnt lgkmcnt(0)
	s_barrier
	s_waitcnt lgkmcnt(7)
	v_mfma_f32_16x16x32_bf16 v[58:61], v[140:143], v[172:175], v[58:61]
	v_mfma_f32_16x16x32_bf16 v[50:53], v[148:151], v[172:175], v[50:53]
	s_waitcnt lgkmcnt(5)
	v_mfma_f32_16x16x32_bf16 v[42:45], v[140:143], v[180:183], v[42:45]
	v_mfma_f32_16x16x32_bf16 v[34:37], v[148:151], v[180:183], v[34:37]
	s_waitcnt lgkmcnt(3)
	v_mfma_f32_16x16x32_bf16 v[26:29], v[140:143], v[188:191], v[26:29]
	v_mfma_f32_16x16x32_bf16 v[18:21], v[148:151], v[188:191], v[18:21]
	s_waitcnt lgkmcnt(1)
	v_mfma_f32_16x16x32_bf16 v[10:13], v[140:143], v[196:199], v[10:13]
	v_mfma_f32_16x16x32_bf16 v[2:5], v[148:151], v[196:199], v[2:5]
	v_mfma_f32_16x16x32_bf16 v[58:61], v[144:147], v[176:179], v[58:61]
	v_mfma_f32_16x16x32_bf16 v[50:53], v[152:155], v[176:179], v[50:53]
	v_mfma_f32_16x16x32_bf16 v[42:45], v[144:147], v[184:187], v[42:45]
	v_mfma_f32_16x16x32_bf16 v[34:37], v[152:155], v[184:187], v[34:37]
	v_mfma_f32_16x16x32_bf16 v[26:29], v[144:147], v[192:195], v[26:29]
	v_mfma_f32_16x16x32_bf16 v[18:21], v[152:155], v[192:195], v[18:21]
	s_waitcnt lgkmcnt(0)
	v_mfma_f32_16x16x32_bf16 v[10:13], v[144:147], v[200:203], v[10:13]
	v_mfma_f32_16x16x32_bf16 v[2:5], v[152:155], v[200:203], v[2:5]
	v_mfma_f32_16x16x32_bf16 v[62:65], v[156:159], v[172:175], v[62:65]
	v_mfma_f32_16x16x32_bf16 v[54:57], v[164:167], v[172:175], v[54:57]
	v_mfma_f32_16x16x32_bf16 v[46:49], v[156:159], v[180:183], v[46:49]
	v_mfma_f32_16x16x32_bf16 v[38:41], v[164:167], v[180:183], v[38:41]
	v_mfma_f32_16x16x32_bf16 v[30:33], v[156:159], v[188:191], v[30:33]
	v_mfma_f32_16x16x32_bf16 v[22:25], v[164:167], v[188:191], v[22:25]
	v_mfma_f32_16x16x32_bf16 v[14:17], v[156:159], v[196:199], v[14:17]
	v_mfma_f32_16x16x32_bf16 v[6:9], v[164:167], v[196:199], v[6:9]
	v_mfma_f32_16x16x32_bf16 v[62:65], v[160:163], v[176:179], v[62:65]
	v_mfma_f32_16x16x32_bf16 v[54:57], v[168:171], v[176:179], v[54:57]
	v_mfma_f32_16x16x32_bf16 v[46:49], v[160:163], v[184:187], v[46:49]
	v_mfma_f32_16x16x32_bf16 v[38:41], v[168:171], v[184:187], v[38:41]
	v_mfma_f32_16x16x32_bf16 v[30:33], v[160:163], v[192:195], v[30:33]
	v_mfma_f32_16x16x32_bf16 v[22:25], v[168:171], v[192:195], v[22:25]
	v_mfma_f32_16x16x32_bf16 v[14:17], v[160:163], v[200:203], v[14:17]
	v_mfma_f32_16x16x32_bf16 v[6:9], v[168:171], v[200:203], v[6:9]
	s_barrier
	s_add_i32 s89, s89, 2
	s_add_u32 s87, s87, 0x100
	s_addc_u32 s88, s88, 0
	s_cmp_gt_u32 s89, 13
	s_mov_b64 s[52:53], s[0:1]

.LBB0_235:
	v_and_b32_e32 v3, 48, v2
	v_lshlrev_b32_e32 v4, 6, v2
	s_movk_i32 s3, 0x3c0
	v_lshlrev_b32_e32 v2, 2, v2
	s_and_b32 s64, s15, 3
	s_lshl_b32 s2, s14, 13
	v_and_or_b32 v3, v4, s3, v3
	v_and_b32_e32 v2, 32, v2
	s_lshl_b32 s79, s14, 6
	v_bitop3_b32 v4, v3, s2, v2 bitop3:0xde
	s_lshl_b32 s2, s64, 12
	s_add_u32 s34, s6, 0x80
	s_addc_u32 s35, s7, 0
	s_add_i32 s81, s65, 0x18000
	v_bitop3_b32 v2, v3, s2, v2 bitop3:0xde
	s_waitcnt vmcnt(2)
	s_barrier
	s_mov_b32 s2, m0
	s_mov_b32 m0, s81
	s_nop 4
	global_load_lds_dwordx4 v131, s[34:35]
	s_mov_b32 m0, s2
	s_add_u32 s34, s6, 0x58080
	s_addc_u32 s35, s7, 0
	s_add_i32 s84, s65, 0x1a000
	s_mov_b32 s2, m0
	s_mov_b32 m0, s84
	s_nop 4
	global_load_lds_dwordx4 v131, s[34:35]
	s_mov_b32 m0, s2
	s_add_u32 s34, s10, 0x80
	s_addc_u32 s35, s11, 0
	s_add_i32 s85, s65, 0x8000
	s_mov_b32 s2, m0
	s_mov_b32 m0, s85
	s_nop 4
	global_load_lds_dwordx4 v130, s[34:35]
	s_mov_b32 m0, s2
	s_add_u32 s34, s10, 0x58080
	s_addc_u32 s35, s11, 0
	s_add_i32 s86, s65, 0xa000
	s_mov_b32 s2, m0
	s_mov_b32 m0, s86
	s_nop 4
	global_load_lds_dwordx4 v130, s[34:35]
	s_mov_b32 m0, s2
	s_add_u32 s34, s6, 0xb0080
	s_addc_u32 s35, s7, 0
	s_add_i32 s87, s65, 0x1c000
	s_mov_b32 s2, m0
	s_mov_b32 m0, s87
	s_nop 4
	global_load_lds_dwordx4 v131, s[34:35]
	s_mov_b32 m0, s2
	s_add_u32 s34, s6, 0x108080
	s_addc_u32 s35, s7, 0
	s_add_i32 s88, s65, 0x1e000
	s_mov_b32 s2, m0
	s_mov_b32 m0, s88
	s_nop 4
	global_load_lds_dwordx4 v131, s[34:35]
	s_mov_b32 m0, s2
	s_waitcnt vmcnt(6)
	s_add_i32 s89, s65, 0xc000
	s_add_u32 s90, s70, s1
	v_mov_b32_e32 v106, 0
	v_add_u32_e32 v2, 0, v2
	s_addc_u32 s91, s71, s0
	s_mov_b32 s92, -2
	s_mov_b64 s[52:53], 0x15cb0080
	v_add_u32_e32 v132, 0x10000, v2
	v_add_u32_e32 v133, 0x14000, v2
	v_add_u32_e32 v134, 0, v4
	v_add_u32_e32 v135, 0x18000, v2
	v_add_u32_e32 v136, 0x1c000, v2
	s_waitcnt lgkmcnt(0)
	s_barrier
	ds_read_b128 v[138:141], v132
	ds_read_b128 v[142:145], v132 offset:1024
	ds_read_b128 v[146:149], v132 offset:2048
	ds_read_b128 v[150:153], v132 offset:3072
	ds_read_b128 v[154:157], v133
	ds_read_b128 v[158:161], v133 offset:1024
	ds_read_b128 v[166:169], v133 offset:2048
	ds_read_b128 v[170:173], v133 offset:3072
	s_add_u32 s0, s52, 0xea350080
	s_addc_u32 s1, s53, -1
	s_cmp_lg_u32 s92, 40
	s_cselect_b32 s3, s0, 0
	s_cselect_b32 s2, s1, 0
	s_add_u32 s0, s10, s3
	s_addc_u32 s1, s11, s2
	s_add_u32 s34, s0, 0x80
	s_addc_u32 s35, s1, 0
	s_add_u32 s54, s6, s3
	s_addc_u32 s55, s7, s2
	ds_read_b128 v[174:177], v134
	ds_read_b128 v[184:187], v134 offset:1024
	ds_read_b128 v[188:191], v134 offset:2048
	ds_read_b128 v[192:195], v134 offset:3072
	ds_read_b128 v[196:199], v134 offset:4096
	ds_read_b128 v[200:203], v134 offset:5120
	ds_read_b128 v[204:207], v134 offset:6144
	ds_read_b128 v[208:211], v134 offset:7168
	s_add_u32 s94, s90, s52
	s_addc_u32 s95, s91, s53
	s_mov_b32 m0, s89
	s_nop 0
	global_load_lds_dwordx4 v130, s[94:95]
	s_add_u32 s94, s94, 0x58000
	s_addc_u32 s95, s95, 0
	s_add_i32 s2, s65, 0xe000
	s_mov_b32 m0, s2
	s_nop 0
	global_load_lds_dwordx4 v130, s[94:95]
	s_waitcnt vmcnt(8)
	s_waitcnt lgkmcnt(0)
	s_barrier
	s_waitcnt lgkmcnt(7)
	v_mfma_f32_16x16x32_bf16 v[2:5], v[138:141], v[174:177], 0
	v_mfma_f32_16x16x32_bf16 v[6:9], v[146:149], v[174:177], 0
	s_waitcnt lgkmcnt(5)
	v_mfma_f32_16x16x32_bf16 v[30:33], v[138:141], v[188:191], 0
	v_mfma_f32_16x16x32_bf16 v[34:37], v[146:149], v[188:191], 0
	s_waitcnt lgkmcnt(3)
	v_mfma_f32_16x16x32_bf16 v[54:57], v[138:141], v[196:199], 0
	v_mfma_f32_16x16x32_bf16 v[50:53], v[146:149], v[196:199], 0
	s_waitcnt lgkmcnt(1)
	v_mfma_f32_16x16x32_bf16 v[70:73], v[138:141], v[204:207], 0
	v_mfma_f32_16x16x32_bf16 v[62:65], v[146:149], v[204:207], 0
	v_mfma_f32_16x16x32_bf16 v[2:5], v[142:145], v[184:187], v[2:5]
	v_mfma_f32_16x16x32_bf16 v[6:9], v[150:153], v[184:187], v[6:9]
	v_mfma_f32_16x16x32_bf16 v[30:33], v[142:145], v[192:195], v[30:33]
	v_mfma_f32_16x16x32_bf16 v[34:37], v[150:153], v[192:195], v[34:37]
	v_mfma_f32_16x16x32_bf16 v[54:57], v[142:145], v[200:203], v[54:57]
	v_mfma_f32_16x16x32_bf16 v[50:53], v[150:153], v[200:203], v[50:53]
	s_waitcnt lgkmcnt(0)
	v_mfma_f32_16x16x32_bf16 v[70:73], v[142:145], v[208:211], v[70:73]
	v_mfma_f32_16x16x32_bf16 v[62:65], v[150:153], v[208:211], v[62:65]
	v_mfma_f32_16x16x32_bf16 v[10:13], v[154:157], v[174:177], 0
	v_mfma_f32_16x16x32_bf16 v[14:17], v[166:169], v[174:177], 0
	v_mfma_f32_16x16x32_bf16 v[22:25], v[154:157], v[188:191], 0
	v_mfma_f32_16x16x32_bf16 v[18:21], v[166:169], v[188:191], 0
	v_mfma_f32_16x16x32_bf16 v[38:41], v[154:157], v[196:199], 0
	v_mfma_f32_16x16x32_bf16 v[26:29], v[166:169], v[196:199], 0
	v_mfma_f32_16x16x32_bf16 v[46:49], v[154:157], v[204:207], 0
	v_mfma_f32_16x16x32_bf16 v[42:45], v[166:169], v[204:207], 0
	v_mfma_f32_16x16x32_bf16 v[10:13], v[158:161], v[184:187], v[10:13]
	v_mfma_f32_16x16x32_bf16 v[14:17], v[170:173], v[184:187], v[14:17]
	v_mfma_f32_16x16x32_bf16 v[22:25], v[158:161], v[192:195], v[22:25]
	v_mfma_f32_16x16x32_bf16 v[18:21], v[170:173], v[192:195], v[18:21]
	v_mfma_f32_16x16x32_bf16 v[38:41], v[158:161], v[200:203], v[38:41]
	v_mfma_f32_16x16x32_bf16 v[26:29], v[170:173], v[200:203], v[26:29]
	v_mfma_f32_16x16x32_bf16 v[46:49], v[158:161], v[208:211], v[46:49]
	v_mfma_f32_16x16x32_bf16 v[42:45], v[170:173], v[208:211], v[42:45]
	s_barrier
	s_add_u32 s94, s54, 0x58000
	ds_read_b128 v[174:177], v134 offset:16384
	ds_read_b128 v[184:187], v134 offset:17408
	ds_read_b128 v[188:191], v134 offset:18432
	ds_read_b128 v[192:195], v134 offset:19456
	ds_read_b128 v[196:199], v134 offset:20480
	ds_read_b128 v[200:203], v134 offset:21504
	ds_read_b128 v[204:207], v134 offset:22528
	ds_read_b128 v[208:211], v134 offset:23552
	s_mov_b32 m0, s73
	s_nop 0
	global_load_lds_dwordx4 v131, s[54:55]
	s_addc_u32 s95, s55, 0
	s_mov_b32 m0, s74
	s_nop 0
	global_load_lds_dwordx4 v131, s[94:95]
	s_add_u32 s94, s54, 0xb0000
	s_addc_u32 s95, s55, 0
	s_mov_b32 m0, s75
	s_nop 0
	global_load_lds_dwordx4 v131, s[94:95]
	s_add_u32 s94, s54, 0x108000
	s_addc_u32 s95, s55, 0
	s_mov_b32 m0, s76
	s_nop 0
	global_load_lds_dwordx4 v131, s[94:95]
	s_add_u32 s94, s0, 0x58000
	s_mov_b32 m0, s65
	s_nop 0
	global_load_lds_dwordx4 v130, s[0:1]
	s_addc_u32 s95, s1, 0
	s_mov_b32 m0, s77
	s_nop 0
	global_load_lds_dwordx4 v130, s[94:95]
	s_waitcnt vmcnt(8)
	s_waitcnt lgkmcnt(0)
	s_barrier
	s_waitcnt lgkmcnt(7)
	v_mfma_f32_16x16x32_bf16 v[82:85], v[138:141], v[174:177], 0
	v_mfma_f32_16x16x32_bf16 v[74:77], v[146:149], v[174:177], 0
	s_waitcnt lgkmcnt(5)
	v_mfma_f32_16x16x32_bf16 v[98:101], v[138:141], v[188:191], 0
	v_mfma_f32_16x16x32_bf16 v[90:93], v[146:149], v[188:191], 0
	s_waitcnt lgkmcnt(3)
	v_mfma_f32_16x16x32_bf16 v[114:117], v[138:141], v[196:199], 0
	v_mfma_f32_16x16x32_bf16 v[110:113], v[146:149], v[196:199], 0
	s_waitcnt lgkmcnt(1)
	v_mfma_f32_16x16x32_bf16 v[126:129], v[138:141], v[204:207], 0
	v_mfma_f32_16x16x32_bf16 v[122:125], v[146:149], v[204:207], 0
	v_mfma_f32_16x16x32_bf16 v[82:85], v[142:145], v[184:187], v[82:85]
	v_mfma_f32_16x16x32_bf16 v[74:77], v[150:153], v[184:187], v[74:77]
	v_mfma_f32_16x16x32_bf16 v[98:101], v[142:145], v[192:195], v[98:101]
	v_mfma_f32_16x16x32_bf16 v[90:93], v[150:153], v[192:195], v[90:93]
	v_mfma_f32_16x16x32_bf16 v[114:117], v[142:145], v[200:203], v[114:117]
	v_mfma_f32_16x16x32_bf16 v[110:113], v[150:153], v[200:203], v[110:113]
	s_waitcnt lgkmcnt(0)
	v_mfma_f32_16x16x32_bf16 v[126:129], v[142:145], v[208:211], v[126:129]
	v_mfma_f32_16x16x32_bf16 v[122:125], v[150:153], v[208:211], v[122:125]
	v_mfma_f32_16x16x32_bf16 v[66:69], v[154:157], v[174:177], 0
	v_mfma_f32_16x16x32_bf16 v[58:61], v[166:169], v[174:177], 0
	v_mfma_f32_16x16x32_bf16 v[86:89], v[154:157], v[188:191], 0
	v_mfma_f32_16x16x32_bf16 v[78:81], v[166:169], v[188:191], 0
	v_mfma_f32_16x16x32_bf16 v[102:105], v[154:157], v[196:199], 0
	v_mfma_f32_16x16x32_bf16 v[94:97], v[166:169], v[196:199], 0
	v_mfma_f32_16x16x32_bf16 v[118:121], v[154:157], v[204:207], 0
	v_mfma_f32_16x16x32_bf16 v[106:109], v[166:169], v[204:207], 0
	v_mfma_f32_16x16x32_bf16 v[66:69], v[158:161], v[184:187], v[66:69]
	v_mfma_f32_16x16x32_bf16 v[58:61], v[170:173], v[184:187], v[58:61]
	v_mfma_f32_16x16x32_bf16 v[86:89], v[158:161], v[192:195], v[86:89]
	v_mfma_f32_16x16x32_bf16 v[78:81], v[170:173], v[192:195], v[78:81]
	v_mfma_f32_16x16x32_bf16 v[102:105], v[158:161], v[200:203], v[102:105]
	v_mfma_f32_16x16x32_bf16 v[94:97], v[170:173], v[200:203], v[94:97]
	v_mfma_f32_16x16x32_bf16 v[118:121], v[158:161], v[208:211], v[118:121]
	v_mfma_f32_16x16x32_bf16 v[106:109], v[170:173], v[208:211], v[106:109]
	s_barrier
	ds_read_b128 v[138:141], v135
	ds_read_b128 v[142:145], v135 offset:1024
	ds_read_b128 v[146:149], v135 offset:2048
	ds_read_b128 v[150:153], v135 offset:3072
	ds_read_b128 v[154:157], v136
	ds_read_b128 v[158:161], v136 offset:1024
	ds_read_b128 v[166:169], v136 offset:2048
	ds_read_b128 v[170:173], v136 offset:3072
	ds_read_b128 v[174:177], v134 offset:32768
	ds_read_b128 v[184:187], v134 offset:33792
	ds_read_b128 v[188:191], v134 offset:34816
	ds_read_b128 v[192:195], v134 offset:35840
	ds_read_b128 v[196:199], v134 offset:36864
	ds_read_b128 v[200:203], v134 offset:37888
	ds_read_b128 v[204:207], v134 offset:38912
	ds_read_b128 v[208:211], v134 offset:39936
	s_add_u32 s94, s0, 0xb0000
	s_addc_u32 s95, s1, 0
	s_mov_b32 m0, s78
	s_nop 0
	global_load_lds_dwordx4 v130, s[94:95]
	s_add_u32 s94, s0, 0x108000
	s_addc_u32 s95, s1, 0
	s_mov_b32 m0, s80
	s_nop 0
	global_load_lds_dwordx4 v130, s[94:95]
	s_waitcnt vmcnt(8)
	s_waitcnt lgkmcnt(0)
	s_barrier
	s_waitcnt lgkmcnt(7)
	v_mfma_f32_16x16x32_bf16 v[2:5], v[138:141], v[174:177], v[2:5]
	v_mfma_f32_16x16x32_bf16 v[6:9], v[146:149], v[174:177], v[6:9]
	s_waitcnt lgkmcnt(5)
	v_mfma_f32_16x16x32_bf16 v[30:33], v[138:141], v[188:191], v[30:33]
	v_mfma_f32_16x16x32_bf16 v[34:37], v[146:149], v[188:191], v[34:37]
	s_waitcnt lgkmcnt(3)
	v_mfma_f32_16x16x32_bf16 v[54:57], v[138:141], v[196:199], v[54:57]
	v_mfma_f32_16x16x32_bf16 v[50:53], v[146:149], v[196:199], v[50:53]
	s_waitcnt lgkmcnt(1)
	v_mfma_f32_16x16x32_bf16 v[70:73], v[138:141], v[204:207], v[70:73]
	v_mfma_f32_16x16x32_bf16 v[62:65], v[146:149], v[204:207], v[62:65]
	v_mfma_f32_16x16x32_bf16 v[2:5], v[142:145], v[184:187], v[2:5]
	v_mfma_f32_16x16x32_bf16 v[6:9], v[150:153], v[184:187], v[6:9]
	v_mfma_f32_16x16x32_bf16 v[30:33], v[142:145], v[192:195], v[30:33]
	v_mfma_f32_16x16x32_bf16 v[34:37], v[150:153], v[192:195], v[34:37]
	v_mfma_f32_16x16x32_bf16 v[54:57], v[142:145], v[200:203], v[54:57]
	v_mfma_f32_16x16x32_bf16 v[50:53], v[150:153], v[200:203], v[50:53]
	s_waitcnt lgkmcnt(0)
	v_mfma_f32_16x16x32_bf16 v[70:73], v[142:145], v[208:211], v[70:73]
	v_mfma_f32_16x16x32_bf16 v[62:65], v[150:153], v[208:211], v[62:65]
	v_mfma_f32_16x16x32_bf16 v[10:13], v[154:157], v[174:177], v[10:13]
	v_mfma_f32_16x16x32_bf16 v[14:17], v[166:169], v[174:177], v[14:17]
	v_mfma_f32_16x16x32_bf16 v[22:25], v[154:157], v[188:191], v[22:25]
	v_mfma_f32_16x16x32_bf16 v[18:21], v[166:169], v[188:191], v[18:21]
	v_mfma_f32_16x16x32_bf16 v[38:41], v[154:157], v[196:199], v[38:41]
	v_mfma_f32_16x16x32_bf16 v[26:29], v[166:169], v[196:199], v[26:29]
	v_mfma_f32_16x16x32_bf16 v[46:49], v[154:157], v[204:207], v[46:49]
	v_mfma_f32_16x16x32_bf16 v[42:45], v[166:169], v[204:207], v[42:45]
	v_mfma_f32_16x16x32_bf16 v[10:13], v[158:161], v[184:187], v[10:13]
	v_mfma_f32_16x16x32_bf16 v[14:17], v[170:173], v[184:187], v[14:17]
	v_mfma_f32_16x16x32_bf16 v[22:25], v[158:161], v[192:195], v[22:25]
	v_mfma_f32_16x16x32_bf16 v[18:21], v[170:173], v[192:195], v[18:21]
	v_mfma_f32_16x16x32_bf16 v[38:41], v[158:161], v[200:203], v[38:41]
	v_mfma_f32_16x16x32_bf16 v[26:29], v[170:173], v[200:203], v[26:29]
	v_mfma_f32_16x16x32_bf16 v[46:49], v[158:161], v[208:211], v[46:49]
	v_mfma_f32_16x16x32_bf16 v[42:45], v[170:173], v[208:211], v[42:45]
	s_barrier
	s_add_u32 s94, s54, 0x80
	s_addc_u32 s95, s55, 0
	ds_read_b128 v[174:177], v134 offset:49152
	ds_read_b128 v[184:187], v134 offset:50176
	ds_read_b128 v[188:191], v134 offset:51200
	ds_read_b128 v[192:195], v134 offset:52224
	ds_read_b128 v[196:199], v134 offset:53248
	ds_read_b128 v[200:203], v134 offset:54272
	ds_read_b128 v[204:207], v134 offset:55296
	ds_read_b128 v[208:211], v134 offset:56320
	s_mov_b32 m0, s81
	s_nop 0
	global_load_lds_dwordx4 v131, s[94:95]
	s_add_u32 s94, s54, 0x58080
	s_addc_u32 s95, s55, 0
	s_mov_b32 m0, s84
	s_nop 0
	global_load_lds_dwordx4 v131, s[94:95]
	s_add_u32 s94, s54, 0xb0080
	s_addc_u32 s95, s55, 0
	s_mov_b32 m0, s87
	s_nop 0
	global_load_lds_dwordx4 v131, s[94:95]
	s_add_u32 s54, s54, 0x108080
	s_addc_u32 s55, s55, 0
	s_mov_b32 m0, s88
	s_nop 0
	global_load_lds_dwordx4 v131, s[54:55]
	s_add_u32 s0, s0, 0x58080
	s_mov_b32 m0, s85
	s_nop 0
	global_load_lds_dwordx4 v130, s[34:35]
	s_addc_u32 s1, s1, 0
	s_mov_b32 m0, s86
	s_nop 0
	global_load_lds_dwordx4 v130, s[0:1]
	s_waitcnt vmcnt(8)
	s_waitcnt lgkmcnt(0)
	s_barrier
	s_waitcnt lgkmcnt(7)
	v_mfma_f32_16x16x32_bf16 v[82:85], v[138:141], v[174:177], v[82:85]
	v_mfma_f32_16x16x32_bf16 v[74:77], v[146:149], v[174:177], v[74:77]
	s_waitcnt lgkmcnt(5)
	v_mfma_f32_16x16x32_bf16 v[98:101], v[138:141], v[188:191], v[98:101]
	v_mfma_f32_16x16x32_bf16 v[90:93], v[146:149], v[188:191], v[90:93]
	s_waitcnt lgkmcnt(3)
	v_mfma_f32_16x16x32_bf16 v[114:117], v[138:141], v[196:199], v[114:117]
	v_mfma_f32_16x16x32_bf16 v[110:113], v[146:149], v[196:199], v[110:113]
	s_waitcnt lgkmcnt(1)
	v_mfma_f32_16x16x32_bf16 v[126:129], v[138:141], v[204:207], v[126:129]
	v_mfma_f32_16x16x32_bf16 v[122:125], v[146:149], v[204:207], v[122:125]
	v_mfma_f32_16x16x32_bf16 v[82:85], v[142:145], v[184:187], v[82:85]
	v_mfma_f32_16x16x32_bf16 v[74:77], v[150:153], v[184:187], v[74:77]
	v_mfma_f32_16x16x32_bf16 v[98:101], v[142:145], v[192:195], v[98:101]
	v_mfma_f32_16x16x32_bf16 v[90:93], v[150:153], v[192:195], v[90:93]
	v_mfma_f32_16x16x32_bf16 v[114:117], v[142:145], v[200:203], v[114:117]
	v_mfma_f32_16x16x32_bf16 v[110:113], v[150:153], v[200:203], v[110:113]
	s_waitcnt lgkmcnt(0)
	v_mfma_f32_16x16x32_bf16 v[126:129], v[142:145], v[208:211], v[126:129]
	v_mfma_f32_16x16x32_bf16 v[122:125], v[150:153], v[208:211], v[122:125]
	v_mfma_f32_16x16x32_bf16 v[66:69], v[154:157], v[174:177], v[66:69]
	v_mfma_f32_16x16x32_bf16 v[58:61], v[166:169], v[174:177], v[58:61]
	v_mfma_f32_16x16x32_bf16 v[86:89], v[154:157], v[188:191], v[86:89]
	v_mfma_f32_16x16x32_bf16 v[78:81], v[166:169], v[188:191], v[78:81]
	v_mfma_f32_16x16x32_bf16 v[102:105], v[154:157], v[196:199], v[102:105]
	v_mfma_f32_16x16x32_bf16 v[94:97], v[166:169], v[196:199], v[94:97]
	v_mfma_f32_16x16x32_bf16 v[118:121], v[154:157], v[204:207], v[118:121]
	v_mfma_f32_16x16x32_bf16 v[106:109], v[166:169], v[204:207], v[106:109]
	v_mfma_f32_16x16x32_bf16 v[66:69], v[158:161], v[184:187], v[66:69]
	v_mfma_f32_16x16x32_bf16 v[58:61], v[170:173], v[184:187], v[58:61]
	v_mfma_f32_16x16x32_bf16 v[86:89], v[158:161], v[192:195], v[86:89]
	v_mfma_f32_16x16x32_bf16 v[78:81], v[170:173], v[192:195], v[78:81]
	v_mfma_f32_16x16x32_bf16 v[102:105], v[158:161], v[200:203], v[102:105]
	v_mfma_f32_16x16x32_bf16 v[94:97], v[170:173], v[200:203], v[94:97]
	v_mfma_f32_16x16x32_bf16 v[118:121], v[158:161], v[208:211], v[118:121]
	v_mfma_f32_16x16x32_bf16 v[106:109], v[170:173], v[208:211], v[106:109]
	s_barrier
	s_add_i32 s92, s92, 2
	s_add_u32 s52, s52, 0x100
	s_addc_u32 s53, s53, 0
	s_cmp_lt_u32 s92, 42

.LBB0_418:
	s_ashr_i32 s37, s36, 31
	s_lshl_b64 s[14:15], s[36:37], 19
	s_add_u32 s38, s18, s14
	s_addc_u32 s39, s19, s15
	s_and_b64 s[14:15], s[4:5], exec
	s_cselect_b32 s14, s39, s51
	s_cselect_b32 s15, s38, s50
	s_ashr_i32 s27, s26, 31
	s_lshl_b64 s[34:35], s[26:27], 19
	s_add_u32 s42, s40, s34
	s_addc_u32 s43, s41, s35
	s_and_b64 s[34:35], s[4:5], exec
	s_cselect_b32 s27, s43, s1
	s_cselect_b32 s37, s42, s0
	s_add_u32 s79, s0, 0x100
	s_addc_u32 s80, s1, 0
	s_mov_b32 s81, -2
	v_add_u32_e32 v134, 0x10000, v145
	ds_read_b128 v[136:139], v134
	ds_read_b128 v[148:151], v134 offset:1024
	ds_read_b128 v[152:155], v134 offset:2048
	ds_read_b128 v[156:159], v134 offset:3072
	v_add_u32_e32 v134, 0x14000, v145
	ds_read_b128 v[160:163], v134
	ds_read_b128 v[164:167], v134 offset:1024
	ds_read_b128 v[168:171], v134 offset:2048
	ds_read_b128 v[172:175], v134 offset:3072
	s_add_u32 s0, s50, 0x100
	s_addc_u32 s1, s51, 0
	s_cmp_eq_u32 s81, 12
	s_cselect_b32 s34, s15, s0
	s_cselect_b32 s35, s14, s1
	s_cselect_b32 s54, s37, s79
	s_cselect_b32 s55, s27, s80
	s_add_u32 s52, s34, 0x80
	s_addc_u32 s53, s35, 0
	ds_read_b128 v[176:179], v146
	ds_read_b128 v[180:183], v146 offset:1024
	ds_read_b128 v[184:187], v146 offset:2048
	ds_read_b128 v[188:191], v146 offset:3072
	ds_read_b128 v[192:195], v146 offset:4096
	ds_read_b128 v[196:199], v146 offset:5120
	ds_read_b128 v[200:203], v146 offset:6144
	ds_read_b128 v[204:207], v146 offset:7168
	s_add_u32 s84, s50, 0x40080
	s_addc_u32 s85, s51, 0
	s_mov_b32 m0, s76
	s_nop 0
	global_load_lds_dwordx4 v1, s[84:85]
	s_add_u32 s50, s50, 0x60080
	s_addc_u32 s51, s51, 0
	s_add_i32 s2, s45, 0xe000
	s_mov_b32 m0, s2
	s_nop 0
	global_load_lds_dwordx4 v1, s[50:51]
	s_waitcnt vmcnt(8)
	s_waitcnt lgkmcnt(0)
	s_barrier
	s_waitcnt lgkmcnt(7)
	v_mfma_f32_16x16x32_bf16 v[122:125], v[136:139], v[176:179], 0
	v_mfma_f32_16x16x32_bf16 v[114:117], v[152:155], v[176:179], 0
	s_waitcnt lgkmcnt(5)
	v_mfma_f32_16x16x32_bf16 v[106:109], v[136:139], v[184:187], 0
	v_mfma_f32_16x16x32_bf16 v[98:101], v[152:155], v[184:187], 0
	s_waitcnt lgkmcnt(3)
	v_mfma_f32_16x16x32_bf16 v[90:93], v[136:139], v[192:195], 0
	v_mfma_f32_16x16x32_bf16 v[82:85], v[152:155], v[192:195], 0
	s_waitcnt lgkmcnt(1)
	v_mfma_f32_16x16x32_bf16 v[74:77], v[136:139], v[200:203], 0
	v_mfma_f32_16x16x32_bf16 v[66:69], v[152:155], v[200:203], 0
	v_mfma_f32_16x16x32_bf16 v[122:125], v[148:151], v[180:183], v[122:125]
	v_mfma_f32_16x16x32_bf16 v[114:117], v[156:159], v[180:183], v[114:117]
	v_mfma_f32_16x16x32_bf16 v[106:109], v[148:151], v[188:191], v[106:109]
	v_mfma_f32_16x16x32_bf16 v[98:101], v[156:159], v[188:191], v[98:101]
	v_mfma_f32_16x16x32_bf16 v[90:93], v[148:151], v[196:199], v[90:93]
	v_mfma_f32_16x16x32_bf16 v[82:85], v[156:159], v[196:199], v[82:85]
	s_waitcnt lgkmcnt(0)
	v_mfma_f32_16x16x32_bf16 v[74:77], v[148:151], v[204:207], v[74:77]
	v_mfma_f32_16x16x32_bf16 v[66:69], v[156:159], v[204:207], v[66:69]
	v_mfma_f32_16x16x32_bf16 v[126:129], v[160:163], v[176:179], 0
	v_mfma_f32_16x16x32_bf16 v[118:121], v[168:171], v[176:179], 0
	v_mfma_f32_16x16x32_bf16 v[110:113], v[160:163], v[184:187], 0
	v_mfma_f32_16x16x32_bf16 v[102:105], v[168:171], v[184:187], 0
	v_mfma_f32_16x16x32_bf16 v[94:97], v[160:163], v[192:195], 0
	v_mfma_f32_16x16x32_bf16 v[86:89], v[168:171], v[192:195], 0
	v_mfma_f32_16x16x32_bf16 v[78:81], v[160:163], v[200:203], 0
	v_mfma_f32_16x16x32_bf16 v[70:73], v[168:171], v[200:203], 0
	v_mfma_f32_16x16x32_bf16 v[126:129], v[164:167], v[180:183], v[126:129]
	v_mfma_f32_16x16x32_bf16 v[118:121], v[172:175], v[180:183], v[118:121]
	v_mfma_f32_16x16x32_bf16 v[110:113], v[164:167], v[188:191], v[110:113]
	v_mfma_f32_16x16x32_bf16 v[102:105], v[172:175], v[188:191], v[102:105]
	v_mfma_f32_16x16x32_bf16 v[94:97], v[164:167], v[196:199], v[94:97]
	v_mfma_f32_16x16x32_bf16 v[86:89], v[172:175], v[196:199], v[86:89]
	v_mfma_f32_16x16x32_bf16 v[78:81], v[164:167], v[204:207], v[78:81]
	v_mfma_f32_16x16x32_bf16 v[70:73], v[172:175], v[204:207], v[70:73]
	s_barrier
	s_add_u32 s50, s54, 0x20000
	ds_read_b128 v[176:179], v146 offset:16384
	ds_read_b128 v[180:183], v146 offset:17408
	ds_read_b128 v[184:187], v146 offset:18432
	ds_read_b128 v[188:191], v146 offset:19456
	ds_read_b128 v[192:195], v146 offset:20480
	ds_read_b128 v[196:199], v146 offset:21504
	ds_read_b128 v[200:203], v146 offset:22528
	ds_read_b128 v[204:207], v146 offset:23552
	s_mov_b32 m0, s58
	s_nop 0
	global_load_lds_dwordx4 v142, s[54:55]
	s_addc_u32 s51, s55, 0
	s_mov_b32 m0, s59
	s_nop 0
	global_load_lds_dwordx4 v142, s[50:51]
	s_add_u32 s50, s54, 0x40000
	s_addc_u32 s51, s55, 0
	s_mov_b32 m0, s60
	s_nop 0
	global_load_lds_dwordx4 v142, s[50:51]
	s_add_u32 s50, s54, 0x60000
	s_addc_u32 s51, s55, 0
	s_mov_b32 m0, s61
	s_nop 0
	global_load_lds_dwordx4 v142, s[50:51]
	s_add_u32 s50, s34, 0x20000
	s_mov_b32 m0, s45
	s_nop 0
	global_load_lds_dwordx4 v1, s[34:35]
	s_addc_u32 s51, s35, 0
	s_mov_b32 m0, s62
	s_nop 0
	global_load_lds_dwordx4 v1, s[50:51]
	s_waitcnt vmcnt(8)
	s_waitcnt lgkmcnt(0)
	s_barrier
	s_waitcnt lgkmcnt(7)
	v_mfma_f32_16x16x32_bf16 v[58:61], v[136:139], v[176:179], 0
	v_mfma_f32_16x16x32_bf16 v[50:53], v[152:155], v[176:179], 0
	s_waitcnt lgkmcnt(5)
	v_mfma_f32_16x16x32_bf16 v[42:45], v[136:139], v[184:187], 0
	v_mfma_f32_16x16x32_bf16 v[34:37], v[152:155], v[184:187], 0
	s_waitcnt lgkmcnt(3)
	v_mfma_f32_16x16x32_bf16 v[26:29], v[136:139], v[192:195], 0
	v_mfma_f32_16x16x32_bf16 v[18:21], v[152:155], v[192:195], 0
	s_waitcnt lgkmcnt(1)
	v_mfma_f32_16x16x32_bf16 v[10:13], v[136:139], v[200:203], 0
	v_mfma_f32_16x16x32_bf16 v[2:5], v[152:155], v[200:203], 0
	v_mfma_f32_16x16x32_bf16 v[58:61], v[148:151], v[180:183], v[58:61]
	v_mfma_f32_16x16x32_bf16 v[50:53], v[156:159], v[180:183], v[50:53]
	v_mfma_f32_16x16x32_bf16 v[42:45], v[148:151], v[188:191], v[42:45]
	v_mfma_f32_16x16x32_bf16 v[34:37], v[156:159], v[188:191], v[34:37]
	v_mfma_f32_16x16x32_bf16 v[26:29], v[148:151], v[196:199], v[26:29]
	v_mfma_f32_16x16x32_bf16 v[18:21], v[156:159], v[196:199], v[18:21]
	s_waitcnt lgkmcnt(0)
	v_mfma_f32_16x16x32_bf16 v[10:13], v[148:151], v[204:207], v[10:13]
	v_mfma_f32_16x16x32_bf16 v[2:5], v[156:159], v[204:207], v[2:5]
	v_mfma_f32_16x16x32_bf16 v[62:65], v[160:163], v[176:179], 0
	v_mfma_f32_16x16x32_bf16 v[54:57], v[168:171], v[176:179], 0
	v_mfma_f32_16x16x32_bf16 v[46:49], v[160:163], v[184:187], 0
	v_mfma_f32_16x16x32_bf16 v[38:41], v[168:171], v[184:187], 0
	v_mfma_f32_16x16x32_bf16 v[30:33], v[160:163], v[192:195], 0
	v_mfma_f32_16x16x32_bf16 v[22:25], v[168:171], v[192:195], 0
	v_mfma_f32_16x16x32_bf16 v[14:17], v[160:163], v[200:203], 0
	v_mfma_f32_16x16x32_bf16 v[6:9], v[168:171], v[200:203], 0
	v_mfma_f32_16x16x32_bf16 v[62:65], v[164:167], v[180:183], v[62:65]
	v_mfma_f32_16x16x32_bf16 v[54:57], v[172:175], v[180:183], v[54:57]
	v_mfma_f32_16x16x32_bf16 v[46:49], v[164:167], v[188:191], v[46:49]
	v_mfma_f32_16x16x32_bf16 v[38:41], v[172:175], v[188:191], v[38:41]
	v_mfma_f32_16x16x32_bf16 v[30:33], v[164:167], v[196:199], v[30:33]
	v_mfma_f32_16x16x32_bf16 v[22:25], v[172:175], v[196:199], v[22:25]
	v_mfma_f32_16x16x32_bf16 v[14:17], v[164:167], v[204:207], v[14:17]
	v_mfma_f32_16x16x32_bf16 v[6:9], v[172:175], v[204:207], v[6:9]
	s_barrier
	v_add_u32_e32 v134, 0x18000, v145
	ds_read_b128 v[136:139], v134
	ds_read_b128 v[148:151], v134 offset:1024
	ds_read_b128 v[152:155], v134 offset:2048
	ds_read_b128 v[156:159], v134 offset:3072
	v_add_u32_e32 v134, 0x1c000, v145
	ds_read_b128 v[160:163], v134
	ds_read_b128 v[164:167], v134 offset:1024
	ds_read_b128 v[168:171], v134 offset:2048
	ds_read_b128 v[172:175], v134 offset:3072
	ds_read_b128 v[176:179], v146 offset:32768
	ds_read_b128 v[180:183], v146 offset:33792
	ds_read_b128 v[184:187], v146 offset:34816
	ds_read_b128 v[188:191], v146 offset:35840
	ds_read_b128 v[192:195], v146 offset:36864
	ds_read_b128 v[196:199], v146 offset:37888
	ds_read_b128 v[200:203], v146 offset:38912
	ds_read_b128 v[204:207], v146 offset:39936
	s_add_u32 s50, s34, 0x40000
	s_addc_u32 s51, s35, 0
	s_mov_b32 m0, s63
	s_nop 0
	global_load_lds_dwordx4 v1, s[50:51]
	s_add_u32 s50, s34, 0x60000
	s_addc_u32 s51, s35, 0
	s_mov_b32 m0, s64
	s_nop 0
	global_load_lds_dwordx4 v1, s[50:51]
	s_waitcnt vmcnt(8)
	s_waitcnt lgkmcnt(0)
	s_barrier
	s_waitcnt lgkmcnt(7)
	v_mfma_f32_16x16x32_bf16 v[122:125], v[136:139], v[176:179], v[122:125]
	v_mfma_f32_16x16x32_bf16 v[114:117], v[152:155], v[176:179], v[114:117]
	s_waitcnt lgkmcnt(5)
	v_mfma_f32_16x16x32_bf16 v[106:109], v[136:139], v[184:187], v[106:109]
	v_mfma_f32_16x16x32_bf16 v[98:101], v[152:155], v[184:187], v[98:101]
	s_waitcnt lgkmcnt(3)
	v_mfma_f32_16x16x32_bf16 v[90:93], v[136:139], v[192:195], v[90:93]
	v_mfma_f32_16x16x32_bf16 v[82:85], v[152:155], v[192:195], v[82:85]
	s_waitcnt lgkmcnt(1)
	v_mfma_f32_16x16x32_bf16 v[74:77], v[136:139], v[200:203], v[74:77]
	v_mfma_f32_16x16x32_bf16 v[66:69], v[152:155], v[200:203], v[66:69]
	v_mfma_f32_16x16x32_bf16 v[122:125], v[148:151], v[180:183], v[122:125]
	v_mfma_f32_16x16x32_bf16 v[114:117], v[156:159], v[180:183], v[114:117]
	v_mfma_f32_16x16x32_bf16 v[106:109], v[148:151], v[188:191], v[106:109]
	v_mfma_f32_16x16x32_bf16 v[98:101], v[156:159], v[188:191], v[98:101]
	v_mfma_f32_16x16x32_bf16 v[90:93], v[148:151], v[196:199], v[90:93]
	v_mfma_f32_16x16x32_bf16 v[82:85], v[156:159], v[196:199], v[82:85]
	s_waitcnt lgkmcnt(0)
	v_mfma_f32_16x16x32_bf16 v[74:77], v[148:151], v[204:207], v[74:77]
	v_mfma_f32_16x16x32_bf16 v[66:69], v[156:159], v[204:207], v[66:69]
	v_mfma_f32_16x16x32_bf16 v[126:129], v[160:163], v[176:179], v[126:129]
	v_mfma_f32_16x16x32_bf16 v[118:121], v[168:171], v[176:179], v[118:121]
	v_mfma_f32_16x16x32_bf16 v[110:113], v[160:163], v[184:187], v[110:113]
	v_mfma_f32_16x16x32_bf16 v[102:105], v[168:171], v[184:187], v[102:105]
	v_mfma_f32_16x16x32_bf16 v[94:97], v[160:163], v[192:195], v[94:97]
	v_mfma_f32_16x16x32_bf16 v[86:89], v[168:171], v[192:195], v[86:89]
	v_mfma_f32_16x16x32_bf16 v[78:81], v[160:163], v[200:203], v[78:81]
	v_mfma_f32_16x16x32_bf16 v[70:73], v[168:171], v[200:203], v[70:73]
	v_mfma_f32_16x16x32_bf16 v[126:129], v[164:167], v[180:183], v[126:129]
	v_mfma_f32_16x16x32_bf16 v[118:121], v[172:175], v[180:183], v[118:121]
	v_mfma_f32_16x16x32_bf16 v[110:113], v[164:167], v[188:191], v[110:113]
	v_mfma_f32_16x16x32_bf16 v[102:105], v[172:175], v[188:191], v[102:105]
	v_mfma_f32_16x16x32_bf16 v[94:97], v[164:167], v[196:199], v[94:97]
	v_mfma_f32_16x16x32_bf16 v[86:89], v[172:175], v[196:199], v[86:89]
	v_mfma_f32_16x16x32_bf16 v[78:81], v[164:167], v[204:207], v[78:81]
	v_mfma_f32_16x16x32_bf16 v[70:73], v[172:175], v[204:207], v[70:73]
	s_barrier
	s_add_u32 s50, s54, 0x80
	s_addc_u32 s51, s55, 0
	ds_read_b128 v[176:179], v146 offset:49152
	ds_read_b128 v[180:183], v146 offset:50176
	ds_read_b128 v[184:187], v146 offset:51200
	ds_read_b128 v[188:191], v146 offset:52224
	ds_read_b128 v[192:195], v146 offset:53248
	ds_read_b128 v[196:199], v146 offset:54272
	ds_read_b128 v[200:203], v146 offset:55296
	ds_read_b128 v[204:207], v146 offset:56320
	s_mov_b32 m0, s65
	s_nop 0
	global_load_lds_dwordx4 v142, s[50:51]
	s_add_u32 s50, s54, 0x20080
	s_addc_u32 s51, s55, 0
	s_mov_b32 m0, s66
	s_nop 0
	global_load_lds_dwordx4 v142, s[50:51]
	s_add_u32 s50, s54, 0x40080
	s_addc_u32 s51, s55, 0
	s_mov_b32 m0, s74
	s_nop 0
	global_load_lds_dwordx4 v142, s[50:51]
	s_add_u32 s50, s54, 0x60080
	s_addc_u32 s51, s55, 0
	s_mov_b32 m0, s75
	s_nop 0
	global_load_lds_dwordx4 v142, s[50:51]
	s_add_u32 s34, s34, 0x20080
	s_mov_b32 m0, s67
	s_nop 0
	global_load_lds_dwordx4 v1, s[52:53]
	s_addc_u32 s35, s35, 0
	s_mov_b32 m0, s73
	s_nop 0
	global_load_lds_dwordx4 v1, s[34:35]
	s_waitcnt vmcnt(8)
	s_waitcnt lgkmcnt(0)
	s_barrier
	s_waitcnt lgkmcnt(7)
	v_mfma_f32_16x16x32_bf16 v[58:61], v[136:139], v[176:179], v[58:61]
	v_mfma_f32_16x16x32_bf16 v[50:53], v[152:155], v[176:179], v[50:53]
	s_waitcnt lgkmcnt(5)
	v_mfma_f32_16x16x32_bf16 v[42:45], v[136:139], v[184:187], v[42:45]
	v_mfma_f32_16x16x32_bf16 v[34:37], v[152:155], v[184:187], v[34:37]
	s_waitcnt lgkmcnt(3)
	v_mfma_f32_16x16x32_bf16 v[26:29], v[136:139], v[192:195], v[26:29]
	v_mfma_f32_16x16x32_bf16 v[18:21], v[152:155], v[192:195], v[18:21]
	s_waitcnt lgkmcnt(1)
	v_mfma_f32_16x16x32_bf16 v[10:13], v[136:139], v[200:203], v[10:13]
	v_mfma_f32_16x16x32_bf16 v[2:5], v[152:155], v[200:203], v[2:5]
	v_mfma_f32_16x16x32_bf16 v[58:61], v[148:151], v[180:183], v[58:61]
	v_mfma_f32_16x16x32_bf16 v[50:53], v[156:159], v[180:183], v[50:53]
	v_mfma_f32_16x16x32_bf16 v[42:45], v[148:151], v[188:191], v[42:45]
	v_mfma_f32_16x16x32_bf16 v[34:37], v[156:159], v[188:191], v[34:37]
	v_mfma_f32_16x16x32_bf16 v[26:29], v[148:151], v[196:199], v[26:29]
	v_mfma_f32_16x16x32_bf16 v[18:21], v[156:159], v[196:199], v[18:21]
	s_waitcnt lgkmcnt(0)
	v_mfma_f32_16x16x32_bf16 v[10:13], v[148:151], v[204:207], v[10:13]
	v_mfma_f32_16x16x32_bf16 v[2:5], v[156:159], v[204:207], v[2:5]
	v_mfma_f32_16x16x32_bf16 v[62:65], v[160:163], v[176:179], v[62:65]
	v_mfma_f32_16x16x32_bf16 v[54:57], v[168:171], v[176:179], v[54:57]
	v_mfma_f32_16x16x32_bf16 v[46:49], v[160:163], v[184:187], v[46:49]
	v_mfma_f32_16x16x32_bf16 v[38:41], v[168:171], v[184:187], v[38:41]
	v_mfma_f32_16x16x32_bf16 v[30:33], v[160:163], v[192:195], v[30:33]
	v_mfma_f32_16x16x32_bf16 v[22:25], v[168:171], v[192:195], v[22:25]
	v_mfma_f32_16x16x32_bf16 v[14:17], v[160:163], v[200:203], v[14:17]
	v_mfma_f32_16x16x32_bf16 v[6:9], v[168:171], v[200:203], v[6:9]
	v_mfma_f32_16x16x32_bf16 v[62:65], v[164:167], v[180:183], v[62:65]
	v_mfma_f32_16x16x32_bf16 v[54:57], v[172:175], v[180:183], v[54:57]
	v_mfma_f32_16x16x32_bf16 v[46:49], v[164:167], v[188:191], v[46:49]
	v_mfma_f32_16x16x32_bf16 v[38:41], v[172:175], v[188:191], v[38:41]
	v_mfma_f32_16x16x32_bf16 v[30:33], v[164:167], v[196:199], v[30:33]
	v_mfma_f32_16x16x32_bf16 v[22:25], v[172:175], v[196:199], v[22:25]
	v_mfma_f32_16x16x32_bf16 v[14:17], v[164:167], v[204:207], v[14:17]
	v_mfma_f32_16x16x32_bf16 v[6:9], v[172:175], v[204:207], v[6:9]
	s_barrier
	s_add_i32 s81, s81, 2
	s_add_u32 s79, s79, 0x100
	s_addc_u32 s80, s80, 0
	s_cmp_gt_u32 s81, 13
	s_mov_b64 s[50:51], s[0:1]

.LBB0_556:
	s_ashr_i32 s27, s26, 31
	s_lshl_b64 s[14:15], s[26:27], 19
	s_add_u32 s36, s16, s14
	s_addc_u32 s37, s17, s15
	s_and_b64 s[14:15], s[4:5], exec
	s_cselect_b32 s14, s37, s45
	s_cselect_b32 s15, s36, s44
	s_ashr_i32 s25, s24, 31
	s_lshl_b64 s[34:35], s[24:25], 19
	s_add_u32 s38, s40, s34
	s_addc_u32 s39, s41, s35
	s_and_b64 s[34:35], s[4:5], exec
	s_cselect_b32 s25, s39, s1
	s_cselect_b32 s27, s38, s0
	s_add_u32 s79, s0, 0x100
	s_addc_u32 s80, s1, 0
	s_mov_b32 s81, -2
	v_add_u32_e32 v134, 0x10000, v139
	ds_read_b128 v[142:145], v134
	ds_read_b128 v[146:149], v134 offset:1024
	ds_read_b128 v[150:153], v134 offset:2048
	ds_read_b128 v[154:157], v134 offset:3072
	v_add_u32_e32 v134, 0x14000, v139
	ds_read_b128 v[158:161], v134
	ds_read_b128 v[162:165], v134 offset:1024
	ds_read_b128 v[166:169], v134 offset:2048
	ds_read_b128 v[170:173], v134 offset:3072
	s_add_u32 s0, s44, 0x100
	s_addc_u32 s1, s45, 0
	s_cmp_eq_u32 s81, 12
	s_cselect_b32 s34, s15, s0
	s_cselect_b32 s35, s14, s1
	s_cselect_b32 s52, s27, s79
	s_cselect_b32 s53, s25, s80
	s_add_u32 s50, s34, 0x80
	s_addc_u32 s51, s35, 0
	ds_read_b128 v[174:177], v140
	ds_read_b128 v[178:181], v140 offset:1024
	ds_read_b128 v[182:185], v140 offset:2048
	ds_read_b128 v[186:189], v140 offset:3072
	ds_read_b128 v[190:193], v140 offset:4096
	ds_read_b128 v[194:197], v140 offset:5120
	ds_read_b128 v[198:201], v140 offset:6144
	ds_read_b128 v[202:205], v140 offset:7168
	s_add_u32 s84, s44, 0x40080
	s_addc_u32 s85, s45, 0
	s_mov_b32 m0, s74
	s_nop 0
	global_load_lds_dwordx4 v1, s[84:85]
	s_add_u32 s44, s44, 0x60080
	s_addc_u32 s45, s45, 0
	s_add_i32 s2, s43, 0xe000
	s_mov_b32 m0, s2
	s_nop 0
	global_load_lds_dwordx4 v1, s[44:45]
	s_waitcnt vmcnt(8)
	s_waitcnt lgkmcnt(0)
	s_barrier
	s_waitcnt lgkmcnt(7)
	v_mfma_f32_16x16x32_bf16 v[122:125], v[142:145], v[174:177], 0
	v_mfma_f32_16x16x32_bf16 v[114:117], v[150:153], v[174:177], 0
	s_waitcnt lgkmcnt(5)
	v_mfma_f32_16x16x32_bf16 v[106:109], v[142:145], v[182:185], 0
	v_mfma_f32_16x16x32_bf16 v[98:101], v[150:153], v[182:185], 0
	s_waitcnt lgkmcnt(3)
	v_mfma_f32_16x16x32_bf16 v[90:93], v[142:145], v[190:193], 0
	v_mfma_f32_16x16x32_bf16 v[82:85], v[150:153], v[190:193], 0
	s_waitcnt lgkmcnt(1)
	v_mfma_f32_16x16x32_bf16 v[74:77], v[142:145], v[198:201], 0
	v_mfma_f32_16x16x32_bf16 v[66:69], v[150:153], v[198:201], 0
	v_mfma_f32_16x16x32_bf16 v[122:125], v[146:149], v[178:181], v[122:125]
	v_mfma_f32_16x16x32_bf16 v[114:117], v[154:157], v[178:181], v[114:117]
	v_mfma_f32_16x16x32_bf16 v[106:109], v[146:149], v[186:189], v[106:109]
	v_mfma_f32_16x16x32_bf16 v[98:101], v[154:157], v[186:189], v[98:101]
	v_mfma_f32_16x16x32_bf16 v[90:93], v[146:149], v[194:197], v[90:93]
	v_mfma_f32_16x16x32_bf16 v[82:85], v[154:157], v[194:197], v[82:85]
	s_waitcnt lgkmcnt(0)
	v_mfma_f32_16x16x32_bf16 v[74:77], v[146:149], v[202:205], v[74:77]
	v_mfma_f32_16x16x32_bf16 v[66:69], v[154:157], v[202:205], v[66:69]
	v_mfma_f32_16x16x32_bf16 v[126:129], v[158:161], v[174:177], 0
	v_mfma_f32_16x16x32_bf16 v[118:121], v[166:169], v[174:177], 0
	v_mfma_f32_16x16x32_bf16 v[110:113], v[158:161], v[182:185], 0
	v_mfma_f32_16x16x32_bf16 v[102:105], v[166:169], v[182:185], 0
	v_mfma_f32_16x16x32_bf16 v[94:97], v[158:161], v[190:193], 0
	v_mfma_f32_16x16x32_bf16 v[86:89], v[166:169], v[190:193], 0
	v_mfma_f32_16x16x32_bf16 v[78:81], v[158:161], v[198:201], 0
	v_mfma_f32_16x16x32_bf16 v[70:73], v[166:169], v[198:201], 0
	v_mfma_f32_16x16x32_bf16 v[126:129], v[162:165], v[178:181], v[126:129]
	v_mfma_f32_16x16x32_bf16 v[118:121], v[170:173], v[178:181], v[118:121]
	v_mfma_f32_16x16x32_bf16 v[110:113], v[162:165], v[186:189], v[110:113]
	v_mfma_f32_16x16x32_bf16 v[102:105], v[170:173], v[186:189], v[102:105]
	v_mfma_f32_16x16x32_bf16 v[94:97], v[162:165], v[194:197], v[94:97]
	v_mfma_f32_16x16x32_bf16 v[86:89], v[170:173], v[194:197], v[86:89]
	v_mfma_f32_16x16x32_bf16 v[78:81], v[162:165], v[202:205], v[78:81]
	v_mfma_f32_16x16x32_bf16 v[70:73], v[170:173], v[202:205], v[70:73]
	s_barrier
	s_add_u32 s44, s52, 0x20000
	ds_read_b128 v[174:177], v140 offset:16384
	ds_read_b128 v[178:181], v140 offset:17408
	ds_read_b128 v[182:185], v140 offset:18432
	ds_read_b128 v[186:189], v140 offset:19456
	ds_read_b128 v[190:193], v140 offset:20480
	ds_read_b128 v[194:197], v140 offset:21504
	ds_read_b128 v[198:201], v140 offset:22528
	ds_read_b128 v[202:205], v140 offset:23552
	s_mov_b32 m0, s56
	s_nop 0
	global_load_lds_dwordx4 v136, s[52:53]
	s_addc_u32 s45, s53, 0
	s_mov_b32 m0, s57
	s_nop 0
	global_load_lds_dwordx4 v136, s[44:45]
	s_add_u32 s44, s52, 0x40000
	s_addc_u32 s45, s53, 0
	s_mov_b32 m0, s58
	s_nop 0
	global_load_lds_dwordx4 v136, s[44:45]
	s_add_u32 s44, s52, 0x60000
	s_addc_u32 s45, s53, 0
	s_mov_b32 m0, s59
	s_nop 0
	global_load_lds_dwordx4 v136, s[44:45]
	s_add_u32 s44, s34, 0x20000
	s_mov_b32 m0, s43
	s_nop 0
	global_load_lds_dwordx4 v1, s[34:35]
	s_addc_u32 s45, s35, 0
	s_mov_b32 m0, s60
	s_nop 0
	global_load_lds_dwordx4 v1, s[44:45]
	s_waitcnt vmcnt(8)
	s_waitcnt lgkmcnt(0)
	s_barrier
	s_waitcnt lgkmcnt(7)
	v_mfma_f32_16x16x32_bf16 v[58:61], v[142:145], v[174:177], 0
	v_mfma_f32_16x16x32_bf16 v[50:53], v[150:153], v[174:177], 0
	s_waitcnt lgkmcnt(5)
	v_mfma_f32_16x16x32_bf16 v[42:45], v[142:145], v[182:185], 0
	v_mfma_f32_16x16x32_bf16 v[34:37], v[150:153], v[182:185], 0
	s_waitcnt lgkmcnt(3)
	v_mfma_f32_16x16x32_bf16 v[26:29], v[142:145], v[190:193], 0
	v_mfma_f32_16x16x32_bf16 v[18:21], v[150:153], v[190:193], 0
	s_waitcnt lgkmcnt(1)
	v_mfma_f32_16x16x32_bf16 v[10:13], v[142:145], v[198:201], 0
	v_mfma_f32_16x16x32_bf16 v[6:9], v[150:153], v[198:201], 0
	v_mfma_f32_16x16x32_bf16 v[58:61], v[146:149], v[178:181], v[58:61]
	v_mfma_f32_16x16x32_bf16 v[50:53], v[154:157], v[178:181], v[50:53]
	v_mfma_f32_16x16x32_bf16 v[42:45], v[146:149], v[186:189], v[42:45]
	v_mfma_f32_16x16x32_bf16 v[34:37], v[154:157], v[186:189], v[34:37]
	v_mfma_f32_16x16x32_bf16 v[26:29], v[146:149], v[194:197], v[26:29]
	v_mfma_f32_16x16x32_bf16 v[18:21], v[154:157], v[194:197], v[18:21]
	s_waitcnt lgkmcnt(0)
	v_mfma_f32_16x16x32_bf16 v[10:13], v[146:149], v[202:205], v[10:13]
	v_mfma_f32_16x16x32_bf16 v[6:9], v[154:157], v[202:205], v[6:9]
	v_mfma_f32_16x16x32_bf16 v[62:65], v[158:161], v[174:177], 0
	v_mfma_f32_16x16x32_bf16 v[54:57], v[166:169], v[174:177], 0
	v_mfma_f32_16x16x32_bf16 v[46:49], v[158:161], v[182:185], 0
	v_mfma_f32_16x16x32_bf16 v[38:41], v[166:169], v[182:185], 0
	v_mfma_f32_16x16x32_bf16 v[30:33], v[158:161], v[190:193], 0
	v_mfma_f32_16x16x32_bf16 v[22:25], v[166:169], v[190:193], 0
	v_mfma_f32_16x16x32_bf16 v[14:17], v[158:161], v[198:201], 0
	v_mfma_f32_16x16x32_bf16 v[2:5], v[166:169], v[198:201], 0
	v_mfma_f32_16x16x32_bf16 v[62:65], v[162:165], v[178:181], v[62:65]
	v_mfma_f32_16x16x32_bf16 v[54:57], v[170:173], v[178:181], v[54:57]
	v_mfma_f32_16x16x32_bf16 v[46:49], v[162:165], v[186:189], v[46:49]
	v_mfma_f32_16x16x32_bf16 v[38:41], v[170:173], v[186:189], v[38:41]
	v_mfma_f32_16x16x32_bf16 v[30:33], v[162:165], v[194:197], v[30:33]
	v_mfma_f32_16x16x32_bf16 v[22:25], v[170:173], v[194:197], v[22:25]
	v_mfma_f32_16x16x32_bf16 v[14:17], v[162:165], v[202:205], v[14:17]
	v_mfma_f32_16x16x32_bf16 v[2:5], v[170:173], v[202:205], v[2:5]
	s_barrier
	v_add_u32_e32 v134, 0x18000, v139
	ds_read_b128 v[142:145], v134
	ds_read_b128 v[146:149], v134 offset:1024
	ds_read_b128 v[150:153], v134 offset:2048
	ds_read_b128 v[154:157], v134 offset:3072
	v_add_u32_e32 v134, 0x1c000, v139
	ds_read_b128 v[158:161], v134
	ds_read_b128 v[162:165], v134 offset:1024
	ds_read_b128 v[166:169], v134 offset:2048
	ds_read_b128 v[170:173], v134 offset:3072
	ds_read_b128 v[174:177], v140 offset:32768
	ds_read_b128 v[178:181], v140 offset:33792
	ds_read_b128 v[182:185], v140 offset:34816
	ds_read_b128 v[186:189], v140 offset:35840
	ds_read_b128 v[190:193], v140 offset:36864
	ds_read_b128 v[194:197], v140 offset:37888
	ds_read_b128 v[198:201], v140 offset:38912
	ds_read_b128 v[202:205], v140 offset:39936
	s_add_u32 s44, s34, 0x40000
	s_addc_u32 s45, s35, 0
	s_mov_b32 m0, s61
	s_nop 0
	global_load_lds_dwordx4 v1, s[44:45]
	s_add_u32 s44, s34, 0x60000
	s_addc_u32 s45, s35, 0
	s_mov_b32 m0, s62
	s_nop 0
	global_load_lds_dwordx4 v1, s[44:45]
	s_waitcnt vmcnt(8)
	s_waitcnt lgkmcnt(0)
	s_barrier
	s_waitcnt lgkmcnt(7)
	v_mfma_f32_16x16x32_bf16 v[122:125], v[142:145], v[174:177], v[122:125]
	v_mfma_f32_16x16x32_bf16 v[114:117], v[150:153], v[174:177], v[114:117]
	s_waitcnt lgkmcnt(5)
	v_mfma_f32_16x16x32_bf16 v[106:109], v[142:145], v[182:185], v[106:109]
	v_mfma_f32_16x16x32_bf16 v[98:101], v[150:153], v[182:185], v[98:101]
	s_waitcnt lgkmcnt(3)
	v_mfma_f32_16x16x32_bf16 v[90:93], v[142:145], v[190:193], v[90:93]
	v_mfma_f32_16x16x32_bf16 v[82:85], v[150:153], v[190:193], v[82:85]
	s_waitcnt lgkmcnt(1)
	v_mfma_f32_16x16x32_bf16 v[74:77], v[142:145], v[198:201], v[74:77]
	v_mfma_f32_16x16x32_bf16 v[66:69], v[150:153], v[198:201], v[66:69]
	v_mfma_f32_16x16x32_bf16 v[122:125], v[146:149], v[178:181], v[122:125]
	v_mfma_f32_16x16x32_bf16 v[114:117], v[154:157], v[178:181], v[114:117]
	v_mfma_f32_16x16x32_bf16 v[106:109], v[146:149], v[186:189], v[106:109]
	v_mfma_f32_16x16x32_bf16 v[98:101], v[154:157], v[186:189], v[98:101]
	v_mfma_f32_16x16x32_bf16 v[90:93], v[146:149], v[194:197], v[90:93]
	v_mfma_f32_16x16x32_bf16 v[82:85], v[154:157], v[194:197], v[82:85]
	s_waitcnt lgkmcnt(0)
	v_mfma_f32_16x16x32_bf16 v[74:77], v[146:149], v[202:205], v[74:77]
	v_mfma_f32_16x16x32_bf16 v[66:69], v[154:157], v[202:205], v[66:69]
	v_mfma_f32_16x16x32_bf16 v[126:129], v[158:161], v[174:177], v[126:129]
	v_mfma_f32_16x16x32_bf16 v[118:121], v[166:169], v[174:177], v[118:121]
	v_mfma_f32_16x16x32_bf16 v[110:113], v[158:161], v[182:185], v[110:113]
	v_mfma_f32_16x16x32_bf16 v[102:105], v[166:169], v[182:185], v[102:105]
	v_mfma_f32_16x16x32_bf16 v[94:97], v[158:161], v[190:193], v[94:97]
	v_mfma_f32_16x16x32_bf16 v[86:89], v[166:169], v[190:193], v[86:89]
	v_mfma_f32_16x16x32_bf16 v[78:81], v[158:161], v[198:201], v[78:81]
	v_mfma_f32_16x16x32_bf16 v[70:73], v[166:169], v[198:201], v[70:73]
	v_mfma_f32_16x16x32_bf16 v[126:129], v[162:165], v[178:181], v[126:129]
	v_mfma_f32_16x16x32_bf16 v[118:121], v[170:173], v[178:181], v[118:121]
	v_mfma_f32_16x16x32_bf16 v[110:113], v[162:165], v[186:189], v[110:113]
	v_mfma_f32_16x16x32_bf16 v[102:105], v[170:173], v[186:189], v[102:105]
	v_mfma_f32_16x16x32_bf16 v[94:97], v[162:165], v[194:197], v[94:97]
	v_mfma_f32_16x16x32_bf16 v[86:89], v[170:173], v[194:197], v[86:89]
	v_mfma_f32_16x16x32_bf16 v[78:81], v[162:165], v[202:205], v[78:81]
	v_mfma_f32_16x16x32_bf16 v[70:73], v[170:173], v[202:205], v[70:73]
	s_barrier
	s_add_u32 s44, s52, 0x80
	s_addc_u32 s45, s53, 0
	ds_read_b128 v[174:177], v140 offset:49152
	ds_read_b128 v[178:181], v140 offset:50176
	ds_read_b128 v[182:185], v140 offset:51200
	ds_read_b128 v[186:189], v140 offset:52224
	ds_read_b128 v[190:193], v140 offset:53248
	ds_read_b128 v[194:197], v140 offset:54272
	ds_read_b128 v[198:201], v140 offset:55296
	ds_read_b128 v[202:205], v140 offset:56320
	s_mov_b32 m0, s63
	s_nop 0
	global_load_lds_dwordx4 v136, s[44:45]
	s_add_u32 s44, s52, 0x20080
	s_addc_u32 s45, s53, 0
	s_mov_b32 m0, s64
	s_nop 0
	global_load_lds_dwordx4 v136, s[44:45]
	s_add_u32 s44, s52, 0x40080
	s_addc_u32 s45, s53, 0
	s_mov_b32 m0, s67
	s_nop 0
	global_load_lds_dwordx4 v136, s[44:45]
	s_add_u32 s44, s52, 0x60080
	s_addc_u32 s45, s53, 0
	s_mov_b32 m0, s73
	s_nop 0
	global_load_lds_dwordx4 v136, s[44:45]
	s_add_u32 s34, s34, 0x20080
	s_mov_b32 m0, s65
	s_nop 0
	global_load_lds_dwordx4 v1, s[50:51]
	s_addc_u32 s35, s35, 0
	s_mov_b32 m0, s66
	s_nop 0
	global_load_lds_dwordx4 v1, s[34:35]
	s_waitcnt vmcnt(8)
	s_waitcnt lgkmcnt(0)
	s_barrier
	s_waitcnt lgkmcnt(7)
	v_mfma_f32_16x16x32_bf16 v[58:61], v[142:145], v[174:177], v[58:61]
	v_mfma_f32_16x16x32_bf16 v[50:53], v[150:153], v[174:177], v[50:53]
	s_waitcnt lgkmcnt(5)
	v_mfma_f32_16x16x32_bf16 v[42:45], v[142:145], v[182:185], v[42:45]
	v_mfma_f32_16x16x32_bf16 v[34:37], v[150:153], v[182:185], v[34:37]
	s_waitcnt lgkmcnt(3)
	v_mfma_f32_16x16x32_bf16 v[26:29], v[142:145], v[190:193], v[26:29]
	v_mfma_f32_16x16x32_bf16 v[18:21], v[150:153], v[190:193], v[18:21]
	s_waitcnt lgkmcnt(1)
	v_mfma_f32_16x16x32_bf16 v[10:13], v[142:145], v[198:201], v[10:13]
	v_mfma_f32_16x16x32_bf16 v[6:9], v[150:153], v[198:201], v[6:9]
	v_mfma_f32_16x16x32_bf16 v[58:61], v[146:149], v[178:181], v[58:61]
	v_mfma_f32_16x16x32_bf16 v[50:53], v[154:157], v[178:181], v[50:53]
	v_mfma_f32_16x16x32_bf16 v[42:45], v[146:149], v[186:189], v[42:45]
	v_mfma_f32_16x16x32_bf16 v[34:37], v[154:157], v[186:189], v[34:37]
	v_mfma_f32_16x16x32_bf16 v[26:29], v[146:149], v[194:197], v[26:29]
	v_mfma_f32_16x16x32_bf16 v[18:21], v[154:157], v[194:197], v[18:21]
	s_waitcnt lgkmcnt(0)
	v_mfma_f32_16x16x32_bf16 v[10:13], v[146:149], v[202:205], v[10:13]
	v_mfma_f32_16x16x32_bf16 v[6:9], v[154:157], v[202:205], v[6:9]
	v_mfma_f32_16x16x32_bf16 v[62:65], v[158:161], v[174:177], v[62:65]
	v_mfma_f32_16x16x32_bf16 v[54:57], v[166:169], v[174:177], v[54:57]
	v_mfma_f32_16x16x32_bf16 v[46:49], v[158:161], v[182:185], v[46:49]
	v_mfma_f32_16x16x32_bf16 v[38:41], v[166:169], v[182:185], v[38:41]
	v_mfma_f32_16x16x32_bf16 v[30:33], v[158:161], v[190:193], v[30:33]
	v_mfma_f32_16x16x32_bf16 v[22:25], v[166:169], v[190:193], v[22:25]
	v_mfma_f32_16x16x32_bf16 v[14:17], v[158:161], v[198:201], v[14:17]
	v_mfma_f32_16x16x32_bf16 v[2:5], v[166:169], v[198:201], v[2:5]
	v_mfma_f32_16x16x32_bf16 v[62:65], v[162:165], v[178:181], v[62:65]
	v_mfma_f32_16x16x32_bf16 v[54:57], v[170:173], v[178:181], v[54:57]
	v_mfma_f32_16x16x32_bf16 v[46:49], v[162:165], v[186:189], v[46:49]
	v_mfma_f32_16x16x32_bf16 v[38:41], v[170:173], v[186:189], v[38:41]
	v_mfma_f32_16x16x32_bf16 v[30:33], v[162:165], v[194:197], v[30:33]
	v_mfma_f32_16x16x32_bf16 v[22:25], v[170:173], v[194:197], v[22:25]
	v_mfma_f32_16x16x32_bf16 v[14:17], v[162:165], v[202:205], v[14:17]
	v_mfma_f32_16x16x32_bf16 v[2:5], v[170:173], v[202:205], v[2:5]
	s_barrier
	s_add_i32 s81, s81, 2
	s_add_u32 s79, s79, 0x100
	s_addc_u32 s80, s80, 0
	s_cmp_gt_u32 s81, 13
	s_mov_b64 s[44:45], s[0:1]

.LBB0_751:
	s_ashr_i32 s37, s36, 31
	s_lshl_b64 s[14:15], s[36:37], 19
	s_add_u32 s38, s16, s14
	s_addc_u32 s39, s17, s15
	s_and_b64 s[14:15], s[4:5], exec
	s_cselect_b32 s7, s39, s45
	s_cselect_b32 s9, s38, s44
	s_ashr_i32 s27, s26, 31
	s_lshl_b64 s[14:15], s[26:27], 19
	s_add_u32 s42, s55, s14
	s_addc_u32 s43, s56, s15
	s_and_b64 s[14:15], s[4:5], exec
	s_cselect_b32 s14, s43, s1
	s_cselect_b32 s15, s42, s0
	s_add_u32 s27, s0, 0x100
	s_addc_u32 s37, s1, 0
	s_mov_b32 vcc_lo, -2
	v_add_u32_e32 v138, 0x10000, v143
	ds_read_b128 v[130:133], v138
	ds_read_b128 v[154:157], v138 offset:1024
	ds_read_b128 v[158:161], v138 offset:2048
	ds_read_b128 v[162:165], v138 offset:3072
	v_add_u32_e32 v138, 0x14000, v143
	ds_read_b128 v[166:169], v138
	ds_read_b128 v[170:173], v138 offset:1024
	ds_read_b128 v[174:177], v138 offset:2048
	ds_read_b128 v[178:181], v138 offset:3072
	s_add_u32 s0, s44, 0x100
	s_addc_u32 s1, s45, 0
	s_cmp_eq_u32 vcc_lo, 12
	s_cselect_b32 s34, s9, s0
	s_cselect_b32 s35, s7, s1
	s_cselect_b32 s52, s15, s27
	s_cselect_b32 s53, s14, s37
	s_add_u32 s50, s34, 0x80
	s_addc_u32 s51, s35, 0
	ds_read_b128 v[182:185], v145
	ds_read_b128 v[186:189], v145 offset:1024
	ds_read_b128 v[190:193], v145 offset:2048
	ds_read_b128 v[194:197], v145 offset:3072
	ds_read_b128 v[198:201], v145 offset:4096
	ds_read_b128 v[202:205], v145 offset:5120
	ds_read_b128 v[206:209], v145 offset:6144
	ds_read_b128 v[210:213], v145 offset:7168
	s_add_u32 s2, s44, 0x40080
	s_addc_u32 s3, s45, 0
	s_mov_b32 m0, s96
	s_nop 0
	global_load_lds_dwordx4 v1, s[2:3]
	s_add_u32 s2, s44, 0x60080
	s_addc_u32 s3, s45, 0
	s_add_i32 s12, s58, 0xe000
	s_mov_b32 m0, s12
	s_nop 0
	global_load_lds_dwordx4 v1, s[2:3]
	s_waitcnt vmcnt(8)
	s_waitcnt lgkmcnt(0)
	s_barrier
	s_waitcnt lgkmcnt(7)
	v_mfma_f32_16x16x32_bf16 v[118:121], v[130:133], v[182:185], 0
	v_mfma_f32_16x16x32_bf16 v[114:117], v[158:161], v[182:185], 0
	s_waitcnt lgkmcnt(5)
	v_mfma_f32_16x16x32_bf16 v[102:105], v[130:133], v[190:193], 0
	v_mfma_f32_16x16x32_bf16 v[98:101], v[158:161], v[190:193], 0
	s_waitcnt lgkmcnt(3)
	v_mfma_f32_16x16x32_bf16 v[86:89], v[130:133], v[198:201], 0
	v_mfma_f32_16x16x32_bf16 v[82:85], v[158:161], v[198:201], 0
	s_waitcnt lgkmcnt(1)
	v_mfma_f32_16x16x32_bf16 v[70:73], v[130:133], v[206:209], 0
	v_mfma_f32_16x16x32_bf16 v[66:69], v[158:161], v[206:209], 0
	v_mfma_f32_16x16x32_bf16 v[118:121], v[154:157], v[186:189], v[118:121]
	v_mfma_f32_16x16x32_bf16 v[114:117], v[162:165], v[186:189], v[114:117]
	v_mfma_f32_16x16x32_bf16 v[102:105], v[154:157], v[194:197], v[102:105]
	v_mfma_f32_16x16x32_bf16 v[98:101], v[162:165], v[194:197], v[98:101]
	v_mfma_f32_16x16x32_bf16 v[86:89], v[154:157], v[202:205], v[86:89]
	v_mfma_f32_16x16x32_bf16 v[82:85], v[162:165], v[202:205], v[82:85]
	s_waitcnt lgkmcnt(0)
	v_mfma_f32_16x16x32_bf16 v[70:73], v[154:157], v[210:213], v[70:73]
	v_mfma_f32_16x16x32_bf16 v[66:69], v[162:165], v[210:213], v[66:69]
	v_mfma_f32_16x16x32_bf16 v[126:129], v[166:169], v[182:185], 0
	v_mfma_f32_16x16x32_bf16 v[122:125], v[174:177], v[182:185], 0
	v_mfma_f32_16x16x32_bf16 v[110:113], v[166:169], v[190:193], 0
	v_mfma_f32_16x16x32_bf16 v[106:109], v[174:177], v[190:193], 0
	v_mfma_f32_16x16x32_bf16 v[94:97], v[166:169], v[198:201], 0
	v_mfma_f32_16x16x32_bf16 v[90:93], v[174:177], v[198:201], 0
	v_mfma_f32_16x16x32_bf16 v[78:81], v[166:169], v[206:209], 0
	v_mfma_f32_16x16x32_bf16 v[74:77], v[174:177], v[206:209], 0
	v_mfma_f32_16x16x32_bf16 v[126:129], v[170:173], v[186:189], v[126:129]
	v_mfma_f32_16x16x32_bf16 v[122:125], v[178:181], v[186:189], v[122:125]
	v_mfma_f32_16x16x32_bf16 v[110:113], v[170:173], v[194:197], v[110:113]
	v_mfma_f32_16x16x32_bf16 v[106:109], v[178:181], v[194:197], v[106:109]
	v_mfma_f32_16x16x32_bf16 v[94:97], v[170:173], v[202:205], v[94:97]
	v_mfma_f32_16x16x32_bf16 v[90:93], v[178:181], v[202:205], v[90:93]
	v_mfma_f32_16x16x32_bf16 v[78:81], v[170:173], v[210:213], v[78:81]
	v_mfma_f32_16x16x32_bf16 v[74:77], v[178:181], v[210:213], v[74:77]
	s_barrier
	ds_read_b128 v[182:185], v145 offset:16384
	ds_read_b128 v[186:189], v145 offset:17408
	ds_read_b128 v[190:193], v145 offset:18432
	ds_read_b128 v[194:197], v145 offset:19456
	ds_read_b128 v[198:201], v145 offset:20480
	ds_read_b128 v[202:205], v145 offset:21504
	ds_read_b128 v[206:209], v145 offset:22528
	ds_read_b128 v[210:213], v145 offset:23552
	s_mov_b32 m0, s60
	s_nop 0
	global_load_lds_dwordx4 v135, s[52:53]
	s_add_u32 s2, s52, 0x20000
	s_addc_u32 s3, s53, 0
	s_mov_b32 m0, s61
	s_nop 0
	global_load_lds_dwordx4 v135, s[2:3]
	s_add_u32 s2, s52, 0x40000
	s_addc_u32 s3, s53, 0
	s_mov_b32 m0, s62
	s_nop 0
	global_load_lds_dwordx4 v135, s[2:3]
	s_add_u32 s2, s52, 0x60000
	s_addc_u32 s3, s53, 0
	s_mov_b32 m0, s63
	s_nop 0
	global_load_lds_dwordx4 v135, s[2:3]
	s_mov_b32 m0, s58
	s_nop 0
	global_load_lds_dwordx4 v1, s[34:35]
	s_add_u32 s2, s34, 0x20000
	s_addc_u32 s3, s35, 0
	s_mov_b32 m0, s64
	s_nop 0
	global_load_lds_dwordx4 v1, s[2:3]
	s_waitcnt vmcnt(8)
	s_waitcnt lgkmcnt(0)
	s_barrier
	s_waitcnt lgkmcnt(7)
	v_mfma_f32_16x16x32_bf16 v[54:57], v[130:133], v[182:185], 0
	v_mfma_f32_16x16x32_bf16 v[50:53], v[158:161], v[182:185], 0
	s_waitcnt lgkmcnt(5)
	v_mfma_f32_16x16x32_bf16 v[38:41], v[130:133], v[190:193], 0
	v_mfma_f32_16x16x32_bf16 v[34:37], v[158:161], v[190:193], 0
	s_waitcnt lgkmcnt(3)
	v_mfma_f32_16x16x32_bf16 v[22:25], v[130:133], v[198:201], 0
	v_mfma_f32_16x16x32_bf16 v[18:21], v[158:161], v[198:201], 0
	s_waitcnt lgkmcnt(1)
	v_mfma_f32_16x16x32_bf16 v[10:13], v[130:133], v[206:209], 0
	v_mfma_f32_16x16x32_bf16 v[6:9], v[158:161], v[206:209], 0
	v_mfma_f32_16x16x32_bf16 v[54:57], v[154:157], v[186:189], v[54:57]
	v_mfma_f32_16x16x32_bf16 v[50:53], v[162:165], v[186:189], v[50:53]
	v_mfma_f32_16x16x32_bf16 v[38:41], v[154:157], v[194:197], v[38:41]
	v_mfma_f32_16x16x32_bf16 v[34:37], v[162:165], v[194:197], v[34:37]
	v_mfma_f32_16x16x32_bf16 v[22:25], v[154:157], v[202:205], v[22:25]
	v_mfma_f32_16x16x32_bf16 v[18:21], v[162:165], v[202:205], v[18:21]
	s_waitcnt lgkmcnt(0)
	v_mfma_f32_16x16x32_bf16 v[10:13], v[154:157], v[210:213], v[10:13]
	v_mfma_f32_16x16x32_bf16 v[6:9], v[162:165], v[210:213], v[6:9]
	v_mfma_f32_16x16x32_bf16 v[62:65], v[166:169], v[182:185], 0
	v_mfma_f32_16x16x32_bf16 v[58:61], v[174:177], v[182:185], 0
	v_mfma_f32_16x16x32_bf16 v[46:49], v[166:169], v[190:193], 0
	v_mfma_f32_16x16x32_bf16 v[42:45], v[174:177], v[190:193], 0
	v_mfma_f32_16x16x32_bf16 v[30:33], v[166:169], v[198:201], 0
	v_mfma_f32_16x16x32_bf16 v[26:29], v[174:177], v[198:201], 0
	v_mfma_f32_16x16x32_bf16 v[14:17], v[166:169], v[206:209], 0
	v_mfma_f32_16x16x32_bf16 v[2:5], v[174:177], v[206:209], 0
	v_mfma_f32_16x16x32_bf16 v[62:65], v[170:173], v[186:189], v[62:65]
	v_mfma_f32_16x16x32_bf16 v[58:61], v[178:181], v[186:189], v[58:61]
	v_mfma_f32_16x16x32_bf16 v[46:49], v[170:173], v[194:197], v[46:49]
	v_mfma_f32_16x16x32_bf16 v[42:45], v[178:181], v[194:197], v[42:45]
	v_mfma_f32_16x16x32_bf16 v[30:33], v[170:173], v[202:205], v[30:33]
	v_mfma_f32_16x16x32_bf16 v[26:29], v[178:181], v[202:205], v[26:29]
	v_mfma_f32_16x16x32_bf16 v[14:17], v[170:173], v[210:213], v[14:17]
	v_mfma_f32_16x16x32_bf16 v[2:5], v[178:181], v[210:213], v[2:5]
	s_barrier
	v_add_u32_e32 v138, 0x18000, v143
	ds_read_b128 v[130:133], v138
	ds_read_b128 v[154:157], v138 offset:1024
	ds_read_b128 v[158:161], v138 offset:2048
	ds_read_b128 v[162:165], v138 offset:3072
	v_add_u32_e32 v138, 0x1c000, v143
	ds_read_b128 v[166:169], v138
	ds_read_b128 v[170:173], v138 offset:1024
	ds_read_b128 v[174:177], v138 offset:2048
	ds_read_b128 v[178:181], v138 offset:3072
	ds_read_b128 v[182:185], v145 offset:32768
	ds_read_b128 v[186:189], v145 offset:33792
	ds_read_b128 v[190:193], v145 offset:34816
	ds_read_b128 v[194:197], v145 offset:35840
	ds_read_b128 v[198:201], v145 offset:36864
	ds_read_b128 v[202:205], v145 offset:37888
	ds_read_b128 v[206:209], v145 offset:38912
	ds_read_b128 v[210:213], v145 offset:39936
	s_add_u32 s2, s34, 0x40000
	s_addc_u32 s3, s35, 0
	s_mov_b32 m0, s65
	s_nop 0
	global_load_lds_dwordx4 v1, s[2:3]
	s_add_u32 s2, s34, 0x60000
	s_addc_u32 s3, s35, 0
	s_mov_b32 m0, s66
	s_nop 0
	global_load_lds_dwordx4 v1, s[2:3]
	s_waitcnt vmcnt(8)
	s_waitcnt lgkmcnt(0)
	s_barrier
	s_waitcnt lgkmcnt(7)
	v_mfma_f32_16x16x32_bf16 v[118:121], v[130:133], v[182:185], v[118:121]
	v_mfma_f32_16x16x32_bf16 v[114:117], v[158:161], v[182:185], v[114:117]
	s_waitcnt lgkmcnt(5)
	v_mfma_f32_16x16x32_bf16 v[102:105], v[130:133], v[190:193], v[102:105]
	v_mfma_f32_16x16x32_bf16 v[98:101], v[158:161], v[190:193], v[98:101]
	s_waitcnt lgkmcnt(3)
	v_mfma_f32_16x16x32_bf16 v[86:89], v[130:133], v[198:201], v[86:89]
	v_mfma_f32_16x16x32_bf16 v[82:85], v[158:161], v[198:201], v[82:85]
	s_waitcnt lgkmcnt(1)
	v_mfma_f32_16x16x32_bf16 v[70:73], v[130:133], v[206:209], v[70:73]
	v_mfma_f32_16x16x32_bf16 v[66:69], v[158:161], v[206:209], v[66:69]
	v_mfma_f32_16x16x32_bf16 v[118:121], v[154:157], v[186:189], v[118:121]
	v_mfma_f32_16x16x32_bf16 v[114:117], v[162:165], v[186:189], v[114:117]
	v_mfma_f32_16x16x32_bf16 v[102:105], v[154:157], v[194:197], v[102:105]
	v_mfma_f32_16x16x32_bf16 v[98:101], v[162:165], v[194:197], v[98:101]
	v_mfma_f32_16x16x32_bf16 v[86:89], v[154:157], v[202:205], v[86:89]
	v_mfma_f32_16x16x32_bf16 v[82:85], v[162:165], v[202:205], v[82:85]
	s_waitcnt lgkmcnt(0)
	v_mfma_f32_16x16x32_bf16 v[70:73], v[154:157], v[210:213], v[70:73]
	v_mfma_f32_16x16x32_bf16 v[66:69], v[162:165], v[210:213], v[66:69]
	v_mfma_f32_16x16x32_bf16 v[126:129], v[166:169], v[182:185], v[126:129]
	v_mfma_f32_16x16x32_bf16 v[122:125], v[174:177], v[182:185], v[122:125]
	v_mfma_f32_16x16x32_bf16 v[110:113], v[166:169], v[190:193], v[110:113]
	v_mfma_f32_16x16x32_bf16 v[106:109], v[174:177], v[190:193], v[106:109]
	v_mfma_f32_16x16x32_bf16 v[94:97], v[166:169], v[198:201], v[94:97]
	v_mfma_f32_16x16x32_bf16 v[90:93], v[174:177], v[198:201], v[90:93]
	v_mfma_f32_16x16x32_bf16 v[78:81], v[166:169], v[206:209], v[78:81]
	v_mfma_f32_16x16x32_bf16 v[74:77], v[174:177], v[206:209], v[74:77]
	v_mfma_f32_16x16x32_bf16 v[126:129], v[170:173], v[186:189], v[126:129]
	v_mfma_f32_16x16x32_bf16 v[122:125], v[178:181], v[186:189], v[122:125]
	v_mfma_f32_16x16x32_bf16 v[110:113], v[170:173], v[194:197], v[110:113]
	v_mfma_f32_16x16x32_bf16 v[106:109], v[178:181], v[194:197], v[106:109]
	v_mfma_f32_16x16x32_bf16 v[94:97], v[170:173], v[202:205], v[94:97]
	v_mfma_f32_16x16x32_bf16 v[90:93], v[178:181], v[202:205], v[90:93]
	v_mfma_f32_16x16x32_bf16 v[78:81], v[170:173], v[210:213], v[78:81]
	v_mfma_f32_16x16x32_bf16 v[74:77], v[178:181], v[210:213], v[74:77]
	s_barrier
	s_add_u32 s2, s52, 0x80
	s_addc_u32 s3, s53, 0
	ds_read_b128 v[182:185], v145 offset:49152
	ds_read_b128 v[186:189], v145 offset:50176
	ds_read_b128 v[190:193], v145 offset:51200
	ds_read_b128 v[194:197], v145 offset:52224
	ds_read_b128 v[198:201], v145 offset:53248
	ds_read_b128 v[202:205], v145 offset:54272
	ds_read_b128 v[206:209], v145 offset:55296
	ds_read_b128 v[210:213], v145 offset:56320
	s_mov_b32 m0, s90
	s_nop 0
	global_load_lds_dwordx4 v135, s[2:3]
	s_add_u32 s2, s52, 0x20080
	s_addc_u32 s3, s53, 0
	s_mov_b32 m0, s91
	s_nop 0
	global_load_lds_dwordx4 v135, s[2:3]
	s_add_u32 s2, s52, 0x40080
	s_addc_u32 s3, s53, 0
	s_mov_b32 m0, s94
	s_nop 0
	global_load_lds_dwordx4 v135, s[2:3]
	s_add_u32 s2, s52, 0x60080
	s_addc_u32 s3, s53, 0
	s_mov_b32 m0, s95
	s_nop 0
	global_load_lds_dwordx4 v135, s[2:3]
	s_mov_b32 m0, s92
	s_nop 0
	global_load_lds_dwordx4 v1, s[50:51]
	s_add_u32 s2, s34, 0x20080
	s_addc_u32 s3, s35, 0
	s_mov_b32 m0, s93
	s_nop 0
	global_load_lds_dwordx4 v1, s[2:3]
	s_waitcnt vmcnt(8)
	s_waitcnt lgkmcnt(0)
	s_barrier
	s_waitcnt lgkmcnt(7)
	v_mfma_f32_16x16x32_bf16 v[54:57], v[130:133], v[182:185], v[54:57]
	v_mfma_f32_16x16x32_bf16 v[50:53], v[158:161], v[182:185], v[50:53]
	s_waitcnt lgkmcnt(5)
	v_mfma_f32_16x16x32_bf16 v[38:41], v[130:133], v[190:193], v[38:41]
	v_mfma_f32_16x16x32_bf16 v[34:37], v[158:161], v[190:193], v[34:37]
	s_waitcnt lgkmcnt(3)
	v_mfma_f32_16x16x32_bf16 v[22:25], v[130:133], v[198:201], v[22:25]
	v_mfma_f32_16x16x32_bf16 v[18:21], v[158:161], v[198:201], v[18:21]
	s_waitcnt lgkmcnt(1)
	v_mfma_f32_16x16x32_bf16 v[10:13], v[130:133], v[206:209], v[10:13]
	v_mfma_f32_16x16x32_bf16 v[6:9], v[158:161], v[206:209], v[6:9]
	v_mfma_f32_16x16x32_bf16 v[54:57], v[154:157], v[186:189], v[54:57]
	v_mfma_f32_16x16x32_bf16 v[50:53], v[162:165], v[186:189], v[50:53]
	v_mfma_f32_16x16x32_bf16 v[38:41], v[154:157], v[194:197], v[38:41]
	v_mfma_f32_16x16x32_bf16 v[34:37], v[162:165], v[194:197], v[34:37]
	v_mfma_f32_16x16x32_bf16 v[22:25], v[154:157], v[202:205], v[22:25]
	v_mfma_f32_16x16x32_bf16 v[18:21], v[162:165], v[202:205], v[18:21]
	s_waitcnt lgkmcnt(0)
	v_mfma_f32_16x16x32_bf16 v[10:13], v[154:157], v[210:213], v[10:13]
	v_mfma_f32_16x16x32_bf16 v[6:9], v[162:165], v[210:213], v[6:9]
	v_mfma_f32_16x16x32_bf16 v[62:65], v[166:169], v[182:185], v[62:65]
	v_mfma_f32_16x16x32_bf16 v[58:61], v[174:177], v[182:185], v[58:61]
	v_mfma_f32_16x16x32_bf16 v[46:49], v[166:169], v[190:193], v[46:49]
	v_mfma_f32_16x16x32_bf16 v[42:45], v[174:177], v[190:193], v[42:45]
	v_mfma_f32_16x16x32_bf16 v[30:33], v[166:169], v[198:201], v[30:33]
	v_mfma_f32_16x16x32_bf16 v[26:29], v[174:177], v[198:201], v[26:29]
	v_mfma_f32_16x16x32_bf16 v[14:17], v[166:169], v[206:209], v[14:17]
	v_mfma_f32_16x16x32_bf16 v[2:5], v[174:177], v[206:209], v[2:5]
	v_mfma_f32_16x16x32_bf16 v[62:65], v[170:173], v[186:189], v[62:65]
	v_mfma_f32_16x16x32_bf16 v[58:61], v[178:181], v[186:189], v[58:61]
	v_mfma_f32_16x16x32_bf16 v[46:49], v[170:173], v[194:197], v[46:49]
	v_mfma_f32_16x16x32_bf16 v[42:45], v[178:181], v[194:197], v[42:45]
	v_mfma_f32_16x16x32_bf16 v[30:33], v[170:173], v[202:205], v[30:33]
	v_mfma_f32_16x16x32_bf16 v[26:29], v[178:181], v[202:205], v[26:29]
	v_mfma_f32_16x16x32_bf16 v[14:17], v[170:173], v[210:213], v[14:17]
	v_mfma_f32_16x16x32_bf16 v[2:5], v[178:181], v[210:213], v[2:5]
	s_barrier
	s_add_i32 vcc_lo, vcc_lo, 2
	s_add_u32 s27, s27, 0x100
	s_addc_u32 s37, s37, 0
	s_cmp_gt_u32 vcc_lo, 13
	s_mov_b64 s[44:45], s[0:1]

.LBB0_799:
	s_ashr_i32 s25, s24, 31
	s_lshl_b64 s[2:3], s[24:25], 19
	s_add_u32 s26, s16, s2
	s_addc_u32 s27, s17, s3
	s_and_b64 s[2:3], s[4:5], exec
	s_cselect_b32 s14, s27, s43
	s_cselect_b32 s15, s26, s42
	s_ashr_i32 s11, s10, 31
	s_lshl_b64 s[2:3], s[10:11], 19
	s_add_u32 s36, s40, s2
	s_addc_u32 s37, s41, s3
	s_and_b64 s[2:3], s[4:5], exec
	s_cselect_b32 s11, s37, s1
	s_cselect_b32 s25, s36, s0
	s_add_u32 s86, s0, 0x100
	s_addc_u32 s87, s1, 0
	s_mov_b32 s88, -2
	v_add_u32_e32 v134, 0x10000, v139
	ds_read_b128 v[142:145], v134
	ds_read_b128 v[146:149], v134 offset:1024
	ds_read_b128 v[150:153], v134 offset:2048
	ds_read_b128 v[154:157], v134 offset:3072
	v_add_u32_e32 v134, 0x14000, v139
	ds_read_b128 v[158:161], v134
	ds_read_b128 v[162:165], v134 offset:1024
	ds_read_b128 v[166:169], v134 offset:2048
	ds_read_b128 v[170:173], v134 offset:3072
	s_add_u32 s0, s42, 0x100
	s_addc_u32 s1, s43, 0
	s_cmp_eq_u32 s88, 12
	s_cselect_b32 s34, s15, s0
	s_cselect_b32 s35, s14, s1
	s_cselect_b32 s50, s25, s86
	s_cselect_b32 s51, s11, s87
	s_add_u32 s44, s34, 0x80
	s_addc_u32 s45, s35, 0
	ds_read_b128 v[174:177], v140
	ds_read_b128 v[178:181], v140 offset:1024
	ds_read_b128 v[182:185], v140 offset:2048
	ds_read_b128 v[186:189], v140 offset:3072
	ds_read_b128 v[190:193], v140 offset:4096
	ds_read_b128 v[194:197], v140 offset:5120
	ds_read_b128 v[198:201], v140 offset:6144
	ds_read_b128 v[202:205], v140 offset:7168
	s_add_u32 s2, s42, 0x40080
	s_addc_u32 s3, s43, 0
	s_mov_b32 m0, s67
	s_nop 0
	global_load_lds_dwordx4 v1, s[2:3]
	s_add_u32 s2, s42, 0x60080
	s_addc_u32 s3, s43, 0
	s_add_i32 s12, s39, 0xe000
	s_mov_b32 m0, s12
	s_nop 0
	global_load_lds_dwordx4 v1, s[2:3]
	s_waitcnt vmcnt(8)
	s_waitcnt lgkmcnt(0)
	s_barrier
	s_waitcnt lgkmcnt(7)
	v_mfma_f32_16x16x32_bf16 v[122:125], v[142:145], v[174:177], 0
	v_mfma_f32_16x16x32_bf16 v[114:117], v[150:153], v[174:177], 0
	s_waitcnt lgkmcnt(5)
	v_mfma_f32_16x16x32_bf16 v[106:109], v[142:145], v[182:185], 0
	v_mfma_f32_16x16x32_bf16 v[98:101], v[150:153], v[182:185], 0
	s_waitcnt lgkmcnt(3)
	v_mfma_f32_16x16x32_bf16 v[90:93], v[142:145], v[190:193], 0
	v_mfma_f32_16x16x32_bf16 v[82:85], v[150:153], v[190:193], 0
	s_waitcnt lgkmcnt(1)
	v_mfma_f32_16x16x32_bf16 v[74:77], v[142:145], v[198:201], 0
	v_mfma_f32_16x16x32_bf16 v[66:69], v[150:153], v[198:201], 0
	v_mfma_f32_16x16x32_bf16 v[122:125], v[146:149], v[178:181], v[122:125]
	v_mfma_f32_16x16x32_bf16 v[114:117], v[154:157], v[178:181], v[114:117]
	v_mfma_f32_16x16x32_bf16 v[106:109], v[146:149], v[186:189], v[106:109]
	v_mfma_f32_16x16x32_bf16 v[98:101], v[154:157], v[186:189], v[98:101]
	v_mfma_f32_16x16x32_bf16 v[90:93], v[146:149], v[194:197], v[90:93]
	v_mfma_f32_16x16x32_bf16 v[82:85], v[154:157], v[194:197], v[82:85]
	s_waitcnt lgkmcnt(0)
	v_mfma_f32_16x16x32_bf16 v[74:77], v[146:149], v[202:205], v[74:77]
	v_mfma_f32_16x16x32_bf16 v[66:69], v[154:157], v[202:205], v[66:69]
	v_mfma_f32_16x16x32_bf16 v[126:129], v[158:161], v[174:177], 0
	v_mfma_f32_16x16x32_bf16 v[118:121], v[166:169], v[174:177], 0
	v_mfma_f32_16x16x32_bf16 v[110:113], v[158:161], v[182:185], 0
	v_mfma_f32_16x16x32_bf16 v[102:105], v[166:169], v[182:185], 0
	v_mfma_f32_16x16x32_bf16 v[94:97], v[158:161], v[190:193], 0
	v_mfma_f32_16x16x32_bf16 v[86:89], v[166:169], v[190:193], 0
	v_mfma_f32_16x16x32_bf16 v[78:81], v[158:161], v[198:201], 0
	v_mfma_f32_16x16x32_bf16 v[70:73], v[166:169], v[198:201], 0
	v_mfma_f32_16x16x32_bf16 v[126:129], v[162:165], v[178:181], v[126:129]
	v_mfma_f32_16x16x32_bf16 v[118:121], v[170:173], v[178:181], v[118:121]
	v_mfma_f32_16x16x32_bf16 v[110:113], v[162:165], v[186:189], v[110:113]
	v_mfma_f32_16x16x32_bf16 v[102:105], v[170:173], v[186:189], v[102:105]
	v_mfma_f32_16x16x32_bf16 v[94:97], v[162:165], v[194:197], v[94:97]
	v_mfma_f32_16x16x32_bf16 v[86:89], v[170:173], v[194:197], v[86:89]
	v_mfma_f32_16x16x32_bf16 v[78:81], v[162:165], v[202:205], v[78:81]
	v_mfma_f32_16x16x32_bf16 v[70:73], v[170:173], v[202:205], v[70:73]
	s_barrier
	ds_read_b128 v[174:177], v140 offset:16384
	ds_read_b128 v[178:181], v140 offset:17408
	ds_read_b128 v[182:185], v140 offset:18432
	ds_read_b128 v[186:189], v140 offset:19456
	ds_read_b128 v[190:193], v140 offset:20480
	ds_read_b128 v[194:197], v140 offset:21504
	ds_read_b128 v[198:201], v140 offset:22528
	ds_read_b128 v[202:205], v140 offset:23552
	s_mov_b32 m0, s54
	s_nop 0
	global_load_lds_dwordx4 v136, s[50:51]
	s_add_u32 s2, s50, 0x20000
	s_addc_u32 s3, s51, 0
	s_mov_b32 m0, s55
	s_nop 0
	global_load_lds_dwordx4 v136, s[2:3]
	s_add_u32 s2, s50, 0x40000
	s_addc_u32 s3, s51, 0
	s_mov_b32 m0, s56
	s_nop 0
	global_load_lds_dwordx4 v136, s[2:3]
	s_add_u32 s2, s50, 0x60000
	s_addc_u32 s3, s51, 0
	s_mov_b32 m0, s57
	s_nop 0
	global_load_lds_dwordx4 v136, s[2:3]
	s_mov_b32 m0, s39
	s_nop 0
	global_load_lds_dwordx4 v1, s[34:35]
	s_add_u32 s2, s34, 0x20000
	s_addc_u32 s3, s35, 0
	s_mov_b32 m0, s58
	s_nop 0
	global_load_lds_dwordx4 v1, s[2:3]
	s_waitcnt vmcnt(8)
	s_waitcnt lgkmcnt(0)
	s_barrier
	s_waitcnt lgkmcnt(7)
	v_mfma_f32_16x16x32_bf16 v[58:61], v[142:145], v[174:177], 0
	v_mfma_f32_16x16x32_bf16 v[50:53], v[150:153], v[174:177], 0
	s_waitcnt lgkmcnt(5)
	v_mfma_f32_16x16x32_bf16 v[42:45], v[142:145], v[182:185], 0
	v_mfma_f32_16x16x32_bf16 v[34:37], v[150:153], v[182:185], 0
	s_waitcnt lgkmcnt(3)
	v_mfma_f32_16x16x32_bf16 v[26:29], v[142:145], v[190:193], 0
	v_mfma_f32_16x16x32_bf16 v[18:21], v[150:153], v[190:193], 0
	s_waitcnt lgkmcnt(1)
	v_mfma_f32_16x16x32_bf16 v[10:13], v[142:145], v[198:201], 0
	v_mfma_f32_16x16x32_bf16 v[6:9], v[150:153], v[198:201], 0
	v_mfma_f32_16x16x32_bf16 v[58:61], v[146:149], v[178:181], v[58:61]
	v_mfma_f32_16x16x32_bf16 v[50:53], v[154:157], v[178:181], v[50:53]
	v_mfma_f32_16x16x32_bf16 v[42:45], v[146:149], v[186:189], v[42:45]
	v_mfma_f32_16x16x32_bf16 v[34:37], v[154:157], v[186:189], v[34:37]
	v_mfma_f32_16x16x32_bf16 v[26:29], v[146:149], v[194:197], v[26:29]
	v_mfma_f32_16x16x32_bf16 v[18:21], v[154:157], v[194:197], v[18:21]
	s_waitcnt lgkmcnt(0)
	v_mfma_f32_16x16x32_bf16 v[10:13], v[146:149], v[202:205], v[10:13]
	v_mfma_f32_16x16x32_bf16 v[6:9], v[154:157], v[202:205], v[6:9]
	v_mfma_f32_16x16x32_bf16 v[62:65], v[158:161], v[174:177], 0
	v_mfma_f32_16x16x32_bf16 v[54:57], v[166:169], v[174:177], 0
	v_mfma_f32_16x16x32_bf16 v[46:49], v[158:161], v[182:185], 0
	v_mfma_f32_16x16x32_bf16 v[38:41], v[166:169], v[182:185], 0
	v_mfma_f32_16x16x32_bf16 v[30:33], v[158:161], v[190:193], 0
	v_mfma_f32_16x16x32_bf16 v[22:25], v[166:169], v[190:193], 0
	v_mfma_f32_16x16x32_bf16 v[14:17], v[158:161], v[198:201], 0
	v_mfma_f32_16x16x32_bf16 v[2:5], v[166:169], v[198:201], 0
	v_mfma_f32_16x16x32_bf16 v[62:65], v[162:165], v[178:181], v[62:65]
	v_mfma_f32_16x16x32_bf16 v[54:57], v[170:173], v[178:181], v[54:57]
	v_mfma_f32_16x16x32_bf16 v[46:49], v[162:165], v[186:189], v[46:49]
	v_mfma_f32_16x16x32_bf16 v[38:41], v[170:173], v[186:189], v[38:41]
	v_mfma_f32_16x16x32_bf16 v[30:33], v[162:165], v[194:197], v[30:33]
	v_mfma_f32_16x16x32_bf16 v[22:25], v[170:173], v[194:197], v[22:25]
	v_mfma_f32_16x16x32_bf16 v[14:17], v[162:165], v[202:205], v[14:17]
	v_mfma_f32_16x16x32_bf16 v[2:5], v[170:173], v[202:205], v[2:5]
	s_barrier
	v_add_u32_e32 v134, 0x18000, v139
	ds_read_b128 v[142:145], v134
	ds_read_b128 v[146:149], v134 offset:1024
	ds_read_b128 v[150:153], v134 offset:2048
	ds_read_b128 v[154:157], v134 offset:3072
	v_add_u32_e32 v134, 0x1c000, v139
	ds_read_b128 v[158:161], v134
	ds_read_b128 v[162:165], v134 offset:1024
	ds_read_b128 v[166:169], v134 offset:2048
	ds_read_b128 v[170:173], v134 offset:3072
	ds_read_b128 v[174:177], v140 offset:32768
	ds_read_b128 v[178:181], v140 offset:33792
	ds_read_b128 v[182:185], v140 offset:34816
	ds_read_b128 v[186:189], v140 offset:35840
	ds_read_b128 v[190:193], v140 offset:36864
	ds_read_b128 v[194:197], v140 offset:37888
	ds_read_b128 v[198:201], v140 offset:38912
	ds_read_b128 v[202:205], v140 offset:39936
	s_add_u32 s2, s34, 0x40000
	s_addc_u32 s3, s35, 0
	s_mov_b32 m0, s59
	s_nop 0
	global_load_lds_dwordx4 v1, s[2:3]
	s_add_u32 s2, s34, 0x60000
	s_addc_u32 s3, s35, 0
	s_mov_b32 m0, s60
	s_nop 0
	global_load_lds_dwordx4 v1, s[2:3]
	s_waitcnt vmcnt(8)
	s_waitcnt lgkmcnt(0)
	s_barrier
	s_waitcnt lgkmcnt(7)
	v_mfma_f32_16x16x32_bf16 v[122:125], v[142:145], v[174:177], v[122:125]
	v_mfma_f32_16x16x32_bf16 v[114:117], v[150:153], v[174:177], v[114:117]
	s_waitcnt lgkmcnt(5)
	v_mfma_f32_16x16x32_bf16 v[106:109], v[142:145], v[182:185], v[106:109]
	v_mfma_f32_16x16x32_bf16 v[98:101], v[150:153], v[182:185], v[98:101]
	s_waitcnt lgkmcnt(3)
	v_mfma_f32_16x16x32_bf16 v[90:93], v[142:145], v[190:193], v[90:93]
	v_mfma_f32_16x16x32_bf16 v[82:85], v[150:153], v[190:193], v[82:85]
	s_waitcnt lgkmcnt(1)
	v_mfma_f32_16x16x32_bf16 v[74:77], v[142:145], v[198:201], v[74:77]
	v_mfma_f32_16x16x32_bf16 v[66:69], v[150:153], v[198:201], v[66:69]
	v_mfma_f32_16x16x32_bf16 v[122:125], v[146:149], v[178:181], v[122:125]
	v_mfma_f32_16x16x32_bf16 v[114:117], v[154:157], v[178:181], v[114:117]
	v_mfma_f32_16x16x32_bf16 v[106:109], v[146:149], v[186:189], v[106:109]
	v_mfma_f32_16x16x32_bf16 v[98:101], v[154:157], v[186:189], v[98:101]
	v_mfma_f32_16x16x32_bf16 v[90:93], v[146:149], v[194:197], v[90:93]
	v_mfma_f32_16x16x32_bf16 v[82:85], v[154:157], v[194:197], v[82:85]
	s_waitcnt lgkmcnt(0)
	v_mfma_f32_16x16x32_bf16 v[74:77], v[146:149], v[202:205], v[74:77]
	v_mfma_f32_16x16x32_bf16 v[66:69], v[154:157], v[202:205], v[66:69]
	v_mfma_f32_16x16x32_bf16 v[126:129], v[158:161], v[174:177], v[126:129]
	v_mfma_f32_16x16x32_bf16 v[118:121], v[166:169], v[174:177], v[118:121]
	v_mfma_f32_16x16x32_bf16 v[110:113], v[158:161], v[182:185], v[110:113]
	v_mfma_f32_16x16x32_bf16 v[102:105], v[166:169], v[182:185], v[102:105]
	v_mfma_f32_16x16x32_bf16 v[94:97], v[158:161], v[190:193], v[94:97]
	v_mfma_f32_16x16x32_bf16 v[86:89], v[166:169], v[190:193], v[86:89]
	v_mfma_f32_16x16x32_bf16 v[78:81], v[158:161], v[198:201], v[78:81]
	v_mfma_f32_16x16x32_bf16 v[70:73], v[166:169], v[198:201], v[70:73]
	v_mfma_f32_16x16x32_bf16 v[126:129], v[162:165], v[178:181], v[126:129]
	v_mfma_f32_16x16x32_bf16 v[118:121], v[170:173], v[178:181], v[118:121]
	v_mfma_f32_16x16x32_bf16 v[110:113], v[162:165], v[186:189], v[110:113]
	v_mfma_f32_16x16x32_bf16 v[102:105], v[170:173], v[186:189], v[102:105]
	v_mfma_f32_16x16x32_bf16 v[94:97], v[162:165], v[194:197], v[94:97]
	v_mfma_f32_16x16x32_bf16 v[86:89], v[170:173], v[194:197], v[86:89]
	v_mfma_f32_16x16x32_bf16 v[78:81], v[162:165], v[202:205], v[78:81]
	v_mfma_f32_16x16x32_bf16 v[70:73], v[170:173], v[202:205], v[70:73]
	s_barrier
	s_add_u32 s2, s50, 0x80
	s_addc_u32 s3, s51, 0
	ds_read_b128 v[174:177], v140 offset:49152
	ds_read_b128 v[178:181], v140 offset:50176
	ds_read_b128 v[182:185], v140 offset:51200
	ds_read_b128 v[186:189], v140 offset:52224
	ds_read_b128 v[190:193], v140 offset:53248
	ds_read_b128 v[194:197], v140 offset:54272
	ds_read_b128 v[198:201], v140 offset:55296
	ds_read_b128 v[202:205], v140 offset:56320
	s_mov_b32 m0, s61
	s_nop 0
	global_load_lds_dwordx4 v136, s[2:3]
	s_add_u32 s2, s50, 0x20080
	s_addc_u32 s3, s51, 0
	s_mov_b32 m0, s62
	s_nop 0
	global_load_lds_dwordx4 v136, s[2:3]
	s_add_u32 s2, s50, 0x40080
	s_addc_u32 s3, s51, 0
	s_mov_b32 m0, s65
	s_nop 0
	global_load_lds_dwordx4 v136, s[2:3]
	s_add_u32 s2, s50, 0x60080
	s_addc_u32 s3, s51, 0
	s_mov_b32 m0, s66
	s_nop 0
	global_load_lds_dwordx4 v136, s[2:3]
	s_mov_b32 m0, s63
	s_nop 0
	global_load_lds_dwordx4 v1, s[44:45]
	s_add_u32 s2, s34, 0x20080
	s_addc_u32 s3, s35, 0
	s_mov_b32 m0, s64
	s_nop 0
	global_load_lds_dwordx4 v1, s[2:3]
	s_waitcnt vmcnt(8)
	s_waitcnt lgkmcnt(0)
	s_barrier
	s_waitcnt lgkmcnt(7)
	v_mfma_f32_16x16x32_bf16 v[58:61], v[142:145], v[174:177], v[58:61]
	v_mfma_f32_16x16x32_bf16 v[50:53], v[150:153], v[174:177], v[50:53]
	s_waitcnt lgkmcnt(5)
	v_mfma_f32_16x16x32_bf16 v[42:45], v[142:145], v[182:185], v[42:45]
	v_mfma_f32_16x16x32_bf16 v[34:37], v[150:153], v[182:185], v[34:37]
	s_waitcnt lgkmcnt(3)
	v_mfma_f32_16x16x32_bf16 v[26:29], v[142:145], v[190:193], v[26:29]
	v_mfma_f32_16x16x32_bf16 v[18:21], v[150:153], v[190:193], v[18:21]
	s_waitcnt lgkmcnt(1)
	v_mfma_f32_16x16x32_bf16 v[10:13], v[142:145], v[198:201], v[10:13]
	v_mfma_f32_16x16x32_bf16 v[6:9], v[150:153], v[198:201], v[6:9]
	v_mfma_f32_16x16x32_bf16 v[58:61], v[146:149], v[178:181], v[58:61]
	v_mfma_f32_16x16x32_bf16 v[50:53], v[154:157], v[178:181], v[50:53]
	v_mfma_f32_16x16x32_bf16 v[42:45], v[146:149], v[186:189], v[42:45]
	v_mfma_f32_16x16x32_bf16 v[34:37], v[154:157], v[186:189], v[34:37]
	v_mfma_f32_16x16x32_bf16 v[26:29], v[146:149], v[194:197], v[26:29]
	v_mfma_f32_16x16x32_bf16 v[18:21], v[154:157], v[194:197], v[18:21]
	s_waitcnt lgkmcnt(0)
	v_mfma_f32_16x16x32_bf16 v[10:13], v[146:149], v[202:205], v[10:13]
	v_mfma_f32_16x16x32_bf16 v[6:9], v[154:157], v[202:205], v[6:9]
	v_mfma_f32_16x16x32_bf16 v[62:65], v[158:161], v[174:177], v[62:65]
	v_mfma_f32_16x16x32_bf16 v[54:57], v[166:169], v[174:177], v[54:57]
	v_mfma_f32_16x16x32_bf16 v[46:49], v[158:161], v[182:185], v[46:49]
	v_mfma_f32_16x16x32_bf16 v[38:41], v[166:169], v[182:185], v[38:41]
	v_mfma_f32_16x16x32_bf16 v[30:33], v[158:161], v[190:193], v[30:33]
	v_mfma_f32_16x16x32_bf16 v[22:25], v[166:169], v[190:193], v[22:25]
	v_mfma_f32_16x16x32_bf16 v[14:17], v[158:161], v[198:201], v[14:17]
	v_mfma_f32_16x16x32_bf16 v[2:5], v[166:169], v[198:201], v[2:5]
	v_mfma_f32_16x16x32_bf16 v[62:65], v[162:165], v[178:181], v[62:65]
	v_mfma_f32_16x16x32_bf16 v[54:57], v[170:173], v[178:181], v[54:57]
	v_mfma_f32_16x16x32_bf16 v[46:49], v[162:165], v[186:189], v[46:49]
	v_mfma_f32_16x16x32_bf16 v[38:41], v[170:173], v[186:189], v[38:41]
	v_mfma_f32_16x16x32_bf16 v[30:33], v[162:165], v[194:197], v[30:33]
	v_mfma_f32_16x16x32_bf16 v[22:25], v[170:173], v[194:197], v[22:25]
	v_mfma_f32_16x16x32_bf16 v[14:17], v[162:165], v[202:205], v[14:17]
	v_mfma_f32_16x16x32_bf16 v[2:5], v[170:173], v[202:205], v[2:5]
	s_barrier
	s_add_i32 s88, s88, 2
	s_add_u32 s86, s86, 0x100
	s_addc_u32 s87, s87, 0
	s_cmp_gt_u32 s88, 13
	s_mov_b64 s[42:43], s[0:1]

.LBB0_987:
	s_ashr_i32 s25, s24, 31
	s_lshl_b64 s[12:13], s[24:25], 19
	s_add_u32 s26, s16, s12
	s_addc_u32 s27, s17, s13
	s_and_b64 s[12:13], s[2:3], exec
	s_cselect_b32 s14, s27, s41
	s_cselect_b32 s15, s26, s40
	s_ashr_i32 s11, s10, 31
	s_lshl_b64 s[12:13], s[10:11], 19
	s_add_u32 s36, s50, s12
	s_addc_u32 s37, s51, s13
	s_and_b64 s[12:13], s[2:3], exec
	s_cselect_b32 s11, s37, s1
	s_cselect_b32 s25, s36, s0
	s_add_u32 s86, s0, 0x100
	s_addc_u32 s87, s1, 0
	s_mov_b32 s88, -2
	v_add_u32_e32 v130, 0x10000, v150
	ds_read_b128 v[152:155], v130
	ds_read_b128 v[156:159], v130 offset:1024
	ds_read_b128 v[160:163], v130 offset:2048
	ds_read_b128 v[164:167], v130 offset:3072
	v_add_u32_e32 v130, 0x14000, v150
	ds_read_b128 v[168:171], v130
	ds_read_b128 v[172:175], v130 offset:1024
	ds_read_b128 v[176:179], v130 offset:2048
	ds_read_b128 v[180:183], v130 offset:3072
	s_add_u32 s0, s40, 0x100
	s_addc_u32 s1, s41, 0
	s_cmp_eq_u32 s88, 12
	s_cselect_b32 s34, s15, s0
	s_cselect_b32 s35, s14, s1
	s_cselect_b32 s44, s25, s86
	s_cselect_b32 s45, s11, s87
	s_add_u32 s42, s34, 0x80
	s_addc_u32 s43, s35, 0
	ds_read_b128 v[184:187], v151
	ds_read_b128 v[188:191], v151 offset:1024
	ds_read_b128 v[192:195], v151 offset:2048
	ds_read_b128 v[196:199], v151 offset:3072
	ds_read_b128 v[200:203], v151 offset:4096
	ds_read_b128 v[204:207], v151 offset:5120
	ds_read_b128 v[208:211], v151 offset:6144
	ds_read_b128 v[212:215], v151 offset:7168
	s_add_u32 s12, s40, 0x40080
	s_addc_u32 s13, s41, 0
	s_mov_b32 m0, s82
	s_nop 0
	global_load_lds_dwordx4 v1, s[12:13]
	s_add_u32 s12, s40, 0x60080
	s_addc_u32 s13, s41, 0
	s_add_i32 s40, s54, 0xe000
	s_mov_b32 m0, s40
	s_nop 0
	global_load_lds_dwordx4 v1, s[12:13]
	s_waitcnt vmcnt(8)
	s_waitcnt lgkmcnt(0)
	s_barrier
	s_waitcnt lgkmcnt(7)
	v_mfma_f32_16x16x32_bf16 v[122:125], v[152:155], v[184:187], 0
	v_mfma_f32_16x16x32_bf16 v[114:117], v[160:163], v[184:187], 0
	s_waitcnt lgkmcnt(5)
	v_mfma_f32_16x16x32_bf16 v[106:109], v[152:155], v[192:195], 0
	v_mfma_f32_16x16x32_bf16 v[98:101], v[160:163], v[192:195], 0
	s_waitcnt lgkmcnt(3)
	v_mfma_f32_16x16x32_bf16 v[90:93], v[152:155], v[200:203], 0
	v_mfma_f32_16x16x32_bf16 v[82:85], v[160:163], v[200:203], 0
	s_waitcnt lgkmcnt(1)
	v_mfma_f32_16x16x32_bf16 v[74:77], v[152:155], v[208:211], 0
	v_mfma_f32_16x16x32_bf16 v[66:69], v[160:163], v[208:211], 0
	v_mfma_f32_16x16x32_bf16 v[122:125], v[156:159], v[188:191], v[122:125]
	v_mfma_f32_16x16x32_bf16 v[114:117], v[164:167], v[188:191], v[114:117]
	v_mfma_f32_16x16x32_bf16 v[106:109], v[156:159], v[196:199], v[106:109]
	v_mfma_f32_16x16x32_bf16 v[98:101], v[164:167], v[196:199], v[98:101]
	v_mfma_f32_16x16x32_bf16 v[90:93], v[156:159], v[204:207], v[90:93]
	v_mfma_f32_16x16x32_bf16 v[82:85], v[164:167], v[204:207], v[82:85]
	s_waitcnt lgkmcnt(0)
	v_mfma_f32_16x16x32_bf16 v[74:77], v[156:159], v[212:215], v[74:77]
	v_mfma_f32_16x16x32_bf16 v[66:69], v[164:167], v[212:215], v[66:69]
	v_mfma_f32_16x16x32_bf16 v[126:129], v[168:171], v[184:187], 0
	v_mfma_f32_16x16x32_bf16 v[118:121], v[176:179], v[184:187], 0
	v_mfma_f32_16x16x32_bf16 v[110:113], v[168:171], v[192:195], 0
	v_mfma_f32_16x16x32_bf16 v[102:105], v[176:179], v[192:195], 0
	v_mfma_f32_16x16x32_bf16 v[94:97], v[168:171], v[200:203], 0
	v_mfma_f32_16x16x32_bf16 v[86:89], v[176:179], v[200:203], 0
	v_mfma_f32_16x16x32_bf16 v[78:81], v[168:171], v[208:211], 0
	v_mfma_f32_16x16x32_bf16 v[70:73], v[176:179], v[208:211], 0
	v_mfma_f32_16x16x32_bf16 v[126:129], v[172:175], v[188:191], v[126:129]
	v_mfma_f32_16x16x32_bf16 v[118:121], v[180:183], v[188:191], v[118:121]
	v_mfma_f32_16x16x32_bf16 v[110:113], v[172:175], v[196:199], v[110:113]
	v_mfma_f32_16x16x32_bf16 v[102:105], v[180:183], v[196:199], v[102:105]
	v_mfma_f32_16x16x32_bf16 v[94:97], v[172:175], v[204:207], v[94:97]
	v_mfma_f32_16x16x32_bf16 v[86:89], v[180:183], v[204:207], v[86:89]
	v_mfma_f32_16x16x32_bf16 v[78:81], v[172:175], v[212:215], v[78:81]
	v_mfma_f32_16x16x32_bf16 v[70:73], v[180:183], v[212:215], v[70:73]
	s_barrier
	ds_read_b128 v[184:187], v151 offset:16384
	ds_read_b128 v[188:191], v151 offset:17408
	ds_read_b128 v[192:195], v151 offset:18432
	ds_read_b128 v[196:199], v151 offset:19456
	ds_read_b128 v[200:203], v151 offset:20480
	ds_read_b128 v[204:207], v151 offset:21504
	ds_read_b128 v[208:211], v151 offset:22528
	ds_read_b128 v[212:215], v151 offset:23552
	s_mov_b32 m0, s56
	s_nop 0
	global_load_lds_dwordx4 v144, s[44:45]
	s_add_u32 s12, s44, 0x20000
	s_addc_u32 s13, s45, 0
	s_mov_b32 m0, s57
	s_nop 0
	global_load_lds_dwordx4 v144, s[12:13]
	s_add_u32 s12, s44, 0x40000
	s_addc_u32 s13, s45, 0
	s_mov_b32 m0, s58
	s_nop 0
	global_load_lds_dwordx4 v144, s[12:13]
	s_add_u32 s12, s44, 0x60000
	s_addc_u32 s13, s45, 0
	s_mov_b32 m0, s59
	s_nop 0
	global_load_lds_dwordx4 v144, s[12:13]
	s_mov_b32 m0, s54
	s_nop 0
	global_load_lds_dwordx4 v1, s[34:35]
	s_add_u32 s12, s34, 0x20000
	s_addc_u32 s13, s35, 0
	s_mov_b32 m0, s60
	s_nop 0
	global_load_lds_dwordx4 v1, s[12:13]
	s_waitcnt vmcnt(8)
	s_waitcnt lgkmcnt(0)
	s_barrier
	s_waitcnt lgkmcnt(7)
	v_mfma_f32_16x16x32_bf16 v[58:61], v[152:155], v[184:187], 0
	v_mfma_f32_16x16x32_bf16 v[50:53], v[160:163], v[184:187], 0
	s_waitcnt lgkmcnt(5)
	v_mfma_f32_16x16x32_bf16 v[42:45], v[152:155], v[192:195], 0
	v_mfma_f32_16x16x32_bf16 v[34:37], v[160:163], v[192:195], 0
	s_waitcnt lgkmcnt(3)
	v_mfma_f32_16x16x32_bf16 v[26:29], v[152:155], v[200:203], 0
	v_mfma_f32_16x16x32_bf16 v[18:21], v[160:163], v[200:203], 0
	s_waitcnt lgkmcnt(1)
	v_mfma_f32_16x16x32_bf16 v[10:13], v[152:155], v[208:211], 0
	v_mfma_f32_16x16x32_bf16 v[6:9], v[160:163], v[208:211], 0
	v_mfma_f32_16x16x32_bf16 v[58:61], v[156:159], v[188:191], v[58:61]
	v_mfma_f32_16x16x32_bf16 v[50:53], v[164:167], v[188:191], v[50:53]
	v_mfma_f32_16x16x32_bf16 v[42:45], v[156:159], v[196:199], v[42:45]
	v_mfma_f32_16x16x32_bf16 v[34:37], v[164:167], v[196:199], v[34:37]
	v_mfma_f32_16x16x32_bf16 v[26:29], v[156:159], v[204:207], v[26:29]
	v_mfma_f32_16x16x32_bf16 v[18:21], v[164:167], v[204:207], v[18:21]
	s_waitcnt lgkmcnt(0)
	v_mfma_f32_16x16x32_bf16 v[10:13], v[156:159], v[212:215], v[10:13]
	v_mfma_f32_16x16x32_bf16 v[6:9], v[164:167], v[212:215], v[6:9]
	v_mfma_f32_16x16x32_bf16 v[62:65], v[168:171], v[184:187], 0
	v_mfma_f32_16x16x32_bf16 v[54:57], v[176:179], v[184:187], 0
	v_mfma_f32_16x16x32_bf16 v[46:49], v[168:171], v[192:195], 0
	v_mfma_f32_16x16x32_bf16 v[38:41], v[176:179], v[192:195], 0
	v_mfma_f32_16x16x32_bf16 v[30:33], v[168:171], v[200:203], 0
	v_mfma_f32_16x16x32_bf16 v[22:25], v[176:179], v[200:203], 0
	v_mfma_f32_16x16x32_bf16 v[14:17], v[168:171], v[208:211], 0
	v_mfma_f32_16x16x32_bf16 v[2:5], v[176:179], v[208:211], 0
	v_mfma_f32_16x16x32_bf16 v[62:65], v[172:175], v[188:191], v[62:65]
	v_mfma_f32_16x16x32_bf16 v[54:57], v[180:183], v[188:191], v[54:57]
	v_mfma_f32_16x16x32_bf16 v[46:49], v[172:175], v[196:199], v[46:49]
	v_mfma_f32_16x16x32_bf16 v[38:41], v[180:183], v[196:199], v[38:41]
	v_mfma_f32_16x16x32_bf16 v[30:33], v[172:175], v[204:207], v[30:33]
	v_mfma_f32_16x16x32_bf16 v[22:25], v[180:183], v[204:207], v[22:25]
	v_mfma_f32_16x16x32_bf16 v[14:17], v[172:175], v[212:215], v[14:17]
	v_mfma_f32_16x16x32_bf16 v[2:5], v[180:183], v[212:215], v[2:5]
	s_barrier
	v_add_u32_e32 v130, 0x18000, v150
	ds_read_b128 v[152:155], v130
	ds_read_b128 v[156:159], v130 offset:1024
	ds_read_b128 v[160:163], v130 offset:2048
	ds_read_b128 v[164:167], v130 offset:3072
	v_add_u32_e32 v130, 0x1c000, v150
	ds_read_b128 v[168:171], v130
	ds_read_b128 v[172:175], v130 offset:1024
	ds_read_b128 v[176:179], v130 offset:2048
	ds_read_b128 v[180:183], v130 offset:3072
	ds_read_b128 v[184:187], v151 offset:32768
	ds_read_b128 v[188:191], v151 offset:33792
	ds_read_b128 v[192:195], v151 offset:34816
	ds_read_b128 v[196:199], v151 offset:35840
	ds_read_b128 v[200:203], v151 offset:36864
	ds_read_b128 v[204:207], v151 offset:37888
	ds_read_b128 v[208:211], v151 offset:38912
	ds_read_b128 v[212:215], v151 offset:39936
	s_add_u32 s12, s34, 0x40000
	s_addc_u32 s13, s35, 0
	s_mov_b32 m0, s61
	s_nop 0
	global_load_lds_dwordx4 v1, s[12:13]
	s_add_u32 s12, s34, 0x60000
	s_addc_u32 s13, s35, 0
	s_mov_b32 m0, s62
	s_nop 0
	global_load_lds_dwordx4 v1, s[12:13]
	s_waitcnt vmcnt(8)
	s_waitcnt lgkmcnt(0)
	s_barrier
	s_waitcnt lgkmcnt(7)
	v_mfma_f32_16x16x32_bf16 v[122:125], v[152:155], v[184:187], v[122:125]
	v_mfma_f32_16x16x32_bf16 v[114:117], v[160:163], v[184:187], v[114:117]
	s_waitcnt lgkmcnt(5)
	v_mfma_f32_16x16x32_bf16 v[106:109], v[152:155], v[192:195], v[106:109]
	v_mfma_f32_16x16x32_bf16 v[98:101], v[160:163], v[192:195], v[98:101]
	s_waitcnt lgkmcnt(3)
	v_mfma_f32_16x16x32_bf16 v[90:93], v[152:155], v[200:203], v[90:93]
	v_mfma_f32_16x16x32_bf16 v[82:85], v[160:163], v[200:203], v[82:85]
	s_waitcnt lgkmcnt(1)
	v_mfma_f32_16x16x32_bf16 v[74:77], v[152:155], v[208:211], v[74:77]
	v_mfma_f32_16x16x32_bf16 v[66:69], v[160:163], v[208:211], v[66:69]
	v_mfma_f32_16x16x32_bf16 v[122:125], v[156:159], v[188:191], v[122:125]
	v_mfma_f32_16x16x32_bf16 v[114:117], v[164:167], v[188:191], v[114:117]
	v_mfma_f32_16x16x32_bf16 v[106:109], v[156:159], v[196:199], v[106:109]
	v_mfma_f32_16x16x32_bf16 v[98:101], v[164:167], v[196:199], v[98:101]
	v_mfma_f32_16x16x32_bf16 v[90:93], v[156:159], v[204:207], v[90:93]
	v_mfma_f32_16x16x32_bf16 v[82:85], v[164:167], v[204:207], v[82:85]
	s_waitcnt lgkmcnt(0)
	v_mfma_f32_16x16x32_bf16 v[74:77], v[156:159], v[212:215], v[74:77]
	v_mfma_f32_16x16x32_bf16 v[66:69], v[164:167], v[212:215], v[66:69]
	v_mfma_f32_16x16x32_bf16 v[126:129], v[168:171], v[184:187], v[126:129]
	v_mfma_f32_16x16x32_bf16 v[118:121], v[176:179], v[184:187], v[118:121]
	v_mfma_f32_16x16x32_bf16 v[110:113], v[168:171], v[192:195], v[110:113]
	v_mfma_f32_16x16x32_bf16 v[102:105], v[176:179], v[192:195], v[102:105]
	v_mfma_f32_16x16x32_bf16 v[94:97], v[168:171], v[200:203], v[94:97]
	v_mfma_f32_16x16x32_bf16 v[86:89], v[176:179], v[200:203], v[86:89]
	v_mfma_f32_16x16x32_bf16 v[78:81], v[168:171], v[208:211], v[78:81]
	v_mfma_f32_16x16x32_bf16 v[70:73], v[176:179], v[208:211], v[70:73]
	v_mfma_f32_16x16x32_bf16 v[126:129], v[172:175], v[188:191], v[126:129]
	v_mfma_f32_16x16x32_bf16 v[118:121], v[180:183], v[188:191], v[118:121]
	v_mfma_f32_16x16x32_bf16 v[110:113], v[172:175], v[196:199], v[110:113]
	v_mfma_f32_16x16x32_bf16 v[102:105], v[180:183], v[196:199], v[102:105]
	v_mfma_f32_16x16x32_bf16 v[94:97], v[172:175], v[204:207], v[94:97]
	v_mfma_f32_16x16x32_bf16 v[86:89], v[180:183], v[204:207], v[86:89]
	v_mfma_f32_16x16x32_bf16 v[78:81], v[172:175], v[212:215], v[78:81]
	v_mfma_f32_16x16x32_bf16 v[70:73], v[180:183], v[212:215], v[70:73]
	s_barrier
	s_add_u32 s12, s44, 0x80
	s_addc_u32 s13, s45, 0
	ds_read_b128 v[184:187], v151 offset:49152
	ds_read_b128 v[188:191], v151 offset:50176
	ds_read_b128 v[192:195], v151 offset:51200
	ds_read_b128 v[196:199], v151 offset:52224
	ds_read_b128 v[200:203], v151 offset:53248
	ds_read_b128 v[204:207], v151 offset:54272
	ds_read_b128 v[208:211], v151 offset:55296
	ds_read_b128 v[212:215], v151 offset:56320
	s_mov_b32 m0, s63
	s_nop 0
	global_load_lds_dwordx4 v144, s[12:13]
	s_add_u32 s12, s44, 0x20080
	s_addc_u32 s13, s45, 0
	s_mov_b32 m0, s64
	s_nop 0
	global_load_lds_dwordx4 v144, s[12:13]
	s_add_u32 s12, s44, 0x40080
	s_addc_u32 s13, s45, 0
	s_mov_b32 m0, s67
	s_nop 0
	global_load_lds_dwordx4 v144, s[12:13]
	s_add_u32 s12, s44, 0x60080
	s_addc_u32 s13, s45, 0
	s_mov_b32 m0, s73
	s_nop 0
	global_load_lds_dwordx4 v144, s[12:13]
	s_mov_b32 m0, s65
	s_nop 0
	global_load_lds_dwordx4 v1, s[42:43]
	s_add_u32 s12, s34, 0x20080
	s_addc_u32 s13, s35, 0
	s_mov_b32 m0, s66
	s_nop 0
	global_load_lds_dwordx4 v1, s[12:13]
	s_waitcnt vmcnt(8)
	s_waitcnt lgkmcnt(0)
	s_barrier
	s_waitcnt lgkmcnt(7)
	v_mfma_f32_16x16x32_bf16 v[58:61], v[152:155], v[184:187], v[58:61]
	v_mfma_f32_16x16x32_bf16 v[50:53], v[160:163], v[184:187], v[50:53]
	s_waitcnt lgkmcnt(5)
	v_mfma_f32_16x16x32_bf16 v[42:45], v[152:155], v[192:195], v[42:45]
	v_mfma_f32_16x16x32_bf16 v[34:37], v[160:163], v[192:195], v[34:37]
	s_waitcnt lgkmcnt(3)
	v_mfma_f32_16x16x32_bf16 v[26:29], v[152:155], v[200:203], v[26:29]
	v_mfma_f32_16x16x32_bf16 v[18:21], v[160:163], v[200:203], v[18:21]
	s_waitcnt lgkmcnt(1)
	v_mfma_f32_16x16x32_bf16 v[10:13], v[152:155], v[208:211], v[10:13]
	v_mfma_f32_16x16x32_bf16 v[6:9], v[160:163], v[208:211], v[6:9]
	v_mfma_f32_16x16x32_bf16 v[58:61], v[156:159], v[188:191], v[58:61]
	v_mfma_f32_16x16x32_bf16 v[50:53], v[164:167], v[188:191], v[50:53]
	v_mfma_f32_16x16x32_bf16 v[42:45], v[156:159], v[196:199], v[42:45]
	v_mfma_f32_16x16x32_bf16 v[34:37], v[164:167], v[196:199], v[34:37]
	v_mfma_f32_16x16x32_bf16 v[26:29], v[156:159], v[204:207], v[26:29]
	v_mfma_f32_16x16x32_bf16 v[18:21], v[164:167], v[204:207], v[18:21]
	s_waitcnt lgkmcnt(0)
	v_mfma_f32_16x16x32_bf16 v[10:13], v[156:159], v[212:215], v[10:13]
	v_mfma_f32_16x16x32_bf16 v[6:9], v[164:167], v[212:215], v[6:9]
	v_mfma_f32_16x16x32_bf16 v[62:65], v[168:171], v[184:187], v[62:65]
	v_mfma_f32_16x16x32_bf16 v[54:57], v[176:179], v[184:187], v[54:57]
	v_mfma_f32_16x16x32_bf16 v[46:49], v[168:171], v[192:195], v[46:49]
	v_mfma_f32_16x16x32_bf16 v[38:41], v[176:179], v[192:195], v[38:41]
	v_mfma_f32_16x16x32_bf16 v[30:33], v[168:171], v[200:203], v[30:33]
	v_mfma_f32_16x16x32_bf16 v[22:25], v[176:179], v[200:203], v[22:25]
	v_mfma_f32_16x16x32_bf16 v[14:17], v[168:171], v[208:211], v[14:17]
	v_mfma_f32_16x16x32_bf16 v[2:5], v[176:179], v[208:211], v[2:5]
	v_mfma_f32_16x16x32_bf16 v[62:65], v[172:175], v[188:191], v[62:65]
	v_mfma_f32_16x16x32_bf16 v[54:57], v[180:183], v[188:191], v[54:57]
	v_mfma_f32_16x16x32_bf16 v[46:49], v[172:175], v[196:199], v[46:49]
	v_mfma_f32_16x16x32_bf16 v[38:41], v[180:183], v[196:199], v[38:41]
	v_mfma_f32_16x16x32_bf16 v[30:33], v[172:175], v[204:207], v[30:33]
	v_mfma_f32_16x16x32_bf16 v[22:25], v[180:183], v[204:207], v[22:25]
	v_mfma_f32_16x16x32_bf16 v[14:17], v[172:175], v[212:215], v[14:17]
	v_mfma_f32_16x16x32_bf16 v[2:5], v[180:183], v[212:215], v[2:5]
	s_barrier
	s_add_i32 s88, s88, 2
	s_add_u32 s86, s86, 0x100
	s_addc_u32 s87, s87, 0
	s_cmp_gt_u32 s88, 13
	s_mov_b64 s[40:41], s[0:1]

.LBB0_1316:
	v_and_b32_e32 v3, 48, v2
	v_lshlrev_b32_e32 v4, 6, v2
	v_lshlrev_b32_e32 v2, 2, v2
	s_and_b32 s45, s15, 3
	s_lshl_b32 s12, s14, 13
	v_and_or_b32 v3, v4, s51, v3
	v_and_b32_e32 v2, 32, v2
	s_lshl_b32 s78, s14, 6
	v_bitop3_b32 v4, v3, s12, v2 bitop3:0xde
	s_lshl_b32 s12, s45, 12
	v_bitop3_b32 v2, v3, s12, v2 bitop3:0xde
	s_add_u32 s12, s4, 0x80
	s_addc_u32 s13, s5, 0
	s_add_i32 s80, s66, 0x18000
	s_waitcnt vmcnt(2)
	s_barrier
	s_mov_b32 s34, m0
	s_mov_b32 m0, s80
	s_nop 4
	global_load_lds_dwordx4 v131, s[12:13]
	s_mov_b32 m0, s34
	s_add_u32 s12, s4, 0x20080
	s_addc_u32 s13, s5, 0
	s_add_i32 s81, s66, 0x1a000
	s_mov_b32 s34, m0
	s_mov_b32 m0, s81
	s_nop 4
	global_load_lds_dwordx4 v131, s[12:13]
	s_mov_b32 m0, s34
	s_add_u32 s12, s8, 0x80
	s_addc_u32 s13, s9, 0
	s_add_i32 s82, s66, 0x8000
	s_mov_b32 s34, m0
	s_mov_b32 m0, s82
	s_nop 4
	global_load_lds_dwordx4 v130, s[12:13]
	s_mov_b32 m0, s34
	s_add_u32 s12, s8, 0x20080
	s_addc_u32 s13, s9, 0
	s_add_i32 s84, s66, 0xa000
	s_mov_b32 s34, m0
	s_mov_b32 m0, s84
	s_nop 4
	global_load_lds_dwordx4 v130, s[12:13]
	s_mov_b32 m0, s34
	s_add_u32 s12, s4, 0x40080
	s_addc_u32 s13, s5, 0
	s_add_i32 s85, s66, 0x1c000
	s_mov_b32 s34, m0
	s_mov_b32 m0, s85
	s_nop 4
	global_load_lds_dwordx4 v131, s[12:13]
	s_mov_b32 m0, s34
	s_add_u32 s12, s4, 0x60080
	s_addc_u32 s13, s5, 0
	s_add_i32 s86, s66, 0x1e000
	s_mov_b32 s34, m0
	s_mov_b32 m0, s86
	s_nop 4
	global_load_lds_dwordx4 v131, s[12:13]
	s_mov_b32 m0, s34
	s_waitcnt vmcnt(6)
	s_add_i32 s87, s66, 0xc000
	s_add_u32 s88, s70, s0
	v_mov_b32_e32 v106, 0
	v_add_u32_e32 v2, 0, v2
	s_addc_u32 s89, s71, s1
	s_mov_b32 s90, -2
	s_mov_b64 s[46:47], 0x15c40080
	v_add_u32_e32 v132, 0x10000, v2
	v_add_u32_e32 v133, 0x14000, v2
	v_add_u32_e32 v134, 0, v4
	v_add_u32_e32 v135, 0x18000, v2
	v_add_u32_e32 v136, 0x1c000, v2
	s_barrier
	ds_read_b128 v[138:141], v132
	ds_read_b128 v[142:145], v132 offset:1024
	ds_read_b128 v[146:149], v132 offset:2048
	ds_read_b128 v[150:153], v132 offset:3072
	ds_read_b128 v[154:157], v133
	ds_read_b128 v[158:161], v133 offset:1024
	ds_read_b128 v[166:169], v133 offset:2048
	ds_read_b128 v[170:173], v133 offset:3072
	s_add_u32 s0, s46, 0xea3c0080
	s_addc_u32 s1, s47, -1
	s_cmp_lg_u32 s90, 12
	s_cselect_b32 s13, s0, 0
	s_cselect_b32 s12, s1, 0
	s_add_u32 s0, s8, s13
	s_addc_u32 s1, s9, s12
	s_add_u32 s34, s0, 0x80
	s_addc_u32 s35, s1, 0
	s_add_u32 s48, s4, s13
	s_addc_u32 s49, s5, s12
	ds_read_b128 v[174:177], v134
	ds_read_b128 v[184:187], v134 offset:1024
	ds_read_b128 v[188:191], v134 offset:2048
	ds_read_b128 v[192:195], v134 offset:3072
	ds_read_b128 v[196:199], v134 offset:4096
	ds_read_b128 v[200:203], v134 offset:5120
	ds_read_b128 v[204:207], v134 offset:6144
	ds_read_b128 v[208:211], v134 offset:7168
	s_add_u32 s12, s88, s46
	s_addc_u32 s13, s89, s47
	s_mov_b32 m0, s87
	s_nop 0
	global_load_lds_dwordx4 v130, s[12:13]
	s_add_u32 s12, s12, 0x20000
	s_addc_u32 s13, s13, 0
	s_add_i32 s91, s66, 0xe000
	s_mov_b32 m0, s91
	s_nop 0
	global_load_lds_dwordx4 v130, s[12:13]
	s_waitcnt vmcnt(8)
	s_waitcnt lgkmcnt(0)
	s_barrier
	s_waitcnt lgkmcnt(7)
	v_mfma_f32_16x16x32_bf16 v[2:5], v[138:141], v[174:177], 0
	v_mfma_f32_16x16x32_bf16 v[6:9], v[146:149], v[174:177], 0
	s_waitcnt lgkmcnt(5)
	v_mfma_f32_16x16x32_bf16 v[30:33], v[138:141], v[188:191], 0
	v_mfma_f32_16x16x32_bf16 v[34:37], v[146:149], v[188:191], 0
	s_waitcnt lgkmcnt(3)
	v_mfma_f32_16x16x32_bf16 v[54:57], v[138:141], v[196:199], 0
	v_mfma_f32_16x16x32_bf16 v[50:53], v[146:149], v[196:199], 0
	s_waitcnt lgkmcnt(1)
	v_mfma_f32_16x16x32_bf16 v[70:73], v[138:141], v[204:207], 0
	v_mfma_f32_16x16x32_bf16 v[66:69], v[146:149], v[204:207], 0
	v_mfma_f32_16x16x32_bf16 v[2:5], v[142:145], v[184:187], v[2:5]
	v_mfma_f32_16x16x32_bf16 v[6:9], v[150:153], v[184:187], v[6:9]
	v_mfma_f32_16x16x32_bf16 v[30:33], v[142:145], v[192:195], v[30:33]
	v_mfma_f32_16x16x32_bf16 v[34:37], v[150:153], v[192:195], v[34:37]
	v_mfma_f32_16x16x32_bf16 v[54:57], v[142:145], v[200:203], v[54:57]
	v_mfma_f32_16x16x32_bf16 v[50:53], v[150:153], v[200:203], v[50:53]
	s_waitcnt lgkmcnt(0)
	v_mfma_f32_16x16x32_bf16 v[70:73], v[142:145], v[208:211], v[70:73]
	v_mfma_f32_16x16x32_bf16 v[66:69], v[150:153], v[208:211], v[66:69]
	v_mfma_f32_16x16x32_bf16 v[10:13], v[154:157], v[174:177], 0
	v_mfma_f32_16x16x32_bf16 v[14:17], v[166:169], v[174:177], 0
	v_mfma_f32_16x16x32_bf16 v[22:25], v[154:157], v[188:191], 0
	v_mfma_f32_16x16x32_bf16 v[18:21], v[166:169], v[188:191], 0
	v_mfma_f32_16x16x32_bf16 v[38:41], v[154:157], v[196:199], 0
	v_mfma_f32_16x16x32_bf16 v[26:29], v[166:169], v[196:199], 0
	v_mfma_f32_16x16x32_bf16 v[46:49], v[154:157], v[204:207], 0
	v_mfma_f32_16x16x32_bf16 v[42:45], v[166:169], v[204:207], 0
	v_mfma_f32_16x16x32_bf16 v[10:13], v[158:161], v[184:187], v[10:13]
	v_mfma_f32_16x16x32_bf16 v[14:17], v[170:173], v[184:187], v[14:17]
	v_mfma_f32_16x16x32_bf16 v[22:25], v[158:161], v[192:195], v[22:25]
	v_mfma_f32_16x16x32_bf16 v[18:21], v[170:173], v[192:195], v[18:21]
	v_mfma_f32_16x16x32_bf16 v[38:41], v[158:161], v[200:203], v[38:41]
	v_mfma_f32_16x16x32_bf16 v[26:29], v[170:173], v[200:203], v[26:29]
	v_mfma_f32_16x16x32_bf16 v[46:49], v[158:161], v[208:211], v[46:49]
	v_mfma_f32_16x16x32_bf16 v[42:45], v[170:173], v[208:211], v[42:45]
	s_barrier
	ds_read_b128 v[174:177], v134 offset:16384
	ds_read_b128 v[184:187], v134 offset:17408
	ds_read_b128 v[188:191], v134 offset:18432
	ds_read_b128 v[192:195], v134 offset:19456
	ds_read_b128 v[196:199], v134 offset:20480
	ds_read_b128 v[200:203], v134 offset:21504
	ds_read_b128 v[204:207], v134 offset:22528
	ds_read_b128 v[208:211], v134 offset:23552
	s_mov_b32 m0, s67
	s_nop 0
	global_load_lds_dwordx4 v131, s[48:49]
	s_add_u32 s12, s48, 0x20000
	s_addc_u32 s13, s49, 0
	s_mov_b32 m0, s73
	s_nop 0
	global_load_lds_dwordx4 v131, s[12:13]
	s_add_u32 s12, s48, 0x40000
	s_addc_u32 s13, s49, 0
	s_mov_b32 m0, s74
	s_nop 0
	global_load_lds_dwordx4 v131, s[12:13]
	s_add_u32 s12, s48, 0x60000
	s_addc_u32 s13, s49, 0
	s_mov_b32 m0, s75
	s_nop 0
	global_load_lds_dwordx4 v131, s[12:13]
	s_mov_b32 m0, s66
	s_nop 0
	global_load_lds_dwordx4 v130, s[0:1]
	s_add_u32 s12, s0, 0x20000
	s_addc_u32 s13, s1, 0
	s_mov_b32 m0, s76
	s_nop 0
	global_load_lds_dwordx4 v130, s[12:13]
	s_waitcnt vmcnt(8)
	s_waitcnt lgkmcnt(0)
	s_barrier
	s_waitcnt lgkmcnt(7)
	v_mfma_f32_16x16x32_bf16 v[82:85], v[138:141], v[174:177], 0
	v_mfma_f32_16x16x32_bf16 v[74:77], v[146:149], v[174:177], 0
	s_waitcnt lgkmcnt(5)
	v_mfma_f32_16x16x32_bf16 v[98:101], v[138:141], v[188:191], 0
	v_mfma_f32_16x16x32_bf16 v[90:93], v[146:149], v[188:191], 0
	s_waitcnt lgkmcnt(3)
	v_mfma_f32_16x16x32_bf16 v[118:121], v[138:141], v[196:199], 0
	v_mfma_f32_16x16x32_bf16 v[114:117], v[146:149], v[196:199], 0
	s_waitcnt lgkmcnt(1)
	v_mfma_f32_16x16x32_bf16 v[126:129], v[138:141], v[204:207], 0
	v_mfma_f32_16x16x32_bf16 v[122:125], v[146:149], v[204:207], 0
	v_mfma_f32_16x16x32_bf16 v[82:85], v[142:145], v[184:187], v[82:85]
	v_mfma_f32_16x16x32_bf16 v[74:77], v[150:153], v[184:187], v[74:77]
	v_mfma_f32_16x16x32_bf16 v[98:101], v[142:145], v[192:195], v[98:101]
	v_mfma_f32_16x16x32_bf16 v[90:93], v[150:153], v[192:195], v[90:93]
	v_mfma_f32_16x16x32_bf16 v[118:121], v[142:145], v[200:203], v[118:121]
	v_mfma_f32_16x16x32_bf16 v[114:117], v[150:153], v[200:203], v[114:117]
	s_waitcnt lgkmcnt(0)
	v_mfma_f32_16x16x32_bf16 v[126:129], v[142:145], v[208:211], v[126:129]
	v_mfma_f32_16x16x32_bf16 v[122:125], v[150:153], v[208:211], v[122:125]
	v_mfma_f32_16x16x32_bf16 v[62:65], v[154:157], v[174:177], 0
	v_mfma_f32_16x16x32_bf16 v[58:61], v[166:169], v[174:177], 0
	v_mfma_f32_16x16x32_bf16 v[86:89], v[154:157], v[188:191], 0
	v_mfma_f32_16x16x32_bf16 v[78:81], v[166:169], v[188:191], 0
	v_mfma_f32_16x16x32_bf16 v[102:105], v[154:157], v[196:199], 0
	v_mfma_f32_16x16x32_bf16 v[94:97], v[166:169], v[196:199], 0
	v_mfma_f32_16x16x32_bf16 v[110:113], v[154:157], v[204:207], 0
	v_mfma_f32_16x16x32_bf16 v[106:109], v[166:169], v[204:207], 0
	v_mfma_f32_16x16x32_bf16 v[62:65], v[158:161], v[184:187], v[62:65]
	v_mfma_f32_16x16x32_bf16 v[58:61], v[170:173], v[184:187], v[58:61]
	v_mfma_f32_16x16x32_bf16 v[86:89], v[158:161], v[192:195], v[86:89]
	v_mfma_f32_16x16x32_bf16 v[78:81], v[170:173], v[192:195], v[78:81]
	v_mfma_f32_16x16x32_bf16 v[102:105], v[158:161], v[200:203], v[102:105]
	v_mfma_f32_16x16x32_bf16 v[94:97], v[170:173], v[200:203], v[94:97]
	v_mfma_f32_16x16x32_bf16 v[110:113], v[158:161], v[208:211], v[110:113]
	v_mfma_f32_16x16x32_bf16 v[106:109], v[170:173], v[208:211], v[106:109]
	s_barrier
	ds_read_b128 v[138:141], v135
	ds_read_b128 v[142:145], v135 offset:1024
	ds_read_b128 v[146:149], v135 offset:2048
	ds_read_b128 v[150:153], v135 offset:3072
	ds_read_b128 v[154:157], v136
	ds_read_b128 v[158:161], v136 offset:1024
	ds_read_b128 v[166:169], v136 offset:2048
	ds_read_b128 v[170:173], v136 offset:3072
	ds_read_b128 v[174:177], v134 offset:32768
	ds_read_b128 v[184:187], v134 offset:33792
	ds_read_b128 v[188:191], v134 offset:34816
	ds_read_b128 v[192:195], v134 offset:35840
	ds_read_b128 v[196:199], v134 offset:36864
	ds_read_b128 v[200:203], v134 offset:37888
	ds_read_b128 v[204:207], v134 offset:38912
	ds_read_b128 v[208:211], v134 offset:39936
	s_add_u32 s12, s0, 0x40000
	s_addc_u32 s13, s1, 0
	s_mov_b32 m0, s77
	s_nop 0
	global_load_lds_dwordx4 v130, s[12:13]
	s_add_u32 s12, s0, 0x60000
	s_addc_u32 s13, s1, 0
	s_mov_b32 m0, s79
	s_nop 0
	global_load_lds_dwordx4 v130, s[12:13]
	s_waitcnt vmcnt(8)
	s_waitcnt lgkmcnt(0)
	s_barrier
	s_waitcnt lgkmcnt(7)
	v_mfma_f32_16x16x32_bf16 v[2:5], v[138:141], v[174:177], v[2:5]
	v_mfma_f32_16x16x32_bf16 v[6:9], v[146:149], v[174:177], v[6:9]
	s_waitcnt lgkmcnt(5)
	v_mfma_f32_16x16x32_bf16 v[30:33], v[138:141], v[188:191], v[30:33]
	v_mfma_f32_16x16x32_bf16 v[34:37], v[146:149], v[188:191], v[34:37]
	s_waitcnt lgkmcnt(3)
	v_mfma_f32_16x16x32_bf16 v[54:57], v[138:141], v[196:199], v[54:57]
	v_mfma_f32_16x16x32_bf16 v[50:53], v[146:149], v[196:199], v[50:53]
	s_waitcnt lgkmcnt(1)
	v_mfma_f32_16x16x32_bf16 v[70:73], v[138:141], v[204:207], v[70:73]
	v_mfma_f32_16x16x32_bf16 v[66:69], v[146:149], v[204:207], v[66:69]
	v_mfma_f32_16x16x32_bf16 v[2:5], v[142:145], v[184:187], v[2:5]
	v_mfma_f32_16x16x32_bf16 v[6:9], v[150:153], v[184:187], v[6:9]
	v_mfma_f32_16x16x32_bf16 v[30:33], v[142:145], v[192:195], v[30:33]
	v_mfma_f32_16x16x32_bf16 v[34:37], v[150:153], v[192:195], v[34:37]
	v_mfma_f32_16x16x32_bf16 v[54:57], v[142:145], v[200:203], v[54:57]
	v_mfma_f32_16x16x32_bf16 v[50:53], v[150:153], v[200:203], v[50:53]
	s_waitcnt lgkmcnt(0)
	v_mfma_f32_16x16x32_bf16 v[70:73], v[142:145], v[208:211], v[70:73]
	v_mfma_f32_16x16x32_bf16 v[66:69], v[150:153], v[208:211], v[66:69]
	v_mfma_f32_16x16x32_bf16 v[10:13], v[154:157], v[174:177], v[10:13]
	v_mfma_f32_16x16x32_bf16 v[14:17], v[166:169], v[174:177], v[14:17]
	v_mfma_f32_16x16x32_bf16 v[22:25], v[154:157], v[188:191], v[22:25]
	v_mfma_f32_16x16x32_bf16 v[18:21], v[166:169], v[188:191], v[18:21]
	v_mfma_f32_16x16x32_bf16 v[38:41], v[154:157], v[196:199], v[38:41]
	v_mfma_f32_16x16x32_bf16 v[26:29], v[166:169], v[196:199], v[26:29]
	v_mfma_f32_16x16x32_bf16 v[46:49], v[154:157], v[204:207], v[46:49]
	v_mfma_f32_16x16x32_bf16 v[42:45], v[166:169], v[204:207], v[42:45]
	v_mfma_f32_16x16x32_bf16 v[10:13], v[158:161], v[184:187], v[10:13]
	v_mfma_f32_16x16x32_bf16 v[14:17], v[170:173], v[184:187], v[14:17]
	v_mfma_f32_16x16x32_bf16 v[22:25], v[158:161], v[192:195], v[22:25]
	v_mfma_f32_16x16x32_bf16 v[18:21], v[170:173], v[192:195], v[18:21]
	v_mfma_f32_16x16x32_bf16 v[38:41], v[158:161], v[200:203], v[38:41]
	v_mfma_f32_16x16x32_bf16 v[26:29], v[170:173], v[200:203], v[26:29]
	v_mfma_f32_16x16x32_bf16 v[46:49], v[158:161], v[208:211], v[46:49]
	v_mfma_f32_16x16x32_bf16 v[42:45], v[170:173], v[208:211], v[42:45]
	s_barrier
	s_add_u32 s12, s48, 0x80
	s_addc_u32 s13, s49, 0
	ds_read_b128 v[174:177], v134 offset:49152
	ds_read_b128 v[184:187], v134 offset:50176
	ds_read_b128 v[188:191], v134 offset:51200
	ds_read_b128 v[192:195], v134 offset:52224
	ds_read_b128 v[196:199], v134 offset:53248
	ds_read_b128 v[200:203], v134 offset:54272
	ds_read_b128 v[204:207], v134 offset:55296
	ds_read_b128 v[208:211], v134 offset:56320
	s_mov_b32 m0, s80
	s_nop 0
	global_load_lds_dwordx4 v131, s[12:13]
	s_add_u32 s12, s48, 0x20080
	s_addc_u32 s13, s49, 0
	s_mov_b32 m0, s81
	s_nop 0
	global_load_lds_dwordx4 v131, s[12:13]
	s_add_u32 s12, s48, 0x40080
	s_addc_u32 s13, s49, 0
	s_mov_b32 m0, s85
	s_nop 0
	global_load_lds_dwordx4 v131, s[12:13]
	s_add_u32 s12, s48, 0x60080
	s_addc_u32 s13, s49, 0
	s_mov_b32 m0, s86
	s_nop 0
	global_load_lds_dwordx4 v131, s[12:13]
	s_mov_b32 m0, s82
	s_nop 0
	global_load_lds_dwordx4 v130, s[34:35]
	s_add_u32 s0, s0, 0x20080
	s_addc_u32 s1, s1, 0
	s_mov_b32 m0, s84
	s_nop 0
	global_load_lds_dwordx4 v130, s[0:1]
	s_waitcnt vmcnt(8)
	s_waitcnt lgkmcnt(0)
	s_barrier
	s_waitcnt lgkmcnt(7)
	v_mfma_f32_16x16x32_bf16 v[82:85], v[138:141], v[174:177], v[82:85]
	v_mfma_f32_16x16x32_bf16 v[74:77], v[146:149], v[174:177], v[74:77]
	s_waitcnt lgkmcnt(5)
	v_mfma_f32_16x16x32_bf16 v[98:101], v[138:141], v[188:191], v[98:101]
	v_mfma_f32_16x16x32_bf16 v[90:93], v[146:149], v[188:191], v[90:93]
	s_waitcnt lgkmcnt(3)
	v_mfma_f32_16x16x32_bf16 v[118:121], v[138:141], v[196:199], v[118:121]
	v_mfma_f32_16x16x32_bf16 v[114:117], v[146:149], v[196:199], v[114:117]
	s_waitcnt lgkmcnt(1)
	v_mfma_f32_16x16x32_bf16 v[126:129], v[138:141], v[204:207], v[126:129]
	v_mfma_f32_16x16x32_bf16 v[122:125], v[146:149], v[204:207], v[122:125]
	v_mfma_f32_16x16x32_bf16 v[82:85], v[142:145], v[184:187], v[82:85]
	v_mfma_f32_16x16x32_bf16 v[74:77], v[150:153], v[184:187], v[74:77]
	v_mfma_f32_16x16x32_bf16 v[98:101], v[142:145], v[192:195], v[98:101]
	v_mfma_f32_16x16x32_bf16 v[90:93], v[150:153], v[192:195], v[90:93]
	v_mfma_f32_16x16x32_bf16 v[118:121], v[142:145], v[200:203], v[118:121]
	v_mfma_f32_16x16x32_bf16 v[114:117], v[150:153], v[200:203], v[114:117]
	s_waitcnt lgkmcnt(0)
	v_mfma_f32_16x16x32_bf16 v[126:129], v[142:145], v[208:211], v[126:129]
	v_mfma_f32_16x16x32_bf16 v[122:125], v[150:153], v[208:211], v[122:125]
	v_mfma_f32_16x16x32_bf16 v[62:65], v[154:157], v[174:177], v[62:65]
	v_mfma_f32_16x16x32_bf16 v[58:61], v[166:169], v[174:177], v[58:61]
	v_mfma_f32_16x16x32_bf16 v[86:89], v[154:157], v[188:191], v[86:89]
	v_mfma_f32_16x16x32_bf16 v[78:81], v[166:169], v[188:191], v[78:81]
	v_mfma_f32_16x16x32_bf16 v[102:105], v[154:157], v[196:199], v[102:105]
	v_mfma_f32_16x16x32_bf16 v[94:97], v[166:169], v[196:199], v[94:97]
	v_mfma_f32_16x16x32_bf16 v[110:113], v[154:157], v[204:207], v[110:113]
	v_mfma_f32_16x16x32_bf16 v[106:109], v[166:169], v[204:207], v[106:109]
	v_mfma_f32_16x16x32_bf16 v[62:65], v[158:161], v[184:187], v[62:65]
	v_mfma_f32_16x16x32_bf16 v[58:61], v[170:173], v[184:187], v[58:61]
	v_mfma_f32_16x16x32_bf16 v[86:89], v[158:161], v[192:195], v[86:89]
	v_mfma_f32_16x16x32_bf16 v[78:81], v[170:173], v[192:195], v[78:81]
	v_mfma_f32_16x16x32_bf16 v[102:105], v[158:161], v[200:203], v[102:105]
	v_mfma_f32_16x16x32_bf16 v[94:97], v[170:173], v[200:203], v[94:97]
	v_mfma_f32_16x16x32_bf16 v[110:113], v[158:161], v[208:211], v[110:113]
	v_mfma_f32_16x16x32_bf16 v[106:109], v[170:173], v[208:211], v[106:109]
	s_barrier
	s_add_i32 s90, s90, 2
	s_add_u32 s46, s46, 0x100
	s_addc_u32 s47, s47, 0
	s_cmp_lt_u32 s90, 14

.LBB0_1423:
	s_ashr_i32 s21, s20, 31
	s_lshl_b64 s[12:13], s[20:21], 19
	s_add_u32 s22, s16, s12
	s_addc_u32 s23, s17, s13
	s_and_b64 s[12:13], s[2:3], exec
	s_cselect_b32 s14, s23, s37
	s_cselect_b32 s15, s22, s36
	s_ashr_i32 s11, s10, 31
	s_lshl_b64 s[12:13], s[10:11], 19
	s_add_u32 s24, s42, s12
	s_addc_u32 s25, s43, s13
	s_and_b64 s[12:13], s[2:3], exec
	s_cselect_b32 s11, s25, s1
	s_cselect_b32 s21, s24, s0
	s_add_u32 s64, s0, 0x100
	s_addc_u32 s65, s1, 0
	s_mov_b32 s66, -2
	v_add_u32_e32 v134, 0x10000, v139
	ds_read_b128 v[142:145], v134
	ds_read_b128 v[146:149], v134 offset:1024
	ds_read_b128 v[150:153], v134 offset:2048
	ds_read_b128 v[154:157], v134 offset:3072
	v_add_u32_e32 v134, 0x14000, v139
	ds_read_b128 v[158:161], v134
	ds_read_b128 v[162:165], v134 offset:1024
	ds_read_b128 v[166:169], v134 offset:2048
	ds_read_b128 v[170:173], v134 offset:3072
	s_add_u32 s0, s36, 0x100
	s_addc_u32 s1, s37, 0
	s_cmp_eq_u32 s66, 12
	s_cselect_b32 s34, s15, s0
	s_cselect_b32 s35, s14, s1
	s_cselect_b32 s40, s21, s64
	s_cselect_b32 s41, s11, s65
	s_add_u32 s38, s34, 0x80
	s_addc_u32 s39, s35, 0
	ds_read_b128 v[174:177], v140
	ds_read_b128 v[178:181], v140 offset:1024
	ds_read_b128 v[182:185], v140 offset:2048
	ds_read_b128 v[186:189], v140 offset:3072
	ds_read_b128 v[190:193], v140 offset:4096
	ds_read_b128 v[194:197], v140 offset:5120
	ds_read_b128 v[198:201], v140 offset:6144
	ds_read_b128 v[202:205], v140 offset:7168
	s_add_u32 s12, s36, 0x40080
	s_addc_u32 s13, s37, 0
	s_mov_b32 m0, s59
	s_nop 0
	global_load_lds_dwordx4 v1, s[12:13]
	s_add_u32 s12, s36, 0x60080
	s_addc_u32 s13, s37, 0
	s_add_i32 s36, s27, 0xe000
	s_mov_b32 m0, s36
	s_nop 0
	global_load_lds_dwordx4 v1, s[12:13]
	s_waitcnt vmcnt(8)
	s_waitcnt lgkmcnt(0)
	s_barrier
	s_waitcnt lgkmcnt(7)
	v_mfma_f32_16x16x32_bf16 v[122:125], v[142:145], v[174:177], 0
	v_mfma_f32_16x16x32_bf16 v[114:117], v[150:153], v[174:177], 0
	s_waitcnt lgkmcnt(5)
	v_mfma_f32_16x16x32_bf16 v[106:109], v[142:145], v[182:185], 0
	v_mfma_f32_16x16x32_bf16 v[98:101], v[150:153], v[182:185], 0
	s_waitcnt lgkmcnt(3)
	v_mfma_f32_16x16x32_bf16 v[90:93], v[142:145], v[190:193], 0
	v_mfma_f32_16x16x32_bf16 v[82:85], v[150:153], v[190:193], 0
	s_waitcnt lgkmcnt(1)
	v_mfma_f32_16x16x32_bf16 v[74:77], v[142:145], v[198:201], 0
	v_mfma_f32_16x16x32_bf16 v[66:69], v[150:153], v[198:201], 0
	v_mfma_f32_16x16x32_bf16 v[122:125], v[146:149], v[178:181], v[122:125]
	v_mfma_f32_16x16x32_bf16 v[114:117], v[154:157], v[178:181], v[114:117]
	v_mfma_f32_16x16x32_bf16 v[106:109], v[146:149], v[186:189], v[106:109]
	v_mfma_f32_16x16x32_bf16 v[98:101], v[154:157], v[186:189], v[98:101]
	v_mfma_f32_16x16x32_bf16 v[90:93], v[146:149], v[194:197], v[90:93]
	v_mfma_f32_16x16x32_bf16 v[82:85], v[154:157], v[194:197], v[82:85]
	s_waitcnt lgkmcnt(0)
	v_mfma_f32_16x16x32_bf16 v[74:77], v[146:149], v[202:205], v[74:77]
	v_mfma_f32_16x16x32_bf16 v[66:69], v[154:157], v[202:205], v[66:69]
	v_mfma_f32_16x16x32_bf16 v[126:129], v[158:161], v[174:177], 0
	v_mfma_f32_16x16x32_bf16 v[118:121], v[166:169], v[174:177], 0
	v_mfma_f32_16x16x32_bf16 v[110:113], v[158:161], v[182:185], 0
	v_mfma_f32_16x16x32_bf16 v[102:105], v[166:169], v[182:185], 0
	v_mfma_f32_16x16x32_bf16 v[94:97], v[158:161], v[190:193], 0
	v_mfma_f32_16x16x32_bf16 v[86:89], v[166:169], v[190:193], 0
	v_mfma_f32_16x16x32_bf16 v[78:81], v[158:161], v[198:201], 0
	v_mfma_f32_16x16x32_bf16 v[70:73], v[166:169], v[198:201], 0
	v_mfma_f32_16x16x32_bf16 v[126:129], v[162:165], v[178:181], v[126:129]
	v_mfma_f32_16x16x32_bf16 v[118:121], v[170:173], v[178:181], v[118:121]
	v_mfma_f32_16x16x32_bf16 v[110:113], v[162:165], v[186:189], v[110:113]
	v_mfma_f32_16x16x32_bf16 v[102:105], v[170:173], v[186:189], v[102:105]
	v_mfma_f32_16x16x32_bf16 v[94:97], v[162:165], v[194:197], v[94:97]
	v_mfma_f32_16x16x32_bf16 v[86:89], v[170:173], v[194:197], v[86:89]
	v_mfma_f32_16x16x32_bf16 v[78:81], v[162:165], v[202:205], v[78:81]
	v_mfma_f32_16x16x32_bf16 v[70:73], v[170:173], v[202:205], v[70:73]
	s_barrier
	ds_read_b128 v[174:177], v140 offset:16384
	ds_read_b128 v[178:181], v140 offset:17408
	ds_read_b128 v[182:185], v140 offset:18432
	ds_read_b128 v[186:189], v140 offset:19456
	ds_read_b128 v[190:193], v140 offset:20480
	ds_read_b128 v[194:197], v140 offset:21504
	ds_read_b128 v[198:201], v140 offset:22528
	ds_read_b128 v[202:205], v140 offset:23552
	s_mov_b32 m0, s46
	s_nop 0
	global_load_lds_dwordx4 v136, s[40:41]
	s_add_u32 s12, s40, 0x20000
	s_addc_u32 s13, s41, 0
	s_mov_b32 m0, s47
	s_nop 0
	global_load_lds_dwordx4 v136, s[12:13]
	s_add_u32 s12, s40, 0x40000
	s_addc_u32 s13, s41, 0
	s_mov_b32 m0, s48
	s_nop 0
	global_load_lds_dwordx4 v136, s[12:13]
	s_add_u32 s12, s40, 0x60000
	s_addc_u32 s13, s41, 0
	s_mov_b32 m0, s49
	s_nop 0
	global_load_lds_dwordx4 v136, s[12:13]
	s_mov_b32 m0, s27
	s_nop 0
	global_load_lds_dwordx4 v1, s[34:35]
	s_add_u32 s12, s34, 0x20000
	s_addc_u32 s13, s35, 0
	s_mov_b32 m0, s50
	s_nop 0
	global_load_lds_dwordx4 v1, s[12:13]
	s_waitcnt vmcnt(8)
	s_waitcnt lgkmcnt(0)
	s_barrier
	s_waitcnt lgkmcnt(7)
	v_mfma_f32_16x16x32_bf16 v[58:61], v[142:145], v[174:177], 0
	v_mfma_f32_16x16x32_bf16 v[50:53], v[150:153], v[174:177], 0
	s_waitcnt lgkmcnt(5)
	v_mfma_f32_16x16x32_bf16 v[42:45], v[142:145], v[182:185], 0
	v_mfma_f32_16x16x32_bf16 v[34:37], v[150:153], v[182:185], 0
	s_waitcnt lgkmcnt(3)
	v_mfma_f32_16x16x32_bf16 v[26:29], v[142:145], v[190:193], 0
	v_mfma_f32_16x16x32_bf16 v[18:21], v[150:153], v[190:193], 0
	s_waitcnt lgkmcnt(1)
	v_mfma_f32_16x16x32_bf16 v[10:13], v[142:145], v[198:201], 0
	v_mfma_f32_16x16x32_bf16 v[6:9], v[150:153], v[198:201], 0
	v_mfma_f32_16x16x32_bf16 v[58:61], v[146:149], v[178:181], v[58:61]
	v_mfma_f32_16x16x32_bf16 v[50:53], v[154:157], v[178:181], v[50:53]
	v_mfma_f32_16x16x32_bf16 v[42:45], v[146:149], v[186:189], v[42:45]
	v_mfma_f32_16x16x32_bf16 v[34:37], v[154:157], v[186:189], v[34:37]
	v_mfma_f32_16x16x32_bf16 v[26:29], v[146:149], v[194:197], v[26:29]
	v_mfma_f32_16x16x32_bf16 v[18:21], v[154:157], v[194:197], v[18:21]
	s_waitcnt lgkmcnt(0)
	v_mfma_f32_16x16x32_bf16 v[10:13], v[146:149], v[202:205], v[10:13]
	v_mfma_f32_16x16x32_bf16 v[6:9], v[154:157], v[202:205], v[6:9]
	v_mfma_f32_16x16x32_bf16 v[62:65], v[158:161], v[174:177], 0
	v_mfma_f32_16x16x32_bf16 v[54:57], v[166:169], v[174:177], 0
	v_mfma_f32_16x16x32_bf16 v[46:49], v[158:161], v[182:185], 0
	v_mfma_f32_16x16x32_bf16 v[38:41], v[166:169], v[182:185], 0
	v_mfma_f32_16x16x32_bf16 v[30:33], v[158:161], v[190:193], 0
	v_mfma_f32_16x16x32_bf16 v[22:25], v[166:169], v[190:193], 0
	v_mfma_f32_16x16x32_bf16 v[14:17], v[158:161], v[198:201], 0
	v_mfma_f32_16x16x32_bf16 v[2:5], v[166:169], v[198:201], 0
	v_mfma_f32_16x16x32_bf16 v[62:65], v[162:165], v[178:181], v[62:65]
	v_mfma_f32_16x16x32_bf16 v[54:57], v[170:173], v[178:181], v[54:57]
	v_mfma_f32_16x16x32_bf16 v[46:49], v[162:165], v[186:189], v[46:49]
	v_mfma_f32_16x16x32_bf16 v[38:41], v[170:173], v[186:189], v[38:41]
	v_mfma_f32_16x16x32_bf16 v[30:33], v[162:165], v[194:197], v[30:33]
	v_mfma_f32_16x16x32_bf16 v[22:25], v[170:173], v[194:197], v[22:25]
	v_mfma_f32_16x16x32_bf16 v[14:17], v[162:165], v[202:205], v[14:17]
	v_mfma_f32_16x16x32_bf16 v[2:5], v[170:173], v[202:205], v[2:5]
	s_barrier
	v_add_u32_e32 v134, 0x18000, v139
	ds_read_b128 v[142:145], v134
	ds_read_b128 v[146:149], v134 offset:1024
	ds_read_b128 v[150:153], v134 offset:2048
	ds_read_b128 v[154:157], v134 offset:3072
	v_add_u32_e32 v134, 0x1c000, v139
	ds_read_b128 v[158:161], v134
	ds_read_b128 v[162:165], v134 offset:1024
	ds_read_b128 v[166:169], v134 offset:2048
	ds_read_b128 v[170:173], v134 offset:3072
	ds_read_b128 v[174:177], v140 offset:32768
	ds_read_b128 v[178:181], v140 offset:33792
	ds_read_b128 v[182:185], v140 offset:34816
	ds_read_b128 v[186:189], v140 offset:35840
	ds_read_b128 v[190:193], v140 offset:36864
	ds_read_b128 v[194:197], v140 offset:37888
	ds_read_b128 v[198:201], v140 offset:38912
	ds_read_b128 v[202:205], v140 offset:39936
	s_add_u32 s12, s34, 0x40000
	s_addc_u32 s13, s35, 0
	s_mov_b32 m0, s51
	s_nop 0
	global_load_lds_dwordx4 v1, s[12:13]
	s_add_u32 s12, s34, 0x60000
	s_addc_u32 s13, s35, 0
	s_mov_b32 m0, s52
	s_nop 0
	global_load_lds_dwordx4 v1, s[12:13]
	s_waitcnt vmcnt(8)
	s_waitcnt lgkmcnt(0)
	s_barrier
	s_waitcnt lgkmcnt(7)
	v_mfma_f32_16x16x32_bf16 v[122:125], v[142:145], v[174:177], v[122:125]
	v_mfma_f32_16x16x32_bf16 v[114:117], v[150:153], v[174:177], v[114:117]
	s_waitcnt lgkmcnt(5)
	v_mfma_f32_16x16x32_bf16 v[106:109], v[142:145], v[182:185], v[106:109]
	v_mfma_f32_16x16x32_bf16 v[98:101], v[150:153], v[182:185], v[98:101]
	s_waitcnt lgkmcnt(3)
	v_mfma_f32_16x16x32_bf16 v[90:93], v[142:145], v[190:193], v[90:93]
	v_mfma_f32_16x16x32_bf16 v[82:85], v[150:153], v[190:193], v[82:85]
	s_waitcnt lgkmcnt(1)
	v_mfma_f32_16x16x32_bf16 v[74:77], v[142:145], v[198:201], v[74:77]
	v_mfma_f32_16x16x32_bf16 v[66:69], v[150:153], v[198:201], v[66:69]
	v_mfma_f32_16x16x32_bf16 v[122:125], v[146:149], v[178:181], v[122:125]
	v_mfma_f32_16x16x32_bf16 v[114:117], v[154:157], v[178:181], v[114:117]
	v_mfma_f32_16x16x32_bf16 v[106:109], v[146:149], v[186:189], v[106:109]
	v_mfma_f32_16x16x32_bf16 v[98:101], v[154:157], v[186:189], v[98:101]
	v_mfma_f32_16x16x32_bf16 v[90:93], v[146:149], v[194:197], v[90:93]
	v_mfma_f32_16x16x32_bf16 v[82:85], v[154:157], v[194:197], v[82:85]
	s_waitcnt lgkmcnt(0)
	v_mfma_f32_16x16x32_bf16 v[74:77], v[146:149], v[202:205], v[74:77]
	v_mfma_f32_16x16x32_bf16 v[66:69], v[154:157], v[202:205], v[66:69]
	v_mfma_f32_16x16x32_bf16 v[126:129], v[158:161], v[174:177], v[126:129]
	v_mfma_f32_16x16x32_bf16 v[118:121], v[166:169], v[174:177], v[118:121]
	v_mfma_f32_16x16x32_bf16 v[110:113], v[158:161], v[182:185], v[110:113]
	v_mfma_f32_16x16x32_bf16 v[102:105], v[166:169], v[182:185], v[102:105]
	v_mfma_f32_16x16x32_bf16 v[94:97], v[158:161], v[190:193], v[94:97]
	v_mfma_f32_16x16x32_bf16 v[86:89], v[166:169], v[190:193], v[86:89]
	v_mfma_f32_16x16x32_bf16 v[78:81], v[158:161], v[198:201], v[78:81]
	v_mfma_f32_16x16x32_bf16 v[70:73], v[166:169], v[198:201], v[70:73]
	v_mfma_f32_16x16x32_bf16 v[126:129], v[162:165], v[178:181], v[126:129]
	v_mfma_f32_16x16x32_bf16 v[118:121], v[170:173], v[178:181], v[118:121]
	v_mfma_f32_16x16x32_bf16 v[110:113], v[162:165], v[186:189], v[110:113]
	v_mfma_f32_16x16x32_bf16 v[102:105], v[170:173], v[186:189], v[102:105]
	v_mfma_f32_16x16x32_bf16 v[94:97], v[162:165], v[194:197], v[94:97]
	v_mfma_f32_16x16x32_bf16 v[86:89], v[170:173], v[194:197], v[86:89]
	v_mfma_f32_16x16x32_bf16 v[78:81], v[162:165], v[202:205], v[78:81]
	v_mfma_f32_16x16x32_bf16 v[70:73], v[170:173], v[202:205], v[70:73]
	s_barrier
	s_add_u32 s12, s40, 0x80
	s_addc_u32 s13, s41, 0
	ds_read_b128 v[174:177], v140 offset:49152
	ds_read_b128 v[178:181], v140 offset:50176
	ds_read_b128 v[182:185], v140 offset:51200
	ds_read_b128 v[186:189], v140 offset:52224
	ds_read_b128 v[190:193], v140 offset:53248
	ds_read_b128 v[194:197], v140 offset:54272
	ds_read_b128 v[198:201], v140 offset:55296
	ds_read_b128 v[202:205], v140 offset:56320
	s_mov_b32 m0, s53
	s_nop 0
	global_load_lds_dwordx4 v136, s[12:13]
	s_add_u32 s12, s40, 0x20080
	s_addc_u32 s13, s41, 0
	s_mov_b32 m0, s54
	s_nop 0
	global_load_lds_dwordx4 v136, s[12:13]
	s_add_u32 s12, s40, 0x40080
	s_addc_u32 s13, s41, 0
	s_mov_b32 m0, s57
	s_nop 0
	global_load_lds_dwordx4 v136, s[12:13]
	s_add_u32 s12, s40, 0x60080
	s_addc_u32 s13, s41, 0
	s_mov_b32 m0, s58
	s_nop 0
	global_load_lds_dwordx4 v136, s[12:13]
	s_mov_b32 m0, s55
	s_nop 0
	global_load_lds_dwordx4 v1, s[38:39]
	s_add_u32 s12, s34, 0x20080
	s_addc_u32 s13, s35, 0
	s_mov_b32 m0, s56
	s_nop 0
	global_load_lds_dwordx4 v1, s[12:13]
	s_waitcnt vmcnt(8)
	s_waitcnt lgkmcnt(0)
	s_barrier
	s_waitcnt lgkmcnt(7)
	v_mfma_f32_16x16x32_bf16 v[58:61], v[142:145], v[174:177], v[58:61]
	v_mfma_f32_16x16x32_bf16 v[50:53], v[150:153], v[174:177], v[50:53]
	s_waitcnt lgkmcnt(5)
	v_mfma_f32_16x16x32_bf16 v[42:45], v[142:145], v[182:185], v[42:45]
	v_mfma_f32_16x16x32_bf16 v[34:37], v[150:153], v[182:185], v[34:37]
	s_waitcnt lgkmcnt(3)
	v_mfma_f32_16x16x32_bf16 v[26:29], v[142:145], v[190:193], v[26:29]
	v_mfma_f32_16x16x32_bf16 v[18:21], v[150:153], v[190:193], v[18:21]
	s_waitcnt lgkmcnt(1)
	v_mfma_f32_16x16x32_bf16 v[10:13], v[142:145], v[198:201], v[10:13]
	v_mfma_f32_16x16x32_bf16 v[6:9], v[150:153], v[198:201], v[6:9]
	v_mfma_f32_16x16x32_bf16 v[58:61], v[146:149], v[178:181], v[58:61]
	v_mfma_f32_16x16x32_bf16 v[50:53], v[154:157], v[178:181], v[50:53]
	v_mfma_f32_16x16x32_bf16 v[42:45], v[146:149], v[186:189], v[42:45]
	v_mfma_f32_16x16x32_bf16 v[34:37], v[154:157], v[186:189], v[34:37]
	v_mfma_f32_16x16x32_bf16 v[26:29], v[146:149], v[194:197], v[26:29]
	v_mfma_f32_16x16x32_bf16 v[18:21], v[154:157], v[194:197], v[18:21]
	s_waitcnt lgkmcnt(0)
	v_mfma_f32_16x16x32_bf16 v[10:13], v[146:149], v[202:205], v[10:13]
	v_mfma_f32_16x16x32_bf16 v[6:9], v[154:157], v[202:205], v[6:9]
	v_mfma_f32_16x16x32_bf16 v[62:65], v[158:161], v[174:177], v[62:65]
	v_mfma_f32_16x16x32_bf16 v[54:57], v[166:169], v[174:177], v[54:57]
	v_mfma_f32_16x16x32_bf16 v[46:49], v[158:161], v[182:185], v[46:49]
	v_mfma_f32_16x16x32_bf16 v[38:41], v[166:169], v[182:185], v[38:41]
	v_mfma_f32_16x16x32_bf16 v[30:33], v[158:161], v[190:193], v[30:33]
	v_mfma_f32_16x16x32_bf16 v[22:25], v[166:169], v[190:193], v[22:25]
	v_mfma_f32_16x16x32_bf16 v[14:17], v[158:161], v[198:201], v[14:17]
	v_mfma_f32_16x16x32_bf16 v[2:5], v[166:169], v[198:201], v[2:5]
	v_mfma_f32_16x16x32_bf16 v[62:65], v[162:165], v[178:181], v[62:65]
	v_mfma_f32_16x16x32_bf16 v[54:57], v[170:173], v[178:181], v[54:57]
	v_mfma_f32_16x16x32_bf16 v[46:49], v[162:165], v[186:189], v[46:49]
	v_mfma_f32_16x16x32_bf16 v[38:41], v[170:173], v[186:189], v[38:41]
	v_mfma_f32_16x16x32_bf16 v[30:33], v[162:165], v[194:197], v[30:33]
	v_mfma_f32_16x16x32_bf16 v[22:25], v[170:173], v[194:197], v[22:25]
	v_mfma_f32_16x16x32_bf16 v[14:17], v[162:165], v[202:205], v[14:17]
	v_mfma_f32_16x16x32_bf16 v[2:5], v[170:173], v[202:205], v[2:5]
	s_barrier
	s_add_i32 s66, s66, 2
	s_add_u32 s64, s64, 0x100
	s_addc_u32 s65, s65, 0
	s_cmp_gt_u32 s66, 13
	s_mov_b64 s[36:37], s[0:1]
